# s5_pass2 GLU epilogue: (bias, y, z) loads of 8 steps in flight from a register-slot ring (dataflow-renamed reads, counted vmcnt) instead of load-wait per step
# speedup vs baseline: 1.0027x; 1.0027x over previous
; __device__ __forceinline__ int otid() { return otid_full() & 255; }
; template <int D>
; __device__ __forceinline__ void gemm_acc(const bf* __restrict__ A, int lda, const bf* __restrict__ Bt, int ldb, int K,
;                                          f32x16 (&acc)[2][2], char* sm) {
;   const int tid = otid(), lane = tid & 63, w = tid >> 6, wr = w >> 1, wc = w & 1, r32 = lane & 31, h5 = lane >> 5;
;   const int lrow = tid >> 2, lch = tid & 3;
;   const bf* ga = A + (size_t)lrow * lda + lch * 8;
;   const bf* gb = Bt + (size_t)lrow * ldb + lch * 8;
;   const size_t a64 = (size_t)64 * lda, b64 = (size_t)64 * ldb;
;   const int nk = K >> 5;
;   char* sA = sm; char* sB = sm + 20480;
;   const int woff = lrow * 80 + lch * 16;
;   const int aoff = (wr * 64 + r32) * 80 + h5 * 16, boff = (wc * 64 + r32) * 80 + h5 * 16;
;   GStage S0, S1, S2, S3;
;   G_LOAD(S0, 0) G_LOAD(S1, 32)
;   if (D == 4) { G_LOAD(S2, 64) G_LOAD(S3, 96) }
;   G_WRITE(S0, 0)
;   if (D < nk) G_LOAD(S0, D * 32)
;   __syncthreads();
;   for (int kt0 = 0; kt0 < nk; kt0 += D) {
;     if (D == 4) {
;       G_ITER(kt0, 0, S1) G_ITER(kt0 + 1, 10240, S2) G_ITER(kt0 + 2, 0, S3) G_ITER(kt0 + 3, 10240, S0)
.LBB0_1800:
	v_mov_b32_e32 v0, v145
	v_mov_b32_e32 v20, v203
	v_mov_b32_e32 v17, v145
	v_bfe_u32 v22, v20, 2, 6
	v_lshlrev_b32_e32 v144, 10, v22
	v_lshlrev_b32_e32 v16, 4, v20
	v_lshl_add_u64 v[18:19], s[0:1], 0, v[144:145]
	v_and_b32_e32 v16, 48, v16
	v_lshl_add_u64 v[160:161], v[18:19], 0, v[16:17]
	v_and_b32_e32 v21, 31, v20
	v_bfe_u32 v18, v20, 1, 7
	v_add_co_u32_e32 v162, vcc, s34, v160
	v_and_or_b32 v19, v18, 64, v21
	v_and_b32_e32 v35, 16, v18
	v_and_b32_e32 v18, 0x5f, v20
	v_addc_co_u32_e32 v163, vcc, 0, v161, vcc
	v_or_b32_e32 v144, v144, v16
	v_mul_u32_u24_e32 v17, 0x50, v22
	v_mul_u32_u24_e32 v34, 0x50, v19
	v_mul_u32_u24_e32 v36, 0x50, v18
	global_load_dwordx4 v[18:21], v[160:161], off
	global_load_dwordx4 v[22:25], v[162:163], off
	global_load_dwordx4 v[26:29], v144, s[4:5]
	v_lshl_add_u64 v[30:31], s[4:5], 0, v[144:145]
	v_add_co_u32_e32 v164, vcc, s34, v30
	v_add3_u32 v167, v17, v16, s84
	s_nop 0
	v_addc_co_u32_e32 v165, vcc, 0, v31, vcc
	global_load_dwordx4 v[30:33], v[164:165], off
	global_load_dwordx4 v[112:115], v[160:161], off offset:64
	global_load_dwordx4 v[116:119], v[162:163], off offset:64
	global_load_dwordx4 v[120:123], v144, s[4:5] offset:64
	global_load_dwordx4 v[124:127], v[164:165], off offset:64
	global_load_dwordx4 v[96:99], v[160:161], off offset:128
	global_load_dwordx4 v[100:103], v[162:163], off offset:128
	global_load_dwordx4 v[104:107], v144, s[4:5] offset:128
	global_load_dwordx4 v[108:111], v[164:165], off offset:128
	global_load_dwordx4 v[80:83], v[160:161], off offset:192
	global_load_dwordx4 v[84:87], v[162:163], off offset:192
	global_load_dwordx4 v[88:91], v144, s[4:5] offset:192
	global_load_dwordx4 v[92:95], v[164:165], off offset:192
	v_add3_u32 v166, v34, v35, s84
	v_add3_u32 v168, v35, v36, s84
	v_mov_b32_e32 v1, v0
	v_mov_b32_e32 v2, v0
	v_mov_b32_e32 v3, v0
	v_mov_b32_e32 v4, v0
	v_mov_b32_e32 v5, v0
	v_mov_b32_e32 v6, v0
	v_mov_b32_e32 v7, v0
	v_mov_b32_e32 v8, v0
	v_mov_b32_e32 v9, v0
	v_mov_b32_e32 v10, v0
	v_mov_b32_e32 v11, v0
	v_mov_b32_e32 v12, v0
	v_mov_b32_e32 v13, v0
	v_mov_b32_e32 v14, v0
	v_mov_b32_e32 v15, v0
	s_waitcnt vmcnt(15)
	ds_write_b128 v167, v[18:21]
	s_waitcnt vmcnt(14)
	ds_write_b128 v167, v[22:25] offset:5120
	s_waitcnt vmcnt(13)
	ds_write_b128 v167, v[26:29] offset:20480
	s_waitcnt vmcnt(12)
	ds_write_b128 v167, v[30:33] offset:25600
	global_load_dwordx4 v[64:67], v[164:165], off offset:256
	global_load_dwordx4 v[68:71], v144, s[4:5] offset:256
	global_load_dwordx4 v[72:75], v[162:163], off offset:256
	global_load_dwordx4 v[76:79], v[160:161], off offset:256
	s_waitcnt lgkmcnt(0)
	s_barrier
	ds_read_b128 v[128:131], v166 offset:2560
	ds_read_b128 v[132:135], v168 offset:23040
	ds_read_b128 v[16:19], v166
	ds_read_b128 v[136:139], v166 offset:32
	ds_read_b128 v[140:143], v168 offset:20480
	ds_read_b128 v[170:173], v168 offset:20512
	s_waitcnt lgkmcnt(1)
	v_mfma_f32_32x32x16_bf16 v[48:63], v[140:143], v[16:19], v[0:15]
	v_mfma_f32_32x32x16_bf16 v[32:47], v[132:135], v[16:19], v[0:15]
	v_mfma_f32_32x32x16_bf16 v[16:31], v[140:143], v[128:131], v[0:15]
	v_mfma_f32_32x32x16_bf16 v[0:15], v[132:135], v[128:131], v[0:15]
	ds_read_b128 v[128:131], v166 offset:2592
	ds_read_b128 v[132:135], v168 offset:23072
	s_waitcnt vmcnt(15)
	ds_write_b128 v167, v[112:115] offset:10240
	s_waitcnt vmcnt(14)
	ds_write_b128 v167, v[116:119] offset:15360
	s_waitcnt vmcnt(13)
	ds_write_b128 v167, v[120:123] offset:30720
	s_waitcnt vmcnt(12)
	ds_write_b128 v167, v[124:127] offset:35840
	global_load_dwordx4 v[112:115], v[160:161], off offset:320
	global_load_dwordx4 v[116:119], v[162:163], off offset:320
	global_load_dwordx4 v[120:123], v144, s[4:5] offset:320
	global_load_dwordx4 v[124:127], v[164:165], off offset:320
	s_waitcnt lgkmcnt(0)
	s_barrier
	v_mfma_f32_32x32x16_bf16 v[32:47], v[132:135], v[136:139], v[32:47]
	v_mfma_f32_32x32x16_bf16 v[16:31], v[170:173], v[128:131], v[16:31]
	v_mfma_f32_32x32x16_bf16 v[0:15], v[132:135], v[128:131], v[0:15]
	v_mfma_f32_32x32x16_bf16 v[48:63], v[170:173], v[136:139], v[48:63]
	ds_read_b128 v[128:131], v166 offset:12800
	ds_read_b128 v[132:135], v168 offset:33280
	ds_read_b128 v[136:139], v166 offset:10240
	ds_read_b128 v[140:143], v166 offset:10272
	ds_read_b128 v[170:173], v168 offset:30720
	ds_read_b128 v[174:177], v168 offset:30752
	s_waitcnt lgkmcnt(3)
	v_mfma_f32_32x32x16_bf16 v[32:47], v[132:135], v[136:139], v[32:47]
	s_waitcnt lgkmcnt(1)
	v_mfma_f32_32x32x16_bf16 v[16:31], v[170:173], v[128:131], v[16:31]
	v_mfma_f32_32x32x16_bf16 v[0:15], v[132:135], v[128:131], v[0:15]
	ds_read_b128 v[128:131], v166 offset:12832
	ds_read_b128 v[132:135], v168 offset:33312
	s_waitcnt vmcnt(15)
	ds_write_b128 v167, v[96:99]
	s_waitcnt vmcnt(14)
	ds_write_b128 v167, v[100:103] offset:5120
	s_waitcnt vmcnt(13)
	ds_write_b128 v167, v[104:107] offset:20480
	s_waitcnt vmcnt(12)
	ds_write_b128 v167, v[108:111] offset:25600
	global_load_dwordx4 v[96:99], v[160:161], off offset:384
	global_load_dwordx4 v[100:103], v[162:163], off offset:384
	global_load_dwordx4 v[104:107], v144, s[4:5] offset:384
	global_load_dwordx4 v[108:111], v[164:165], off offset:384
	s_waitcnt lgkmcnt(0)
	s_barrier
	v_mfma_f32_32x32x16_bf16 v[48:63], v[170:173], v[136:139], v[48:63]
	v_mfma_f32_32x32x16_bf16 v[32:47], v[132:135], v[140:143], v[32:47]
	v_mfma_f32_32x32x16_bf16 v[16:31], v[174:177], v[128:131], v[16:31]
	v_mfma_f32_32x32x16_bf16 v[0:15], v[132:135], v[128:131], v[0:15]
	v_mfma_f32_32x32x16_bf16 v[48:63], v[174:177], v[140:143], v[48:63]
	ds_read_b128 v[128:131], v166 offset:2560
	ds_read_b128 v[132:135], v168 offset:23040
	ds_read_b128 v[136:139], v166
	ds_read_b128 v[140:143], v166 offset:32
	ds_read_b128 v[170:173], v168 offset:20480
	ds_read_b128 v[174:177], v168 offset:20512
	s_waitcnt lgkmcnt(3)
	v_mfma_f32_32x32x16_bf16 v[32:47], v[132:135], v[136:139], v[32:47]
	s_waitcnt lgkmcnt(1)
	v_mfma_f32_32x32x16_bf16 v[16:31], v[170:173], v[128:131], v[16:31]
	v_mfma_f32_32x32x16_bf16 v[0:15], v[132:135], v[128:131], v[0:15]
	ds_read_b128 v[128:131], v166 offset:2592
	ds_read_b128 v[132:135], v168 offset:23072
	s_waitcnt vmcnt(15)
	ds_write_b128 v167, v[80:83] offset:10240
	s_waitcnt vmcnt(14)
	ds_write_b128 v167, v[84:87] offset:15360
	s_waitcnt vmcnt(13)
	ds_write_b128 v167, v[88:91] offset:30720
	s_waitcnt vmcnt(12)
	ds_write_b128 v167, v[92:95] offset:35840
	global_load_dwordx4 v[80:83], v[160:161], off offset:448
	global_load_dwordx4 v[84:87], v[162:163], off offset:448
	global_load_dwordx4 v[88:91], v144, s[4:5] offset:448
	global_load_dwordx4 v[92:95], v[164:165], off offset:448
	s_waitcnt lgkmcnt(0)
	s_barrier
	v_mfma_f32_32x32x16_bf16 v[48:63], v[170:173], v[136:139], v[48:63]
	v_mfma_f32_32x32x16_bf16 v[48:63], v[174:177], v[140:143], v[48:63]
	v_mfma_f32_32x32x16_bf16 v[32:47], v[132:135], v[140:143], v[32:47]
	v_mfma_f32_32x32x16_bf16 v[16:31], v[174:177], v[128:131], v[16:31]
	v_mfma_f32_32x32x16_bf16 v[0:15], v[132:135], v[128:131], v[0:15]
	ds_read_b128 v[128:131], v166 offset:12800
	ds_read_b128 v[132:135], v168 offset:33280
	ds_read_b128 v[136:139], v166 offset:10240
	ds_read_b128 v[140:143], v166 offset:10272
	ds_read_b128 v[170:173], v168 offset:30720
	ds_read_b128 v[174:177], v168 offset:30752
	s_waitcnt lgkmcnt(1)
	v_mfma_f32_32x32x16_bf16 v[48:63], v[170:173], v[136:139], v[48:63]
	v_mfma_f32_32x32x16_bf16 v[32:47], v[132:135], v[136:139], v[32:47]
	v_mfma_f32_32x32x16_bf16 v[16:31], v[170:173], v[128:131], v[16:31]
	v_mfma_f32_32x32x16_bf16 v[0:15], v[132:135], v[128:131], v[0:15]
	ds_read_b128 v[128:131], v166 offset:12832
	ds_read_b128 v[132:135], v168 offset:33312
	s_waitcnt vmcnt(12)
	ds_write_b128 v167, v[76:79]
	ds_write_b128 v167, v[72:75] offset:5120
	ds_write_b128 v167, v[68:71] offset:20480
	ds_write_b128 v167, v[64:67] offset:25600
	global_load_dwordx4 v[64:67], v[160:161], off offset:512
	global_load_dwordx4 v[68:71], v[162:163], off offset:512
	global_load_dwordx4 v[72:75], v144, s[4:5] offset:512
	global_load_dwordx4 v[76:79], v[164:165], off offset:512
	s_waitcnt lgkmcnt(0)
	s_barrier
	v_mfma_f32_32x32x16_bf16 v[48:63], v[174:177], v[140:143], v[48:63]
	v_mfma_f32_32x32x16_bf16 v[32:47], v[132:135], v[140:143], v[32:47]
	v_mfma_f32_32x32x16_bf16 v[16:31], v[174:177], v[128:131], v[16:31]
	v_mfma_f32_32x32x16_bf16 v[0:15], v[132:135], v[128:131], v[0:15]
	ds_read_b128 v[128:131], v166 offset:2560
	ds_read_b128 v[132:135], v168 offset:23040
	ds_read_b128 v[136:139], v166
	ds_read_b128 v[140:143], v166 offset:32
	ds_read_b128 v[170:173], v168 offset:20480
	ds_read_b128 v[174:177], v168 offset:20512
	s_waitcnt lgkmcnt(1)
	v_mfma_f32_32x32x16_bf16 v[48:63], v[170:173], v[136:139], v[48:63]
	v_mfma_f32_32x32x16_bf16 v[32:47], v[132:135], v[136:139], v[32:47]
	v_mfma_f32_32x32x16_bf16 v[16:31], v[170:173], v[128:131], v[16:31]
	v_mfma_f32_32x32x16_bf16 v[0:15], v[132:135], v[128:131], v[0:15]
	ds_read_b128 v[128:131], v166 offset:2592
	ds_read_b128 v[132:135], v168 offset:23072
	s_waitcnt vmcnt(15)
	ds_write_b128 v167, v[112:115] offset:10240
	s_waitcnt vmcnt(14)
	ds_write_b128 v167, v[116:119] offset:15360
	s_waitcnt vmcnt(13)
	ds_write_b128 v167, v[120:123] offset:30720
	s_waitcnt vmcnt(12)
	ds_write_b128 v167, v[124:127] offset:35840
	global_load_dwordx4 v[112:115], v[160:161], off offset:576
	global_load_dwordx4 v[116:119], v[162:163], off offset:576
	global_load_dwordx4 v[120:123], v144, s[4:5] offset:576
	global_load_dwordx4 v[124:127], v[164:165], off offset:576
	s_waitcnt lgkmcnt(0)
	s_barrier
	v_mfma_f32_32x32x16_bf16 v[48:63], v[174:177], v[140:143], v[48:63]
	v_mfma_f32_32x32x16_bf16 v[32:47], v[132:135], v[140:143], v[32:47]
	v_mfma_f32_32x32x16_bf16 v[16:31], v[174:177], v[128:131], v[16:31]
	v_mfma_f32_32x32x16_bf16 v[0:15], v[132:135], v[128:131], v[0:15]
	ds_read_b128 v[128:131], v166 offset:12800
	ds_read_b128 v[132:135], v168 offset:33280
	ds_read_b128 v[136:139], v166 offset:10240
	ds_read_b128 v[140:143], v166 offset:10272
	ds_read_b128 v[170:173], v168 offset:30720
	ds_read_b128 v[174:177], v168 offset:30752
	s_waitcnt lgkmcnt(1)
	v_mfma_f32_32x32x16_bf16 v[48:63], v[170:173], v[136:139], v[48:63]
	v_mfma_f32_32x32x16_bf16 v[32:47], v[132:135], v[136:139], v[32:47]
	v_mfma_f32_32x32x16_bf16 v[16:31], v[170:173], v[128:131], v[16:31]
	v_mfma_f32_32x32x16_bf16 v[0:15], v[132:135], v[128:131], v[0:15]
	ds_read_b128 v[128:131], v166 offset:12832
	ds_read_b128 v[132:135], v168 offset:33312
	s_waitcnt vmcnt(15)
	ds_write_b128 v167, v[96:99]
	s_waitcnt vmcnt(14)
	ds_write_b128 v167, v[100:103] offset:5120
	s_waitcnt vmcnt(13)
	ds_write_b128 v167, v[104:107] offset:20480
	s_waitcnt vmcnt(12)
	ds_write_b128 v167, v[108:111] offset:25600
	s_waitcnt lgkmcnt(6)
	v_mfma_f32_32x32x16_bf16 v[48:63], v[174:177], v[140:143], v[48:63]
	s_waitcnt lgkmcnt(4)
	v_mfma_f32_32x32x16_bf16 v[32:47], v[132:135], v[140:143], v[32:47]
	v_mfma_f32_32x32x16_bf16 v[16:31], v[174:177], v[128:131], v[16:31]
	v_mfma_f32_32x32x16_bf16 v[0:15], v[132:135], v[128:131], v[0:15]
	global_load_dwordx4 v[128:131], v[160:161], off offset:640
	global_load_dwordx4 v[132:135], v[162:163], off offset:640
	global_load_dwordx4 v[136:139], v144, s[4:5] offset:640
	global_load_dwordx4 v[140:143], v[164:165], off offset:640
	s_waitcnt lgkmcnt(0)
	s_barrier
	ds_read_b128 v[96:99], v166 offset:2560
	ds_read_b128 v[100:103], v168 offset:23040
	ds_read_b128 v[104:107], v166
	ds_read_b128 v[108:111], v166 offset:32
	ds_read_b128 v[170:173], v168 offset:20480
	ds_read_b128 v[174:177], v168 offset:20512
	s_waitcnt lgkmcnt(3)
	v_mfma_f32_32x32x16_bf16 v[32:47], v[100:103], v[104:107], v[32:47]
	s_waitcnt lgkmcnt(1)
	v_mfma_f32_32x32x16_bf16 v[16:31], v[170:173], v[96:99], v[16:31]
	v_mfma_f32_32x32x16_bf16 v[0:15], v[100:103], v[96:99], v[0:15]
	ds_read_b128 v[96:99], v166 offset:2592
	ds_read_b128 v[100:103], v168 offset:23072
	s_waitcnt vmcnt(15)
	ds_write_b128 v167, v[80:83] offset:10240
	s_waitcnt vmcnt(14)
	ds_write_b128 v167, v[84:87] offset:15360
	s_waitcnt vmcnt(13)
	ds_write_b128 v167, v[88:91] offset:30720
	s_waitcnt vmcnt(12)
	ds_write_b128 v167, v[92:95] offset:35840
	global_load_dwordx4 v[80:83], v[160:161], off offset:704
	global_load_dwordx4 v[84:87], v[162:163], off offset:704
	global_load_dwordx4 v[88:91], v144, s[4:5] offset:704
	global_load_dwordx4 v[92:95], v[164:165], off offset:704
	s_waitcnt lgkmcnt(0)
	s_barrier
	v_mfma_f32_32x32x16_bf16 v[48:63], v[170:173], v[104:107], v[48:63]
	v_mfma_f32_32x32x16_bf16 v[48:63], v[174:177], v[108:111], v[48:63]
	v_mfma_f32_32x32x16_bf16 v[32:47], v[100:103], v[108:111], v[32:47]
	v_mfma_f32_32x32x16_bf16 v[16:31], v[174:177], v[96:99], v[16:31]
	v_mfma_f32_32x32x16_bf16 v[0:15], v[100:103], v[96:99], v[0:15]
	ds_read_b128 v[96:99], v166 offset:12800
	ds_read_b128 v[100:103], v168 offset:33280
	ds_read_b128 v[104:107], v166 offset:10240
	ds_read_b128 v[108:111], v166 offset:10272
	ds_read_b128 v[170:173], v168 offset:30720
	ds_read_b128 v[174:177], v168 offset:30752
	s_waitcnt lgkmcnt(1)
	v_mfma_f32_32x32x16_bf16 v[48:63], v[170:173], v[104:107], v[48:63]
	v_mfma_f32_32x32x16_bf16 v[32:47], v[100:103], v[104:107], v[32:47]
	v_mfma_f32_32x32x16_bf16 v[16:31], v[170:173], v[96:99], v[16:31]
	v_mfma_f32_32x32x16_bf16 v[0:15], v[100:103], v[96:99], v[0:15]
	ds_read_b128 v[96:99], v166 offset:12832
	ds_read_b128 v[100:103], v168 offset:33312
	s_waitcnt vmcnt(15)
	ds_write_b128 v167, v[64:67]
	s_waitcnt vmcnt(14)
	ds_write_b128 v167, v[68:71] offset:5120
	s_waitcnt vmcnt(13)
	ds_write_b128 v167, v[72:75] offset:20480
	s_waitcnt vmcnt(12)
	ds_write_b128 v167, v[76:79] offset:25600
	global_load_dwordx4 v[64:67], v[160:161], off offset:768
	global_load_dwordx4 v[68:71], v[162:163], off offset:768
	global_load_dwordx4 v[72:75], v144, s[4:5] offset:768
	global_load_dwordx4 v[76:79], v[164:165], off offset:768
	s_waitcnt lgkmcnt(0)
	s_barrier
	v_mfma_f32_32x32x16_bf16 v[48:63], v[174:177], v[108:111], v[48:63]
	v_mfma_f32_32x32x16_bf16 v[32:47], v[100:103], v[108:111], v[32:47]
	v_mfma_f32_32x32x16_bf16 v[16:31], v[174:177], v[96:99], v[16:31]
	v_mfma_f32_32x32x16_bf16 v[0:15], v[100:103], v[96:99], v[0:15]
	ds_read_b128 v[96:99], v166 offset:2560
	ds_read_b128 v[100:103], v168 offset:23040
	ds_read_b128 v[104:107], v166
	ds_read_b128 v[108:111], v166 offset:32
	ds_read_b128 v[170:173], v168 offset:20480
	ds_read_b128 v[174:177], v168 offset:20512
	s_waitcnt lgkmcnt(1)
	v_mfma_f32_32x32x16_bf16 v[48:63], v[170:173], v[104:107], v[48:63]
	v_mfma_f32_32x32x16_bf16 v[32:47], v[100:103], v[104:107], v[32:47]
	v_mfma_f32_32x32x16_bf16 v[16:31], v[170:173], v[96:99], v[16:31]
	v_mfma_f32_32x32x16_bf16 v[0:15], v[100:103], v[96:99], v[0:15]
	ds_read_b128 v[96:99], v166 offset:2592
	ds_read_b128 v[100:103], v168 offset:23072
	s_waitcnt vmcnt(15)
	ds_write_b128 v167, v[112:115] offset:10240
	s_waitcnt vmcnt(14)
	ds_write_b128 v167, v[116:119] offset:15360
	s_waitcnt vmcnt(13)
	ds_write_b128 v167, v[120:123] offset:30720
	s_waitcnt vmcnt(12)
	ds_write_b128 v167, v[124:127] offset:35840
	s_waitcnt lgkmcnt(6)
	v_mfma_f32_32x32x16_bf16 v[48:63], v[174:177], v[108:111], v[48:63]
	s_waitcnt lgkmcnt(4)
	v_mfma_f32_32x32x16_bf16 v[32:47], v[100:103], v[108:111], v[32:47]
	v_mfma_f32_32x32x16_bf16 v[16:31], v[174:177], v[96:99], v[16:31]
	v_mfma_f32_32x32x16_bf16 v[0:15], v[100:103], v[96:99], v[0:15]
	global_load_dwordx4 v[96:99], v[160:161], off offset:832
	global_load_dwordx4 v[100:103], v[162:163], off offset:832
	global_load_dwordx4 v[104:107], v144, s[4:5] offset:832
	global_load_dwordx4 v[108:111], v[164:165], off offset:832
	s_waitcnt lgkmcnt(0)
	s_barrier
	ds_read_b128 v[112:115], v166 offset:12800
	ds_read_b128 v[116:119], v168 offset:33280
	ds_read_b128 v[120:123], v166 offset:10240
	ds_read_b128 v[124:127], v166 offset:10272
	ds_read_b128 v[170:173], v168 offset:30720
	ds_read_b128 v[174:177], v168 offset:30752
	s_waitcnt lgkmcnt(1)
	v_mfma_f32_32x32x16_bf16 v[48:63], v[170:173], v[120:123], v[48:63]
	v_mfma_f32_32x32x16_bf16 v[32:47], v[116:119], v[120:123], v[32:47]
	v_mfma_f32_32x32x16_bf16 v[16:31], v[170:173], v[112:115], v[16:31]
	v_mfma_f32_32x32x16_bf16 v[0:15], v[116:119], v[112:115], v[0:15]
	ds_read_b128 v[112:115], v166 offset:12832
	ds_read_b128 v[116:119], v168 offset:33312
	s_waitcnt vmcnt(15)
	ds_write_b128 v167, v[128:131]
	s_waitcnt vmcnt(14)
	ds_write_b128 v167, v[132:135] offset:5120
	s_waitcnt vmcnt(13)
	ds_write_b128 v167, v[136:139] offset:20480
	s_waitcnt vmcnt(12)
	ds_write_b128 v167, v[140:143] offset:25600
	s_waitcnt lgkmcnt(6)
	v_mfma_f32_32x32x16_bf16 v[48:63], v[174:177], v[124:127], v[48:63]
	s_waitcnt lgkmcnt(4)
	v_mfma_f32_32x32x16_bf16 v[32:47], v[116:119], v[124:127], v[32:47]
	v_mfma_f32_32x32x16_bf16 v[16:31], v[174:177], v[112:115], v[16:31]
	v_mfma_f32_32x32x16_bf16 v[0:15], v[116:119], v[112:115], v[0:15]
	global_load_dwordx4 v[112:115], v[160:161], off offset:896
	global_load_dwordx4 v[116:119], v[162:163], off offset:896
	global_load_dwordx4 v[120:123], v144, s[4:5] offset:896
	global_load_dwordx4 v[124:127], v[164:165], off offset:896
	s_waitcnt lgkmcnt(0)
	s_barrier
	ds_read_b128 v[128:131], v166 offset:2560
	ds_read_b128 v[132:135], v168 offset:23040
	ds_read_b128 v[136:139], v166
	ds_read_b128 v[140:143], v166 offset:32
	ds_read_b128 v[170:173], v168 offset:20480
	ds_read_b128 v[174:177], v168 offset:20512
	s_waitcnt lgkmcnt(3)
	v_mfma_f32_32x32x16_bf16 v[32:47], v[132:135], v[136:139], v[32:47]
	s_waitcnt lgkmcnt(1)
	v_mfma_f32_32x32x16_bf16 v[16:31], v[170:173], v[128:131], v[16:31]
	v_mfma_f32_32x32x16_bf16 v[0:15], v[132:135], v[128:131], v[0:15]
	ds_read_b128 v[128:131], v166 offset:2592
	ds_read_b128 v[132:135], v168 offset:23072
	s_waitcnt vmcnt(15)
	ds_write_b128 v167, v[80:83] offset:10240
	s_waitcnt vmcnt(14)
	ds_write_b128 v167, v[84:87] offset:15360
	s_waitcnt vmcnt(13)
	ds_write_b128 v167, v[88:91] offset:30720
	s_waitcnt vmcnt(12)
	ds_write_b128 v167, v[92:95] offset:35840
	global_load_dwordx4 v[80:83], v[160:161], off offset:960
	global_load_dwordx4 v[84:87], v[162:163], off offset:960
	global_load_dwordx4 v[88:91], v144, s[4:5] offset:960
	global_load_dwordx4 v[92:95], v[164:165], off offset:960
	s_waitcnt lgkmcnt(0)
	s_barrier
	s_add_u32 s4, s4, 0x20000
	v_mfma_f32_32x32x16_bf16 v[48:63], v[170:173], v[136:139], v[48:63]
	s_addc_u32 s5, s5, 0
	v_mfma_f32_32x32x16_bf16 v[16:31], v[174:177], v[128:131], v[16:31]
	v_mfma_f32_32x32x16_bf16 v[0:15], v[132:135], v[128:131], v[0:15]
	v_mfma_f32_32x32x16_bf16 v[32:47], v[132:135], v[140:143], v[32:47]
	v_mfma_f32_32x32x16_bf16 v[48:63], v[174:177], v[140:143], v[48:63]
	ds_read_b128 v[128:131], v166 offset:12800
	ds_read_b128 v[132:135], v168 offset:33280
	ds_read_b128 v[136:139], v166 offset:10240
	ds_read_b128 v[140:143], v166 offset:10272
	ds_read_b128 v[160:163], v168 offset:30720
	ds_read_b128 v[170:173], v168 offset:30752
	s_waitcnt lgkmcnt(1)
	v_mfma_f32_32x32x16_bf16 v[16:31], v[160:163], v[128:131], v[16:31]
	v_mfma_f32_32x32x16_bf16 v[0:15], v[132:135], v[128:131], v[0:15]
	v_mfma_f32_32x32x16_bf16 v[32:47], v[132:135], v[136:139], v[32:47]
	ds_read_b128 v[128:131], v166 offset:12832
	ds_read_b128 v[132:135], v168 offset:33312
	s_waitcnt vmcnt(15)
	ds_write_b128 v167, v[64:67]
	s_waitcnt vmcnt(14)
	ds_write_b128 v167, v[68:71] offset:5120
	s_waitcnt vmcnt(13)
	ds_write_b128 v167, v[72:75] offset:20480
	s_waitcnt vmcnt(12)
	ds_write_b128 v167, v[76:79] offset:25600
	s_waitcnt lgkmcnt(0)
	s_barrier
	v_mfma_f32_32x32x16_bf16 v[48:63], v[160:163], v[136:139], v[48:63]
	v_mfma_f32_32x32x16_bf16 v[16:31], v[170:173], v[128:131], v[16:31]
	v_mfma_f32_32x32x16_bf16 v[0:15], v[132:135], v[128:131], v[0:15]
	v_mfma_f32_32x32x16_bf16 v[32:47], v[132:135], v[140:143], v[32:47]
	ds_read_b128 v[64:67], v166 offset:2560
	ds_read_b128 v[68:71], v168 offset:23040
	ds_read_b128 v[72:75], v166
	ds_read_b128 v[76:79], v166 offset:32
	ds_read_b128 v[128:131], v168 offset:20480
	ds_read_b128 v[132:135], v168 offset:20512
	v_mfma_f32_32x32x16_bf16 v[48:63], v[170:173], v[140:143], v[48:63]
	s_waitcnt lgkmcnt(1)
	v_mfma_f32_32x32x16_bf16 v[16:31], v[128:131], v[64:67], v[16:31]
	v_mfma_f32_32x32x16_bf16 v[0:15], v[68:71], v[64:67], v[0:15]
	v_mfma_f32_32x32x16_bf16 v[32:47], v[68:71], v[72:75], v[32:47]
	ds_read_b128 v[64:67], v166 offset:2592
	ds_read_b128 v[68:71], v168 offset:23072
	s_waitcnt vmcnt(11)
	ds_write_b128 v167, v[96:99] offset:10240
	s_waitcnt vmcnt(10)
	ds_write_b128 v167, v[100:103] offset:15360
	s_waitcnt vmcnt(9)
	ds_write_b128 v167, v[104:107] offset:30720
	s_waitcnt vmcnt(8)
	ds_write_b128 v167, v[108:111] offset:35840
	s_waitcnt lgkmcnt(0)
	s_barrier
	v_mfma_f32_32x32x16_bf16 v[48:63], v[128:131], v[72:75], v[48:63]
	v_mfma_f32_32x32x16_bf16 v[16:31], v[132:135], v[64:67], v[16:31]
	v_mfma_f32_32x32x16_bf16 v[0:15], v[68:71], v[64:67], v[0:15]
	v_mfma_f32_32x32x16_bf16 v[32:47], v[68:71], v[76:79], v[32:47]
	v_mfma_f32_32x32x16_bf16 v[48:63], v[132:135], v[76:79], v[48:63]
	ds_read_b128 v[64:67], v166 offset:12800
	ds_read_b128 v[68:71], v168 offset:33280
	ds_read_b128 v[72:75], v166 offset:10240
	ds_read_b128 v[76:79], v166 offset:10272
	ds_read_b128 v[96:99], v168 offset:30720
	ds_read_b128 v[100:103], v168 offset:30752
	s_waitcnt lgkmcnt(1)
	v_mfma_f32_32x32x16_bf16 v[16:31], v[96:99], v[64:67], v[16:31]
	v_mfma_f32_32x32x16_bf16 v[0:15], v[68:71], v[64:67], v[0:15]
	v_mfma_f32_32x32x16_bf16 v[32:47], v[68:71], v[72:75], v[32:47]
	ds_read_b128 v[64:67], v166 offset:12832
	ds_read_b128 v[68:71], v168 offset:33312
	s_waitcnt vmcnt(7)
	ds_write_b128 v167, v[112:115]
	s_waitcnt vmcnt(6)
	ds_write_b128 v167, v[116:119] offset:5120
	s_waitcnt vmcnt(5)
	ds_write_b128 v167, v[120:123] offset:20480
	s_waitcnt vmcnt(4)
	ds_write_b128 v167, v[124:127] offset:25600
	s_waitcnt lgkmcnt(0)
	s_barrier
	v_mfma_f32_32x32x16_bf16 v[48:63], v[96:99], v[72:75], v[48:63]
	v_mfma_f32_32x32x16_bf16 v[16:31], v[100:103], v[64:67], v[16:31]
	v_mfma_f32_32x32x16_bf16 v[0:15], v[68:71], v[64:67], v[0:15]
	v_mfma_f32_32x32x16_bf16 v[32:47], v[68:71], v[76:79], v[32:47]
	v_mfma_f32_32x32x16_bf16 v[48:63], v[100:103], v[76:79], v[48:63]
	ds_read_b128 v[64:67], v166 offset:2560
	ds_read_b128 v[68:71], v168 offset:23040
	ds_read_b128 v[72:75], v166
	ds_read_b128 v[76:79], v166 offset:32
	ds_read_b128 v[96:99], v168 offset:20480
	ds_read_b128 v[100:103], v168 offset:20512
	s_waitcnt lgkmcnt(1)
	v_mfma_f32_32x32x16_bf16 v[16:31], v[96:99], v[64:67], v[16:31]
	v_mfma_f32_32x32x16_bf16 v[0:15], v[68:71], v[64:67], v[0:15]
	v_mfma_f32_32x32x16_bf16 v[32:47], v[68:71], v[72:75], v[32:47]
	ds_read_b128 v[64:67], v166 offset:2592
	ds_read_b128 v[68:71], v168 offset:23072
	s_waitcnt vmcnt(3)
	ds_write_b128 v167, v[80:83] offset:10240
	s_waitcnt vmcnt(2)
	ds_write_b128 v167, v[84:87] offset:15360
	s_waitcnt vmcnt(1)
	ds_write_b128 v167, v[88:91] offset:30720
	s_waitcnt vmcnt(0)
	ds_write_b128 v167, v[92:95] offset:35840
	s_waitcnt lgkmcnt(0)
	s_barrier
; __device__ __forceinline__ float bflo(unsigned u) { return __uint_as_float(u << 16); }
; __device__ __forceinline__ float bfhi(unsigned u) { return __uint_as_float(u & 0xFFFF0000u); }
; __device__ __forceinline__ float sigmoidf_(float x) { return __builtin_amdgcn_rcpf(1.f + __expf(-x)); }
; __device__ __forceinline__ float siluf_(float x) { return x * __builtin_amdgcn_rcpf(1.f + __expf(-x)); }
; __device__ __forceinline__ void s5_pass2(const Params& p, int layer, int task, char* sm) {
;     ...
; #pragma unroll
;     for (int i = 0; i < 2; i++) {
;       const size_t tok = tok0 + wr * 64 + i * 32 + r32;
; #pragma unroll
;       for (int j = 0; j < 2; j++)
; #pragma unroll
;         for (int q = 0; q < 4; q++) {
;           const int n = tn * 128 + wc * 64 + j * 32 + q * 8 + h5 * 4;
;           float4 bg = *(const float4*)(p.b_glu + layer * 512 + n);
;           uint2 yy = *(const uint2*)(p.YG + tok * 512 + n);
;           uint2 zz = *(const uint2*)(p.P + tok * PW + C_S5Z + n);
;           float o0 = bflo(yy.x) * sigmoidf_(acc[i][j][4 * q] + bg.x) * siluf_(bflo(zz.x));
;           float o1 = bfhi(yy.x) * sigmoidf_(acc[i][j][4 * q + 1] + bg.y) * siluf_(bfhi(zz.x));
;           float o2 = bflo(yy.y) * sigmoidf_(acc[i][j][4 * q + 2] + bg.z) * siluf_(bflo(zz.y));
;           float o3 = bfhi(yy.y) * sigmoidf_(acc[i][j][4 * q + 3] + bg.w) * siluf_(bfhi(zz.y));
;           *(uint2*)(p.Y + tok * YW + Y_S5 + n) = make_uint2(pk2(o0, o1), pk2(o2, o3));
;         }
	v_mfma_f32_32x32x16_bf16 v[48:63], v[96:99], v[72:75], v[48:63]
	v_mfma_f32_32x32x16_bf16 v[16:31], v[100:103], v[64:67], v[16:31]
	v_mfma_f32_32x32x16_bf16 v[0:15], v[68:71], v[64:67], v[0:15]
	v_mfma_f32_32x32x16_bf16 v[32:47], v[68:71], v[76:79], v[32:47]
	v_mfma_f32_32x32x16_bf16 v[48:63], v[100:103], v[76:79], v[48:63]
	ds_read_b128 v[64:67], v166 offset:12800
	ds_read_b128 v[68:71], v168 offset:33280
	ds_read_b128 v[72:75], v166 offset:10240
	ds_read_b128 v[76:79], v166 offset:10272
	ds_read_b128 v[80:83], v168 offset:30720
	ds_read_b128 v[84:87], v168 offset:30752
	s_waitcnt lgkmcnt(1)
	v_mfma_f32_32x32x16_bf16 v[16:31], v[80:83], v[64:67], v[16:31]
	v_mfma_f32_32x32x16_bf16 v[0:15], v[68:71], v[64:67], v[0:15]
	v_mfma_f32_32x32x16_bf16 v[32:47], v[68:71], v[72:75], v[32:47]
	ds_read_b128 v[64:67], v166 offset:12832
	ds_read_b128 v[68:71], v168 offset:33312
	s_waitcnt lgkmcnt(0)
	s_barrier
	v_mfma_f32_32x32x16_bf16 v[16:31], v[84:87], v[64:67], v[16:31]
	v_mfma_f32_32x32x16_bf16 v[0:15], v[68:71], v[64:67], v[0:15]
	v_lshl_add_u64 v[66:67], v[152:153], 0, s[2:3]
	v_lshl_add_u64 v[64:65], v[156:157], 0, s[2:3]
	v_mfma_f32_32x32x16_bf16 v[48:63], v[80:83], v[72:75], v[48:63]
	v_lshl_add_u64 v[160:161], v[156:157], 0, s[2:3]
	v_lshl_add_u64 v[162:163], v[152:153], 0, s[2:3]
	v_lshl_add_u64 v[164:165], v[148:149], 0, s[2:3]
	v_lshl_add_u64 v[166:167], v[150:151], 0, s[2:3]
	global_load_dwordx4 v[88:91], v[158:159], off offset:-128
	global_load_dwordx2 v[92:93], v[160:161], off
	global_load_dwordx2 v[94:95], v[162:163], off offset:1024
	global_load_dwordx4 v[96:99], v[158:159], off offset:-96
	global_load_dwordx2 v[100:101], v[160:161], off offset:16
	global_load_dwordx2 v[102:103], v[162:163], off offset:1040
	global_load_dwordx4 v[104:107], v[158:159], off offset:-64
	global_load_dwordx2 v[108:109], v[160:161], off offset:32
	global_load_dwordx2 v[110:111], v[162:163], off offset:1056
	global_load_dwordx4 v[112:115], v[158:159], off offset:-32
	global_load_dwordx2 v[116:117], v[160:161], off offset:48
	global_load_dwordx2 v[118:119], v[162:163], off offset:1072
	global_load_dwordx4 v[120:123], v[158:159], off
	global_load_dwordx2 v[124:125], v[160:161], off offset:64
	global_load_dwordx2 v[126:127], v[162:163], off offset:1088
	global_load_dwordx4 v[128:131], v[158:159], off offset:32
	global_load_dwordx2 v[132:133], v[160:161], off offset:80
	global_load_dwordx2 v[134:135], v[162:163], off offset:1104
	global_load_dwordx4 v[136:139], v[158:159], off offset:64
	global_load_dwordx2 v[140:141], v[160:161], off offset:96
	global_load_dwordx2 v[142:143], v[162:163], off offset:1120
	global_load_dwordx4 v[170:173], v[158:159], off offset:96
	global_load_dwordx2 v[174:175], v[160:161], off offset:112
	global_load_dwordx2 v[176:177], v[162:163], off offset:1136
	v_mfma_f32_32x32x16_bf16 v[32:47], v[68:71], v[76:79], v[32:47]
	v_mfma_f32_32x32x16_bf16 v[48:63], v[84:87], v[76:79], v[48:63]
	s_waitcnt vmcnt(21)
	v_lshlrev_b32_e32 v76, 16, v92
	v_and_b32_e32 v77, 0xffff0000, v92
	s_nop 7
	v_add_f32_e32 v48, v48, v88
	v_lshlrev_b32_e32 v68, 16, v94
	v_mul_f32_e32 v72, 0xbfb8aa3b, v68
	v_exp_f32_e32 v72, v72
	v_add_f32_e32 v49, v49, v89
	v_and_b32_e32 v69, 0xffff0000, v94
	v_mul_f32_e32 v48, 0xbfb8aa3b, v48
	v_add_f32_e32 v72, 1.0, v72
	v_mul_f32_e32 v49, 0xbfb8aa3b, v49
	v_rcp_f32_e32 v78, v72
	v_mul_f32_e32 v72, 0xbfb8aa3b, v69
	v_exp_f32_e32 v48, v48
	v_exp_f32_e32 v49, v49
	v_exp_f32_e32 v72, v72
	v_add_f32_e32 v50, v50, v90
	v_add_f32_e32 v51, v51, v91
	v_mul_f32_e32 v50, 0xbfb8aa3b, v50
	v_mul_f32_e32 v51, 0xbfb8aa3b, v51
	v_exp_f32_e32 v50, v50
	v_exp_f32_e32 v51, v51
	v_add_f32_e32 v48, 1.0, v48
	v_add_f32_e32 v49, 1.0, v49
	v_add_f32_e32 v72, 1.0, v72
	v_rcp_f32_e32 v48, v48
	v_rcp_f32_e32 v49, v49
	v_rcp_f32_e32 v79, v72
	v_add_f32_e32 v50, 1.0, v50
	v_add_f32_e32 v51, 1.0, v51
	v_rcp_f32_e32 v50, v50
	v_rcp_f32_e32 v51, v51
	v_pk_mul_f32 v[48:49], v[48:49], v[76:77]
	v_pk_mul_f32 v[68:69], v[78:79], v[68:69]
	v_lshlrev_b32_e32 v70, 16, v95
	v_pk_mul_f32 v[48:49], v[48:49], v[68:69]
	v_lshlrev_b32_e32 v68, 16, v93
	v_and_b32_e32 v69, 0xffff0000, v93
	v_and_b32_e32 v71, 0xffff0000, v95
	v_mul_f32_e32 v72, 0xbfb8aa3b, v70
	v_pk_mul_f32 v[50:51], v[50:51], v[68:69]
	v_mul_f32_e32 v68, 0xbfb8aa3b, v71
	v_exp_f32_e32 v72, v72
	v_exp_f32_e32 v68, v68
	v_add_f32_e32 v72, 1.0, v72
	v_add_f32_e32 v68, 1.0, v68
	v_rcp_f32_e32 v72, v72
	v_rcp_f32_e32 v73, v68
	s_nop 0
	v_pk_mul_f32 v[68:69], v[72:73], v[70:71]
	s_nop 0
	v_pk_mul_f32 v[50:51], v[50:51], v[68:69]
	v_cvt_pk_bf16_f32 v68, v48, v49
	v_cvt_pk_bf16_f32 v69, v50, v51
	v_lshl_add_u64 v[48:49], v[154:155], 0, s[2:3]
	global_store_dwordx2 v[48:49], v[68:69], off
	global_load_dwordx4 v[88:91], v[158:159], off offset:-128
	global_load_dwordx2 v[92:93], v[164:165], off
	global_load_dwordx2 v[94:95], v[166:167], off offset:1024
	s_nop 0
	s_waitcnt vmcnt(22)
; __device__ __forceinline__ float bflo(unsigned u) { return __uint_as_float(u << 16); }
; __device__ __forceinline__ float bfhi(unsigned u) { return __uint_as_float(u & 0xFFFF0000u); }
; __device__ __forceinline__ float sigmoidf_(float x) { return __builtin_amdgcn_rcpf(1.f + __expf(-x)); }
; __device__ __forceinline__ float siluf_(float x) { return x * __builtin_amdgcn_rcpf(1.f + __expf(-x)); }
; __device__ __forceinline__ void s5_pass2(const Params& p, int layer, int task, char* sm) {
;     ...
; #pragma unroll
;     for (int i = 0; i < 2; i++) {
;       const size_t tok = tok0 + wr * 64 + i * 32 + r32;
; #pragma unroll
;       for (int j = 0; j < 2; j++)
; #pragma unroll
;         for (int q = 0; q < 4; q++) {
;           const int n = tn * 128 + wc * 64 + j * 32 + q * 8 + h5 * 4;
;           float4 bg = *(const float4*)(p.b_glu + layer * 512 + n);
;           uint2 yy = *(const uint2*)(p.YG + tok * 512 + n);
;           uint2 zz = *(const uint2*)(p.P + tok * PW + C_S5Z + n);
;           float o0 = bflo(yy.x) * sigmoidf_(acc[i][j][4 * q] + bg.x) * siluf_(bflo(zz.x));
;           float o1 = bfhi(yy.x) * sigmoidf_(acc[i][j][4 * q + 1] + bg.y) * siluf_(bfhi(zz.x));
;           float o2 = bflo(yy.y) * sigmoidf_(acc[i][j][4 * q + 2] + bg.z) * siluf_(bflo(zz.y));
;           float o3 = bfhi(yy.y) * sigmoidf_(acc[i][j][4 * q + 3] + bg.w) * siluf_(bfhi(zz.y));
;           *(uint2*)(p.Y + tok * YW + Y_S5 + n) = make_uint2(pk2(o0, o1), pk2(o2, o3));
;         }
	v_add_f32_e32 v52, v52, v96
	v_lshlrev_b32_e32 v74, 16, v100
	v_and_b32_e32 v75, 0xffff0000, v100
	v_add_f32_e32 v50, v53, v97
	v_mul_f32_e32 v50, 0xbfb8aa3b, v50
	v_exp_f32_e32 v50, v50
	v_lshlrev_b32_e32 v68, 16, v102
	v_and_b32_e32 v69, 0xffff0000, v102
	v_mul_f32_e32 v52, 0xbfb8aa3b, v52
	v_add_f32_e32 v50, 1.0, v50
	v_rcp_f32_e32 v53, v50
	v_mul_f32_e32 v50, 0xbfb8aa3b, v68
	v_exp_f32_e32 v50, v50
	v_exp_f32_e32 v52, v52
	v_add_f32_e32 v54, v54, v98
	v_add_f32_e32 v55, v55, v99
	v_add_f32_e32 v50, 1.0, v50
	v_rcp_f32_e32 v76, v50
	v_mul_f32_e32 v50, 0xbfb8aa3b, v69
	v_exp_f32_e32 v50, v50
	v_mul_f32_e32 v54, 0xbfb8aa3b, v54
	v_mul_f32_e32 v55, 0xbfb8aa3b, v55
	v_exp_f32_e32 v54, v54
	v_exp_f32_e32 v55, v55
	v_add_f32_e32 v52, 1.0, v52
	v_add_f32_e32 v50, 1.0, v50
	v_rcp_f32_e32 v52, v52
	v_rcp_f32_e32 v77, v50
	v_add_f32_e32 v54, 1.0, v54
	v_add_f32_e32 v55, 1.0, v55
	v_rcp_f32_e32 v54, v54
	v_rcp_f32_e32 v55, v55
	v_pk_mul_f32 v[52:53], v[52:53], v[74:75]
	v_pk_mul_f32 v[68:69], v[76:77], v[68:69]
	v_lshlrev_b32_e32 v50, 16, v101
	v_pk_mul_f32 v[52:53], v[52:53], v[68:69]
	v_lshlrev_b32_e32 v68, 16, v103
	v_and_b32_e32 v51, 0xffff0000, v101
	v_and_b32_e32 v69, 0xffff0000, v103
	v_mul_f32_e32 v70, 0xbfb8aa3b, v68
	v_pk_mul_f32 v[50:51], v[54:55], v[50:51]
	v_mul_f32_e32 v54, 0xbfb8aa3b, v69
	v_exp_f32_e32 v70, v70
	v_exp_f32_e32 v54, v54
	v_cvt_pk_bf16_f32 v52, v52, v53
	v_add_f32_e32 v70, 1.0, v70
	v_add_f32_e32 v54, 1.0, v54
	v_rcp_f32_e32 v70, v70
	v_rcp_f32_e32 v71, v54
	s_nop 0
	v_pk_mul_f32 v[54:55], v[70:71], v[68:69]
	s_nop 0
	v_pk_mul_f32 v[50:51], v[50:51], v[54:55]
	s_nop 0
	v_cvt_pk_bf16_f32 v53, v50, v51
	global_store_dwordx2 v[48:49], v[52:53], off offset:16
	global_load_dwordx4 v[96:99], v[158:159], off offset:-96
	global_load_dwordx2 v[100:101], v[164:165], off offset:16
	global_load_dwordx2 v[102:103], v[166:167], off offset:1040
	s_nop 0
	s_waitcnt vmcnt(23)
	v_add_f32_e32 v50, v56, v104
	v_lshlrev_b32_e32 v70, 16, v108
	v_lshlrev_b32_e32 v56, 16, v110
	v_and_b32_e32 v71, 0xffff0000, v108
	v_mul_f32_e32 v54, 0xbfb8aa3b, v56
	v_exp_f32_e32 v54, v54
	v_add_f32_e32 v51, v57, v105
	v_and_b32_e32 v57, 0xffff0000, v110
	v_mul_f32_e32 v50, 0xbfb8aa3b, v50
	v_add_f32_e32 v54, 1.0, v54
	v_mul_f32_e32 v51, 0xbfb8aa3b, v51
	v_rcp_f32_e32 v72, v54
	v_mul_f32_e32 v54, 0xbfb8aa3b, v57
	v_exp_f32_e32 v50, v50
	v_exp_f32_e32 v51, v51
	v_exp_f32_e32 v54, v54
	v_add_f32_e32 v52, v58, v106
	v_add_f32_e32 v53, v59, v107
	v_mul_f32_e32 v52, 0xbfb8aa3b, v52
	v_mul_f32_e32 v53, 0xbfb8aa3b, v53
	v_exp_f32_e32 v52, v52
	v_exp_f32_e32 v53, v53
	v_add_f32_e32 v50, 1.0, v50
	v_add_f32_e32 v51, 1.0, v51
	v_add_f32_e32 v54, 1.0, v54
	v_rcp_f32_e32 v50, v50
	v_rcp_f32_e32 v51, v51
	v_rcp_f32_e32 v73, v54
	v_add_f32_e32 v52, 1.0, v52
	v_add_f32_e32 v53, 1.0, v53
	v_rcp_f32_e32 v52, v52
	v_rcp_f32_e32 v53, v53
	v_pk_mul_f32 v[50:51], v[50:51], v[70:71]
	v_pk_mul_f32 v[56:57], v[72:73], v[56:57]
	v_lshlrev_b32_e32 v54, 16, v109
	v_pk_mul_f32 v[50:51], v[50:51], v[56:57]
	v_lshlrev_b32_e32 v56, 16, v111
	v_and_b32_e32 v55, 0xffff0000, v109
	v_and_b32_e32 v57, 0xffff0000, v111
	v_mul_f32_e32 v58, 0xbfb8aa3b, v56
	v_pk_mul_f32 v[52:53], v[52:53], v[54:55]
	v_mul_f32_e32 v54, 0xbfb8aa3b, v57
	v_exp_f32_e32 v58, v58
	v_exp_f32_e32 v54, v54
	v_cvt_pk_bf16_f32 v50, v50, v51
	v_add_f32_e32 v58, 1.0, v58
	v_add_f32_e32 v54, 1.0, v54
	v_rcp_f32_e32 v58, v58
	v_rcp_f32_e32 v59, v54
	s_nop 0
	v_pk_mul_f32 v[54:55], v[58:59], v[56:57]
	s_nop 0
	v_pk_mul_f32 v[52:53], v[52:53], v[54:55]
	s_nop 0
	v_cvt_pk_bf16_f32 v51, v52, v53
	global_store_dwordx2 v[48:49], v[50:51], off offset:32
	global_load_dwordx4 v[104:107], v[158:159], off offset:-64
	global_load_dwordx2 v[108:109], v[164:165], off offset:32
	global_load_dwordx2 v[110:111], v[166:167], off offset:1056
	s_nop 0
	s_waitcnt vmcnt(24)
	v_add_f32_e32 v50, v60, v112
	v_lshlrev_b32_e32 v58, 16, v116
	v_lshlrev_b32_e32 v60, 16, v118
	v_and_b32_e32 v59, 0xffff0000, v116
	v_mul_f32_e32 v54, 0xbfb8aa3b, v60
	v_exp_f32_e32 v54, v54
	v_add_f32_e32 v51, v61, v113
	v_and_b32_e32 v61, 0xffff0000, v118
	v_mul_f32_e32 v50, 0xbfb8aa3b, v50
	v_add_f32_e32 v54, 1.0, v54
	v_mul_f32_e32 v51, 0xbfb8aa3b, v51
	v_rcp_f32_e32 v68, v54
	v_mul_f32_e32 v54, 0xbfb8aa3b, v61
	v_add_f32_e32 v52, v62, v114
	v_add_f32_e32 v53, v63, v115
	v_exp_f32_e32 v50, v50
	v_exp_f32_e32 v51, v51
	v_exp_f32_e32 v54, v54
	v_mul_f32_e32 v52, 0xbfb8aa3b, v52
	v_mul_f32_e32 v53, 0xbfb8aa3b, v53
	v_exp_f32_e32 v52, v52
	v_exp_f32_e32 v53, v53
	v_add_f32_e32 v50, 1.0, v50
	v_add_f32_e32 v51, 1.0, v51
	v_add_f32_e32 v54, 1.0, v54
	v_rcp_f32_e32 v50, v50
	v_rcp_f32_e32 v51, v51
	v_rcp_f32_e32 v69, v54
	v_add_f32_e32 v52, 1.0, v52
	v_add_f32_e32 v53, 1.0, v53
	v_rcp_f32_e32 v52, v52
	v_rcp_f32_e32 v53, v53
	v_pk_mul_f32 v[50:51], v[50:51], v[58:59]
	v_pk_mul_f32 v[58:59], v[68:69], v[60:61]
	v_lshlrev_b32_e32 v54, 16, v117
	v_lshlrev_b32_e32 v56, 16, v119
	v_and_b32_e32 v55, 0xffff0000, v117
	v_and_b32_e32 v57, 0xffff0000, v119
	v_pk_mul_f32 v[50:51], v[50:51], v[58:59]
	v_mul_f32_e32 v58, 0xbfb8aa3b, v56
	v_pk_mul_f32 v[52:53], v[52:53], v[54:55]
	v_mul_f32_e32 v54, 0xbfb8aa3b, v57
	v_exp_f32_e32 v58, v58
	v_exp_f32_e32 v54, v54
	v_cvt_pk_bf16_f32 v50, v50, v51
	v_add_f32_e32 v58, 1.0, v58
	v_add_f32_e32 v54, 1.0, v54
	v_rcp_f32_e32 v58, v58
	v_rcp_f32_e32 v59, v54
	s_nop 0
	v_pk_mul_f32 v[54:55], v[58:59], v[56:57]
	s_nop 0
	v_pk_mul_f32 v[52:53], v[52:53], v[54:55]
	s_nop 0
	v_cvt_pk_bf16_f32 v51, v52, v53
	global_store_dwordx2 v[48:49], v[50:51], off offset:48
	global_load_dwordx4 v[112:115], v[158:159], off offset:-32
	global_load_dwordx2 v[116:117], v[164:165], off offset:48
	global_load_dwordx2 v[118:119], v[166:167], off offset:1072
	s_nop 0
	s_waitcnt vmcnt(25)
; __device__ __forceinline__ float bflo(unsigned u) { return __uint_as_float(u << 16); }
; __device__ __forceinline__ float bfhi(unsigned u) { return __uint_as_float(u & 0xFFFF0000u); }
; __device__ __forceinline__ float sigmoidf_(float x) { return __builtin_amdgcn_rcpf(1.f + __expf(-x)); }
; __device__ __forceinline__ float siluf_(float x) { return x * __builtin_amdgcn_rcpf(1.f + __expf(-x)); }
; __device__ __forceinline__ void s5_pass2(const Params& p, int layer, int task, char* sm) {
;     ...
; #pragma unroll
;     for (int i = 0; i < 2; i++) {
;       const size_t tok = tok0 + wr * 64 + i * 32 + r32;
; #pragma unroll
;       for (int j = 0; j < 2; j++)
; #pragma unroll
;         for (int q = 0; q < 4; q++) {
;           const int n = tn * 128 + wc * 64 + j * 32 + q * 8 + h5 * 4;
;           float4 bg = *(const float4*)(p.b_glu + layer * 512 + n);
;           uint2 yy = *(const uint2*)(p.YG + tok * 512 + n);
;           uint2 zz = *(const uint2*)(p.P + tok * PW + C_S5Z + n);
;           float o0 = bflo(yy.x) * sigmoidf_(acc[i][j][4 * q] + bg.x) * siluf_(bflo(zz.x));
;           float o1 = bfhi(yy.x) * sigmoidf_(acc[i][j][4 * q + 1] + bg.y) * siluf_(bfhi(zz.x));
;           float o2 = bflo(yy.y) * sigmoidf_(acc[i][j][4 * q + 2] + bg.z) * siluf_(bflo(zz.y));
;           float o3 = bfhi(yy.y) * sigmoidf_(acc[i][j][4 * q + 3] + bg.w) * siluf_(bfhi(zz.y));
;           *(uint2*)(p.Y + tok * YW + Y_S5 + n) = make_uint2(pk2(o0, o1), pk2(o2, o3));
;         }
	v_add_f32_e32 v32, v32, v120
	v_lshlrev_b32_e32 v58, 16, v124
	v_lshlrev_b32_e32 v50, 16, v126
	v_and_b32_e32 v59, 0xffff0000, v124
	v_mul_f32_e32 v54, 0xbfb8aa3b, v50
	v_exp_f32_e32 v54, v54
	v_add_f32_e32 v33, v33, v121
	v_and_b32_e32 v51, 0xffff0000, v126
	v_mul_f32_e32 v32, 0xbfb8aa3b, v32
	v_add_f32_e32 v54, 1.0, v54
	v_mul_f32_e32 v33, 0xbfb8aa3b, v33
	v_rcp_f32_e32 v60, v54
	v_mul_f32_e32 v54, 0xbfb8aa3b, v51
	v_exp_f32_e32 v32, v32
	v_exp_f32_e32 v33, v33
	v_exp_f32_e32 v54, v54
	v_add_f32_e32 v34, v34, v122
	v_add_f32_e32 v35, v35, v123
	v_mul_f32_e32 v34, 0xbfb8aa3b, v34
	v_mul_f32_e32 v35, 0xbfb8aa3b, v35
	v_exp_f32_e32 v34, v34
	v_exp_f32_e32 v35, v35
	v_add_f32_e32 v32, 1.0, v32
	v_add_f32_e32 v33, 1.0, v33
	v_add_f32_e32 v54, 1.0, v54
	v_rcp_f32_e32 v32, v32
	v_rcp_f32_e32 v33, v33
	v_rcp_f32_e32 v61, v54
	v_add_f32_e32 v34, 1.0, v34
	v_add_f32_e32 v35, 1.0, v35
	v_rcp_f32_e32 v34, v34
	v_rcp_f32_e32 v35, v35
	v_pk_mul_f32 v[32:33], v[32:33], v[58:59]
	v_pk_mul_f32 v[50:51], v[60:61], v[50:51]
	v_lshlrev_b32_e32 v52, 16, v127
	v_pk_mul_f32 v[32:33], v[32:33], v[50:51]
	v_lshlrev_b32_e32 v50, 16, v125
	v_and_b32_e32 v51, 0xffff0000, v125
	v_and_b32_e32 v53, 0xffff0000, v127
	v_mul_f32_e32 v54, 0xbfb8aa3b, v52
	v_pk_mul_f32 v[34:35], v[34:35], v[50:51]
	v_mul_f32_e32 v50, 0xbfb8aa3b, v53
	v_exp_f32_e32 v54, v54
	v_exp_f32_e32 v50, v50
	v_cvt_pk_bf16_f32 v32, v32, v33
	v_add_f32_e32 v54, 1.0, v54
	v_add_f32_e32 v50, 1.0, v50
	v_rcp_f32_e32 v54, v54
	v_rcp_f32_e32 v55, v50
	s_nop 0
	v_pk_mul_f32 v[50:51], v[54:55], v[52:53]
	s_nop 0
	v_pk_mul_f32 v[34:35], v[34:35], v[50:51]
	s_nop 0
	v_cvt_pk_bf16_f32 v33, v34, v35
	global_store_dwordx2 v[48:49], v[32:33], off offset:64
	global_load_dwordx4 v[120:123], v[158:159], off
	global_load_dwordx2 v[124:125], v[164:165], off offset:64
	global_load_dwordx2 v[126:127], v[166:167], off offset:1088
	s_nop 0
	s_waitcnt vmcnt(26)
	v_add_f32_e32 v32, v36, v128
	v_lshlrev_b32_e32 v54, 16, v132
	v_lshlrev_b32_e32 v36, 16, v134
	v_and_b32_e32 v55, 0xffff0000, v132
	v_mul_f32_e32 v50, 0xbfb8aa3b, v36
	v_exp_f32_e32 v50, v50
	v_add_f32_e32 v33, v37, v129
	v_and_b32_e32 v37, 0xffff0000, v134
	v_mul_f32_e32 v32, 0xbfb8aa3b, v32
	v_add_f32_e32 v50, 1.0, v50
	v_mul_f32_e32 v33, 0xbfb8aa3b, v33
	v_rcp_f32_e32 v56, v50
	v_mul_f32_e32 v50, 0xbfb8aa3b, v37
	v_exp_f32_e32 v32, v32
	v_exp_f32_e32 v33, v33
	v_exp_f32_e32 v50, v50
	v_add_f32_e32 v34, v38, v130
	v_add_f32_e32 v35, v39, v131
	v_mul_f32_e32 v34, 0xbfb8aa3b, v34
	v_mul_f32_e32 v35, 0xbfb8aa3b, v35
	v_exp_f32_e32 v34, v34
	v_exp_f32_e32 v35, v35
	v_add_f32_e32 v32, 1.0, v32
	v_add_f32_e32 v33, 1.0, v33
	v_add_f32_e32 v50, 1.0, v50
	v_rcp_f32_e32 v32, v32
	v_rcp_f32_e32 v33, v33
	v_rcp_f32_e32 v57, v50
	v_add_f32_e32 v34, 1.0, v34
	v_add_f32_e32 v35, 1.0, v35
	v_rcp_f32_e32 v34, v34
	v_rcp_f32_e32 v35, v35
	v_pk_mul_f32 v[32:33], v[32:33], v[54:55]
	v_pk_mul_f32 v[36:37], v[56:57], v[36:37]
	v_lshlrev_b32_e32 v38, 16, v135
	v_pk_mul_f32 v[32:33], v[32:33], v[36:37]
	v_lshlrev_b32_e32 v36, 16, v133
	v_and_b32_e32 v37, 0xffff0000, v133
	v_and_b32_e32 v39, 0xffff0000, v135
	v_mul_f32_e32 v50, 0xbfb8aa3b, v38
	v_pk_mul_f32 v[34:35], v[34:35], v[36:37]
	v_mul_f32_e32 v36, 0xbfb8aa3b, v39
	v_exp_f32_e32 v50, v50
	v_exp_f32_e32 v36, v36
	v_cvt_pk_bf16_f32 v32, v32, v33
	v_add_f32_e32 v50, 1.0, v50
	v_add_f32_e32 v36, 1.0, v36
	v_rcp_f32_e32 v50, v50
	v_rcp_f32_e32 v51, v36
	s_nop 0
	v_pk_mul_f32 v[36:37], v[50:51], v[38:39]
	s_nop 0
	v_pk_mul_f32 v[34:35], v[34:35], v[36:37]
	s_nop 0
	v_cvt_pk_bf16_f32 v33, v34, v35
	global_store_dwordx2 v[48:49], v[32:33], off offset:80
	global_load_dwordx4 v[128:131], v[158:159], off offset:32
	global_load_dwordx2 v[132:133], v[164:165], off offset:80
	global_load_dwordx2 v[134:135], v[166:167], off offset:1104
	s_nop 0
	s_waitcnt vmcnt(27)
	v_add_f32_e32 v32, v40, v136
	v_lshlrev_b32_e32 v50, 16, v140
	v_lshlrev_b32_e32 v40, 16, v142
	v_and_b32_e32 v51, 0xffff0000, v140
	v_mul_f32_e32 v36, 0xbfb8aa3b, v40
	v_exp_f32_e32 v36, v36
	v_add_f32_e32 v33, v41, v137
	v_and_b32_e32 v41, 0xffff0000, v142
	v_mul_f32_e32 v32, 0xbfb8aa3b, v32
	v_add_f32_e32 v36, 1.0, v36
	v_mul_f32_e32 v33, 0xbfb8aa3b, v33
	v_rcp_f32_e32 v52, v36
	v_mul_f32_e32 v36, 0xbfb8aa3b, v41
	v_add_f32_e32 v34, v42, v138
	v_add_f32_e32 v35, v43, v139
	v_exp_f32_e32 v32, v32
	v_exp_f32_e32 v33, v33
	v_exp_f32_e32 v36, v36
	v_mul_f32_e32 v34, 0xbfb8aa3b, v34
	v_mul_f32_e32 v35, 0xbfb8aa3b, v35
	v_exp_f32_e32 v34, v34
	v_exp_f32_e32 v35, v35
	v_add_f32_e32 v32, 1.0, v32
	v_add_f32_e32 v33, 1.0, v33
	v_add_f32_e32 v36, 1.0, v36
	v_rcp_f32_e32 v32, v32
	v_rcp_f32_e32 v33, v33
	v_rcp_f32_e32 v53, v36
	v_add_f32_e32 v34, 1.0, v34
	v_add_f32_e32 v35, 1.0, v35
	v_rcp_f32_e32 v34, v34
	v_rcp_f32_e32 v35, v35
	v_pk_mul_f32 v[32:33], v[32:33], v[50:51]
	v_pk_mul_f32 v[40:41], v[52:53], v[40:41]
	v_lshlrev_b32_e32 v36, 16, v141
	v_lshlrev_b32_e32 v38, 16, v143
	v_and_b32_e32 v37, 0xffff0000, v141
	v_and_b32_e32 v39, 0xffff0000, v143
	v_pk_mul_f32 v[32:33], v[32:33], v[40:41]
	v_mul_f32_e32 v40, 0xbfb8aa3b, v38
	v_pk_mul_f32 v[34:35], v[34:35], v[36:37]
	v_mul_f32_e32 v36, 0xbfb8aa3b, v39
	v_exp_f32_e32 v40, v40
	v_exp_f32_e32 v36, v36
	v_cvt_pk_bf16_f32 v32, v32, v33
	v_add_f32_e32 v40, 1.0, v40
	v_add_f32_e32 v36, 1.0, v36
	v_rcp_f32_e32 v40, v40
	v_rcp_f32_e32 v41, v36
	s_nop 0
	v_pk_mul_f32 v[36:37], v[40:41], v[38:39]
	s_nop 0
	v_pk_mul_f32 v[34:35], v[34:35], v[36:37]
	s_nop 0
	v_cvt_pk_bf16_f32 v33, v34, v35
	global_store_dwordx2 v[48:49], v[32:33], off offset:96
	global_load_dwordx4 v[136:139], v[158:159], off offset:64
	global_load_dwordx2 v[140:141], v[164:165], off offset:96
	global_load_dwordx2 v[142:143], v[166:167], off offset:1120
	s_nop 0
	s_waitcnt vmcnt(28)
; __device__ __forceinline__ float bflo(unsigned u) { return __uint_as_float(u << 16); }
; __device__ __forceinline__ float bfhi(unsigned u) { return __uint_as_float(u & 0xFFFF0000u); }
; __device__ __forceinline__ float sigmoidf_(float x) { return __builtin_amdgcn_rcpf(1.f + __expf(-x)); }
; __device__ __forceinline__ float siluf_(float x) { return x * __builtin_amdgcn_rcpf(1.f + __expf(-x)); }
; __device__ __forceinline__ void s5_pass2(const Params& p, int layer, int task, char* sm) {
;     ...
; #pragma unroll
;     for (int i = 0; i < 2; i++) {
;       const size_t tok = tok0 + wr * 64 + i * 32 + r32;
; #pragma unroll
;       for (int j = 0; j < 2; j++)
; #pragma unroll
;         for (int q = 0; q < 4; q++) {
;           const int n = tn * 128 + wc * 64 + j * 32 + q * 8 + h5 * 4;
;           float4 bg = *(const float4*)(p.b_glu + layer * 512 + n);
;           uint2 yy = *(const uint2*)(p.YG + tok * 512 + n);
;           uint2 zz = *(const uint2*)(p.P + tok * PW + C_S5Z + n);
;           float o0 = bflo(yy.x) * sigmoidf_(acc[i][j][4 * q] + bg.x) * siluf_(bflo(zz.x));
;           float o1 = bfhi(yy.x) * sigmoidf_(acc[i][j][4 * q + 1] + bg.y) * siluf_(bfhi(zz.x));
;           float o2 = bflo(yy.y) * sigmoidf_(acc[i][j][4 * q + 2] + bg.z) * siluf_(bflo(zz.y));
;           float o3 = bfhi(yy.y) * sigmoidf_(acc[i][j][4 * q + 3] + bg.w) * siluf_(bfhi(zz.y));
;           *(uint2*)(p.Y + tok * YW + Y_S5 + n) = make_uint2(pk2(o0, o1), pk2(o2, o3));
;         }
	v_add_f32_e32 v32, v44, v170
	v_lshlrev_b32_e32 v40, 16, v174
	v_lshlrev_b32_e32 v42, 16, v176
	v_and_b32_e32 v41, 0xffff0000, v174
	v_mul_f32_e32 v36, 0xbfb8aa3b, v42
	v_exp_f32_e32 v36, v36
	v_add_f32_e32 v33, v45, v171
	v_and_b32_e32 v43, 0xffff0000, v176
	v_mul_f32_e32 v32, 0xbfb8aa3b, v32
	v_add_f32_e32 v36, 1.0, v36
	v_mul_f32_e32 v33, 0xbfb8aa3b, v33
	v_rcp_f32_e32 v44, v36
	v_mul_f32_e32 v36, 0xbfb8aa3b, v43
	v_add_f32_e32 v34, v46, v172
	v_add_f32_e32 v35, v47, v173
	v_exp_f32_e32 v32, v32
	v_exp_f32_e32 v33, v33
	v_exp_f32_e32 v36, v36
	v_mul_f32_e32 v34, 0xbfb8aa3b, v34
	v_mul_f32_e32 v35, 0xbfb8aa3b, v35
	v_exp_f32_e32 v34, v34
	v_exp_f32_e32 v35, v35
	v_add_f32_e32 v32, 1.0, v32
	v_add_f32_e32 v33, 1.0, v33
	v_add_f32_e32 v36, 1.0, v36
	v_rcp_f32_e32 v32, v32
	v_rcp_f32_e32 v33, v33
	v_rcp_f32_e32 v45, v36
	v_add_f32_e32 v34, 1.0, v34
	v_add_f32_e32 v35, 1.0, v35
	v_rcp_f32_e32 v34, v34
	v_rcp_f32_e32 v35, v35
	v_pk_mul_f32 v[32:33], v[32:33], v[40:41]
	v_pk_mul_f32 v[40:41], v[44:45], v[42:43]
	v_lshlrev_b32_e32 v36, 16, v175
	v_lshlrev_b32_e32 v38, 16, v177
	v_and_b32_e32 v37, 0xffff0000, v175
	v_and_b32_e32 v39, 0xffff0000, v177
	v_pk_mul_f32 v[32:33], v[32:33], v[40:41]
	v_mul_f32_e32 v40, 0xbfb8aa3b, v38
	v_pk_mul_f32 v[34:35], v[34:35], v[36:37]
	v_mul_f32_e32 v36, 0xbfb8aa3b, v39
	v_exp_f32_e32 v40, v40
	v_exp_f32_e32 v36, v36
	v_cvt_pk_bf16_f32 v32, v32, v33
	v_add_f32_e32 v40, 1.0, v40
	v_add_f32_e32 v36, 1.0, v36
	v_rcp_f32_e32 v40, v40
	v_rcp_f32_e32 v41, v36
	s_nop 0
	v_pk_mul_f32 v[36:37], v[40:41], v[38:39]
	s_nop 0
	v_pk_mul_f32 v[34:35], v[34:35], v[36:37]
	v_lshl_add_u64 v[38:39], v[150:151], 0, s[2:3]
	v_cvt_pk_bf16_f32 v33, v34, v35
	global_store_dwordx2 v[48:49], v[32:33], off offset:112
	global_load_dwordx4 v[170:173], v[158:159], off offset:96
	global_load_dwordx2 v[174:175], v[164:165], off offset:112
	global_load_dwordx2 v[176:177], v[166:167], off offset:1136
	v_lshl_add_u64 v[36:37], v[148:149], 0, s[2:3]
	s_waitcnt vmcnt(28)
	v_add_f32_e32 v16, v16, v88
	v_add_f32_e32 v17, v17, v89
	v_lshlrev_b32_e32 v32, 16, v94
	v_lshlrev_b32_e32 v44, 16, v92
	v_and_b32_e32 v45, 0xffff0000, v92
	v_mul_f32_e32 v40, 0xbfb8aa3b, v32
	v_exp_f32_e32 v40, v40
	v_and_b32_e32 v33, 0xffff0000, v94
	v_mul_f32_e32 v16, 0xbfb8aa3b, v16
	v_mul_f32_e32 v17, 0xbfb8aa3b, v17
	v_add_f32_e32 v40, 1.0, v40
	v_rcp_f32_e32 v46, v40
	v_mul_f32_e32 v40, 0xbfb8aa3b, v33
	v_exp_f32_e32 v16, v16
	v_exp_f32_e32 v17, v17
	v_exp_f32_e32 v40, v40
	v_add_f32_e32 v18, v18, v90
	v_add_f32_e32 v19, v19, v91
	v_mul_f32_e32 v18, 0xbfb8aa3b, v18
	v_mul_f32_e32 v19, 0xbfb8aa3b, v19
	v_exp_f32_e32 v18, v18
	v_exp_f32_e32 v19, v19
	v_add_f32_e32 v16, 1.0, v16
	v_add_f32_e32 v17, 1.0, v17
	v_add_f32_e32 v40, 1.0, v40
	v_rcp_f32_e32 v16, v16
	v_rcp_f32_e32 v17, v17
	v_rcp_f32_e32 v47, v40
	v_add_f32_e32 v18, 1.0, v18
	v_add_f32_e32 v19, 1.0, v19
	v_rcp_f32_e32 v18, v18
	v_rcp_f32_e32 v19, v19
	v_pk_mul_f32 v[16:17], v[16:17], v[44:45]
	v_pk_mul_f32 v[32:33], v[46:47], v[32:33]
	v_lshlrev_b32_e32 v34, 16, v95
	v_pk_mul_f32 v[16:17], v[16:17], v[32:33]
	v_lshlrev_b32_e32 v32, 16, v93
	v_and_b32_e32 v33, 0xffff0000, v93
	v_and_b32_e32 v35, 0xffff0000, v95
	v_mul_f32_e32 v40, 0xbfb8aa3b, v34
	v_pk_mul_f32 v[18:19], v[18:19], v[32:33]
	v_mul_f32_e32 v32, 0xbfb8aa3b, v35
	v_exp_f32_e32 v40, v40
	v_exp_f32_e32 v32, v32
	v_add_f32_e32 v40, 1.0, v40
	v_add_f32_e32 v32, 1.0, v32
	v_rcp_f32_e32 v40, v40
	v_rcp_f32_e32 v41, v32
	s_nop 0
	v_pk_mul_f32 v[32:33], v[40:41], v[34:35]
	s_nop 0
	v_pk_mul_f32 v[32:33], v[18:19], v[32:33]
	v_cvt_pk_bf16_f32 v18, v16, v17
	v_cvt_pk_bf16_f32 v19, v32, v33
	v_lshl_add_u64 v[16:17], v[146:147], 0, s[2:3]
	global_store_dwordx2 v[16:17], v[18:19], off
	s_add_u32 s2, s2, 0x100
	s_addc_u32 s3, s3, 0
	s_cmpk_eq_i32 s2, 0x400
	s_waitcnt vmcnt(25)
	v_add_f32_e32 v19, v20, v96
	v_add_f32_e32 v21, v21, v97
	v_mul_f32_e32 v19, 0xbfb8aa3b, v19
	v_mul_f32_e32 v21, 0xbfb8aa3b, v21
	v_exp_f32_e32 v19, v19
	v_exp_f32_e32 v21, v21
	v_lshlrev_b32_e32 v18, 16, v100
	v_lshlrev_b32_e32 v32, 16, v102
	v_add_f32_e32 v19, 1.0, v19
	v_add_f32_e32 v21, 1.0, v21
	v_rcp_f32_e32 v20, v19
	v_rcp_f32_e32 v21, v21
	v_and_b32_e32 v19, 0xffff0000, v100
	v_and_b32_e32 v33, 0xffff0000, v102
	v_mul_f32_e32 v40, 0xbfb8aa3b, v32
	v_pk_mul_f32 v[18:19], v[20:21], v[18:19]
	v_mul_f32_e32 v20, 0xbfb8aa3b, v33
	v_exp_f32_e32 v40, v40
	v_exp_f32_e32 v20, v20
	v_add_f32_e32 v23, v23, v99
	v_mul_f32_e32 v23, 0xbfb8aa3b, v23
	v_add_f32_e32 v40, 1.0, v40
	v_add_f32_e32 v20, 1.0, v20
	v_rcp_f32_e32 v44, v40
	v_rcp_f32_e32 v45, v20
	v_exp_f32_e32 v23, v23
	v_pk_mul_f32 v[20:21], v[44:45], v[32:33]
	s_nop 0
	v_pk_mul_f32 v[18:19], v[18:19], v[20:21]
	v_add_f32_e32 v21, v22, v98
	v_mul_f32_e32 v21, 0xbfb8aa3b, v21
	v_exp_f32_e32 v21, v21
	v_add_f32_e32 v23, 1.0, v23
	v_rcp_f32_e32 v23, v23
	v_lshlrev_b32_e32 v20, 16, v101
	v_add_f32_e32 v21, 1.0, v21
	v_rcp_f32_e32 v22, v21
	v_lshlrev_b32_e32 v32, 16, v103
	v_and_b32_e32 v21, 0xffff0000, v101
	v_and_b32_e32 v33, 0xffff0000, v103
	v_mul_f32_e32 v34, 0xbfb8aa3b, v32
	v_pk_mul_f32 v[20:21], v[22:23], v[20:21]
	v_mul_f32_e32 v22, 0xbfb8aa3b, v33
	v_exp_f32_e32 v34, v34
	v_exp_f32_e32 v22, v22
	v_cvt_pk_bf16_f32 v18, v18, v19
	v_add_f32_e32 v34, 1.0, v34
	v_add_f32_e32 v22, 1.0, v22
	v_rcp_f32_e32 v34, v34
	v_rcp_f32_e32 v35, v22
	s_nop 0
	v_pk_mul_f32 v[22:23], v[34:35], v[32:33]
	s_nop 0
	v_pk_mul_f32 v[20:21], v[20:21], v[22:23]
	s_nop 0
	v_cvt_pk_bf16_f32 v19, v20, v21
	global_store_dwordx2 v[16:17], v[18:19], off offset:16
	s_nop 0
	s_waitcnt vmcnt(22)
; __device__ __forceinline__ float bflo(unsigned u) { return __uint_as_float(u << 16); }
; __device__ __forceinline__ float bfhi(unsigned u) { return __uint_as_float(u & 0xFFFF0000u); }
; __device__ __forceinline__ float sigmoidf_(float x) { return __builtin_amdgcn_rcpf(1.f + __expf(-x)); }
; __device__ __forceinline__ float siluf_(float x) { return x * __builtin_amdgcn_rcpf(1.f + __expf(-x)); }
; __device__ __forceinline__ void s5_pass2(const Params& p, int layer, int task, char* sm) {
;     ...
; #pragma unroll
;     for (int i = 0; i < 2; i++) {
;       const size_t tok = tok0 + wr * 64 + i * 32 + r32;
; #pragma unroll
;       for (int j = 0; j < 2; j++)
; #pragma unroll
;         for (int q = 0; q < 4; q++) {
;           const int n = tn * 128 + wc * 64 + j * 32 + q * 8 + h5 * 4;
;           float4 bg = *(const float4*)(p.b_glu + layer * 512 + n);
;           uint2 yy = *(const uint2*)(p.YG + tok * 512 + n);
;           uint2 zz = *(const uint2*)(p.P + tok * PW + C_S5Z + n);
;           float o0 = bflo(yy.x) * sigmoidf_(acc[i][j][4 * q] + bg.x) * siluf_(bflo(zz.x));
;           float o1 = bfhi(yy.x) * sigmoidf_(acc[i][j][4 * q + 1] + bg.y) * siluf_(bfhi(zz.x));
;           float o2 = bflo(yy.y) * sigmoidf_(acc[i][j][4 * q + 2] + bg.z) * siluf_(bflo(zz.y));
;           float o3 = bfhi(yy.y) * sigmoidf_(acc[i][j][4 * q + 3] + bg.w) * siluf_(bfhi(zz.y));
;           *(uint2*)(p.Y + tok * YW + Y_S5 + n) = make_uint2(pk2(o0, o1), pk2(o2, o3));
;         }
	v_add_f32_e32 v18, v24, v104
	v_lshlrev_b32_e32 v34, 16, v108
	v_lshlrev_b32_e32 v24, 16, v110
	v_and_b32_e32 v35, 0xffff0000, v108
	v_mul_f32_e32 v22, 0xbfb8aa3b, v24
	v_exp_f32_e32 v22, v22
	v_add_f32_e32 v19, v25, v105
	v_and_b32_e32 v25, 0xffff0000, v110
	v_mul_f32_e32 v18, 0xbfb8aa3b, v18
	v_add_f32_e32 v22, 1.0, v22
	v_mul_f32_e32 v19, 0xbfb8aa3b, v19
	v_rcp_f32_e32 v40, v22
	v_mul_f32_e32 v22, 0xbfb8aa3b, v25
	v_exp_f32_e32 v18, v18
	v_exp_f32_e32 v19, v19
	v_exp_f32_e32 v22, v22
	v_add_f32_e32 v20, v26, v106
	v_add_f32_e32 v21, v27, v107
	v_mul_f32_e32 v20, 0xbfb8aa3b, v20
	v_mul_f32_e32 v21, 0xbfb8aa3b, v21
	v_exp_f32_e32 v20, v20
	v_exp_f32_e32 v21, v21
	v_add_f32_e32 v18, 1.0, v18
	v_add_f32_e32 v19, 1.0, v19
	v_add_f32_e32 v22, 1.0, v22
	v_rcp_f32_e32 v18, v18
	v_rcp_f32_e32 v19, v19
	v_rcp_f32_e32 v41, v22
	v_add_f32_e32 v20, 1.0, v20
	v_add_f32_e32 v21, 1.0, v21
	v_rcp_f32_e32 v20, v20
	v_rcp_f32_e32 v21, v21
	v_pk_mul_f32 v[18:19], v[18:19], v[34:35]
	v_pk_mul_f32 v[24:25], v[40:41], v[24:25]
	v_lshlrev_b32_e32 v22, 16, v109
	v_pk_mul_f32 v[18:19], v[18:19], v[24:25]
	v_lshlrev_b32_e32 v24, 16, v111
	v_and_b32_e32 v23, 0xffff0000, v109
	v_and_b32_e32 v25, 0xffff0000, v111
	v_mul_f32_e32 v26, 0xbfb8aa3b, v24
	v_pk_mul_f32 v[20:21], v[20:21], v[22:23]
	v_mul_f32_e32 v22, 0xbfb8aa3b, v25
	v_exp_f32_e32 v26, v26
	v_exp_f32_e32 v22, v22
	v_cvt_pk_bf16_f32 v18, v18, v19
	v_add_f32_e32 v26, 1.0, v26
	v_add_f32_e32 v22, 1.0, v22
	v_rcp_f32_e32 v26, v26
	v_rcp_f32_e32 v27, v22
	s_nop 0
	v_pk_mul_f32 v[22:23], v[26:27], v[24:25]
	s_nop 0
	v_pk_mul_f32 v[20:21], v[20:21], v[22:23]
	s_nop 0
	v_cvt_pk_bf16_f32 v19, v20, v21
	global_store_dwordx2 v[16:17], v[18:19], off offset:32
	s_nop 0
	s_waitcnt vmcnt(19)
	v_add_f32_e32 v18, v28, v112
	v_lshlrev_b32_e32 v26, 16, v116
	v_lshlrev_b32_e32 v28, 16, v118
	v_and_b32_e32 v27, 0xffff0000, v116
	v_mul_f32_e32 v22, 0xbfb8aa3b, v28
	v_exp_f32_e32 v22, v22
	v_add_f32_e32 v19, v29, v113
	v_and_b32_e32 v29, 0xffff0000, v118
	v_mul_f32_e32 v18, 0xbfb8aa3b, v18
	v_add_f32_e32 v22, 1.0, v22
	v_mul_f32_e32 v19, 0xbfb8aa3b, v19
	v_rcp_f32_e32 v32, v22
	v_mul_f32_e32 v22, 0xbfb8aa3b, v29
	v_add_f32_e32 v20, v30, v114
	v_add_f32_e32 v21, v31, v115
	v_exp_f32_e32 v18, v18
	v_exp_f32_e32 v19, v19
	v_exp_f32_e32 v22, v22
	v_mul_f32_e32 v20, 0xbfb8aa3b, v20
	v_mul_f32_e32 v21, 0xbfb8aa3b, v21
	v_exp_f32_e32 v20, v20
	v_exp_f32_e32 v21, v21
	v_add_f32_e32 v18, 1.0, v18
	v_add_f32_e32 v19, 1.0, v19
	v_add_f32_e32 v22, 1.0, v22
	v_rcp_f32_e32 v18, v18
	v_rcp_f32_e32 v19, v19
	v_rcp_f32_e32 v33, v22
	v_add_f32_e32 v20, 1.0, v20
	v_add_f32_e32 v21, 1.0, v21
	v_rcp_f32_e32 v20, v20
	v_rcp_f32_e32 v21, v21
	v_pk_mul_f32 v[18:19], v[18:19], v[26:27]
	v_pk_mul_f32 v[26:27], v[32:33], v[28:29]
	v_lshlrev_b32_e32 v22, 16, v117
	v_lshlrev_b32_e32 v24, 16, v119
	v_and_b32_e32 v23, 0xffff0000, v117
	v_and_b32_e32 v25, 0xffff0000, v119
	v_pk_mul_f32 v[18:19], v[18:19], v[26:27]
	v_mul_f32_e32 v26, 0xbfb8aa3b, v24
	v_pk_mul_f32 v[20:21], v[20:21], v[22:23]
	v_mul_f32_e32 v22, 0xbfb8aa3b, v25
	v_exp_f32_e32 v26, v26
	v_exp_f32_e32 v22, v22
	v_cvt_pk_bf16_f32 v18, v18, v19
	v_add_f32_e32 v26, 1.0, v26
	v_add_f32_e32 v22, 1.0, v22
	v_rcp_f32_e32 v26, v26
	v_rcp_f32_e32 v27, v22
	s_nop 0
	v_pk_mul_f32 v[22:23], v[26:27], v[24:25]
	s_nop 0
	v_pk_mul_f32 v[20:21], v[20:21], v[22:23]
	s_nop 0
	v_cvt_pk_bf16_f32 v19, v20, v21
	global_store_dwordx2 v[16:17], v[18:19], off offset:48
	s_nop 0
	s_waitcnt vmcnt(16)
	v_add_f32_e32 v0, v0, v120
	v_lshlrev_b32_e32 v26, 16, v124
	v_lshlrev_b32_e32 v18, 16, v126
	v_and_b32_e32 v27, 0xffff0000, v124
	v_mul_f32_e32 v22, 0xbfb8aa3b, v18
	v_exp_f32_e32 v22, v22
	v_add_f32_e32 v1, v1, v121
	v_and_b32_e32 v19, 0xffff0000, v126
	v_mul_f32_e32 v0, 0xbfb8aa3b, v0
	v_add_f32_e32 v22, 1.0, v22
	v_mul_f32_e32 v1, 0xbfb8aa3b, v1
	v_rcp_f32_e32 v28, v22
	v_mul_f32_e32 v22, 0xbfb8aa3b, v19
	v_exp_f32_e32 v0, v0
	v_exp_f32_e32 v1, v1
	v_exp_f32_e32 v22, v22
	v_add_f32_e32 v2, v2, v122
	v_add_f32_e32 v3, v3, v123
	v_mul_f32_e32 v2, 0xbfb8aa3b, v2
	v_mul_f32_e32 v3, 0xbfb8aa3b, v3
	v_exp_f32_e32 v2, v2
	v_exp_f32_e32 v3, v3
	v_add_f32_e32 v0, 1.0, v0
	v_add_f32_e32 v1, 1.0, v1
	v_add_f32_e32 v22, 1.0, v22
	v_rcp_f32_e32 v0, v0
	v_rcp_f32_e32 v1, v1
	v_rcp_f32_e32 v29, v22
	v_add_f32_e32 v2, 1.0, v2
	v_add_f32_e32 v3, 1.0, v3
	v_rcp_f32_e32 v2, v2
	v_rcp_f32_e32 v3, v3
	v_pk_mul_f32 v[0:1], v[0:1], v[26:27]
	v_pk_mul_f32 v[18:19], v[28:29], v[18:19]
	v_lshlrev_b32_e32 v20, 16, v127
	v_pk_mul_f32 v[0:1], v[0:1], v[18:19]
	v_lshlrev_b32_e32 v18, 16, v125
	v_and_b32_e32 v19, 0xffff0000, v125
	v_and_b32_e32 v21, 0xffff0000, v127
	v_mul_f32_e32 v22, 0xbfb8aa3b, v20
	v_pk_mul_f32 v[2:3], v[2:3], v[18:19]
	v_mul_f32_e32 v18, 0xbfb8aa3b, v21
	v_exp_f32_e32 v22, v22
	v_exp_f32_e32 v18, v18
	v_cvt_pk_bf16_f32 v0, v0, v1
	v_add_f32_e32 v22, 1.0, v22
	v_add_f32_e32 v18, 1.0, v18
	v_rcp_f32_e32 v22, v22
	v_rcp_f32_e32 v23, v18
	s_nop 0
	v_pk_mul_f32 v[18:19], v[22:23], v[20:21]
	s_nop 0
	v_pk_mul_f32 v[2:3], v[2:3], v[18:19]
	s_nop 0
	v_cvt_pk_bf16_f32 v1, v2, v3
	global_store_dwordx2 v[16:17], v[0:1], off offset:64
	s_nop 0
	s_waitcnt vmcnt(13)
; __device__ __forceinline__ float bflo(unsigned u) { return __uint_as_float(u << 16); }
; __device__ __forceinline__ float bfhi(unsigned u) { return __uint_as_float(u & 0xFFFF0000u); }
; __device__ __forceinline__ float sigmoidf_(float x) { return __builtin_amdgcn_rcpf(1.f + __expf(-x)); }
; __device__ __forceinline__ float siluf_(float x) { return x * __builtin_amdgcn_rcpf(1.f + __expf(-x)); }
; __device__ __forceinline__ void s5_pass2(const Params& p, int layer, int task, char* sm) {
;     ...
; #pragma unroll
;     for (int i = 0; i < 2; i++) {
;       const size_t tok = tok0 + wr * 64 + i * 32 + r32;
; #pragma unroll
;       for (int j = 0; j < 2; j++)
; #pragma unroll
;         for (int q = 0; q < 4; q++) {
;           const int n = tn * 128 + wc * 64 + j * 32 + q * 8 + h5 * 4;
;           float4 bg = *(const float4*)(p.b_glu + layer * 512 + n);
;           uint2 yy = *(const uint2*)(p.YG + tok * 512 + n);
;           uint2 zz = *(const uint2*)(p.P + tok * PW + C_S5Z + n);
;           float o0 = bflo(yy.x) * sigmoidf_(acc[i][j][4 * q] + bg.x) * siluf_(bflo(zz.x));
;           float o1 = bfhi(yy.x) * sigmoidf_(acc[i][j][4 * q + 1] + bg.y) * siluf_(bfhi(zz.x));
;           float o2 = bflo(yy.y) * sigmoidf_(acc[i][j][4 * q + 2] + bg.z) * siluf_(bflo(zz.y));
;           float o3 = bfhi(yy.y) * sigmoidf_(acc[i][j][4 * q + 3] + bg.w) * siluf_(bfhi(zz.y));
;           *(uint2*)(p.Y + tok * YW + Y_S5 + n) = make_uint2(pk2(o0, o1), pk2(o2, o3));
;         }
	v_add_f32_e32 v0, v4, v128
	v_lshlrev_b32_e32 v22, 16, v132
	v_lshlrev_b32_e32 v4, 16, v134
	v_and_b32_e32 v23, 0xffff0000, v132
	v_mul_f32_e32 v18, 0xbfb8aa3b, v4
	v_exp_f32_e32 v18, v18
	v_add_f32_e32 v1, v5, v129
	v_and_b32_e32 v5, 0xffff0000, v134
	v_mul_f32_e32 v0, 0xbfb8aa3b, v0
	v_add_f32_e32 v18, 1.0, v18
	v_mul_f32_e32 v1, 0xbfb8aa3b, v1
	v_rcp_f32_e32 v24, v18
	v_mul_f32_e32 v18, 0xbfb8aa3b, v5
	v_exp_f32_e32 v0, v0
	v_exp_f32_e32 v1, v1
	v_exp_f32_e32 v18, v18
	v_add_f32_e32 v2, v6, v130
	v_add_f32_e32 v3, v7, v131
	v_mul_f32_e32 v2, 0xbfb8aa3b, v2
	v_mul_f32_e32 v3, 0xbfb8aa3b, v3
	v_exp_f32_e32 v2, v2
	v_exp_f32_e32 v3, v3
	v_add_f32_e32 v0, 1.0, v0
	v_add_f32_e32 v1, 1.0, v1
	v_add_f32_e32 v18, 1.0, v18
	v_rcp_f32_e32 v0, v0
	v_rcp_f32_e32 v1, v1
	v_rcp_f32_e32 v25, v18
	v_add_f32_e32 v2, 1.0, v2
	v_add_f32_e32 v3, 1.0, v3
	v_rcp_f32_e32 v2, v2
	v_rcp_f32_e32 v3, v3
	v_pk_mul_f32 v[0:1], v[0:1], v[22:23]
	v_pk_mul_f32 v[4:5], v[24:25], v[4:5]
	v_lshlrev_b32_e32 v6, 16, v135
	v_pk_mul_f32 v[0:1], v[0:1], v[4:5]
	v_lshlrev_b32_e32 v4, 16, v133
	v_and_b32_e32 v5, 0xffff0000, v133
	v_and_b32_e32 v7, 0xffff0000, v135
	v_mul_f32_e32 v18, 0xbfb8aa3b, v6
	v_pk_mul_f32 v[2:3], v[2:3], v[4:5]
	v_mul_f32_e32 v4, 0xbfb8aa3b, v7
	v_exp_f32_e32 v18, v18
	v_exp_f32_e32 v4, v4
	v_cvt_pk_bf16_f32 v0, v0, v1
	v_add_f32_e32 v18, 1.0, v18
	v_add_f32_e32 v4, 1.0, v4
	v_rcp_f32_e32 v18, v18
	v_rcp_f32_e32 v19, v4
	s_nop 0
	v_pk_mul_f32 v[4:5], v[18:19], v[6:7]
	s_nop 0
	v_pk_mul_f32 v[2:3], v[2:3], v[4:5]
	s_nop 0
	v_cvt_pk_bf16_f32 v1, v2, v3
	global_store_dwordx2 v[16:17], v[0:1], off offset:80
	s_nop 0
	s_waitcnt vmcnt(10)
	v_add_f32_e32 v0, v8, v136
	v_lshlrev_b32_e32 v18, 16, v140
	v_lshlrev_b32_e32 v8, 16, v142
	v_and_b32_e32 v19, 0xffff0000, v140
	v_mul_f32_e32 v4, 0xbfb8aa3b, v8
	v_exp_f32_e32 v4, v4
	v_add_f32_e32 v1, v9, v137
	v_and_b32_e32 v9, 0xffff0000, v142
	v_mul_f32_e32 v0, 0xbfb8aa3b, v0
	v_add_f32_e32 v4, 1.0, v4
	v_mul_f32_e32 v1, 0xbfb8aa3b, v1
	v_rcp_f32_e32 v20, v4
	v_mul_f32_e32 v4, 0xbfb8aa3b, v9
	v_add_f32_e32 v2, v10, v138
	v_add_f32_e32 v3, v11, v139
	v_exp_f32_e32 v0, v0
	v_exp_f32_e32 v1, v1
	v_exp_f32_e32 v4, v4
	v_mul_f32_e32 v2, 0xbfb8aa3b, v2
	v_mul_f32_e32 v3, 0xbfb8aa3b, v3
	v_exp_f32_e32 v2, v2
	v_exp_f32_e32 v3, v3
	v_add_f32_e32 v0, 1.0, v0
	v_add_f32_e32 v1, 1.0, v1
	v_add_f32_e32 v4, 1.0, v4
	v_rcp_f32_e32 v0, v0
	v_rcp_f32_e32 v1, v1
	v_rcp_f32_e32 v21, v4
	v_add_f32_e32 v2, 1.0, v2
	v_add_f32_e32 v3, 1.0, v3
	v_rcp_f32_e32 v2, v2
	v_rcp_f32_e32 v3, v3
	v_pk_mul_f32 v[0:1], v[0:1], v[18:19]
	v_pk_mul_f32 v[8:9], v[20:21], v[8:9]
	v_lshlrev_b32_e32 v4, 16, v141
	v_lshlrev_b32_e32 v6, 16, v143
	v_and_b32_e32 v5, 0xffff0000, v141
	v_and_b32_e32 v7, 0xffff0000, v143
	v_pk_mul_f32 v[0:1], v[0:1], v[8:9]
	v_mul_f32_e32 v8, 0xbfb8aa3b, v6
	v_pk_mul_f32 v[2:3], v[2:3], v[4:5]
	v_mul_f32_e32 v4, 0xbfb8aa3b, v7
	v_exp_f32_e32 v8, v8
	v_exp_f32_e32 v4, v4
	v_cvt_pk_bf16_f32 v0, v0, v1
	v_add_f32_e32 v8, 1.0, v8
	v_add_f32_e32 v4, 1.0, v4
	v_rcp_f32_e32 v8, v8
	v_rcp_f32_e32 v9, v4
	s_nop 0
	v_pk_mul_f32 v[4:5], v[8:9], v[6:7]
	s_nop 0
	v_pk_mul_f32 v[2:3], v[2:3], v[4:5]
	s_nop 0
	v_cvt_pk_bf16_f32 v1, v2, v3
	global_store_dwordx2 v[16:17], v[0:1], off offset:96
	s_nop 0
	v_lshl_add_u64 v[158:159], v[158:159], 0, s[6:7]
	s_waitcnt vmcnt(7)
	v_add_f32_e32 v0, v12, v170
	v_lshlrev_b32_e32 v8, 16, v174
	v_lshlrev_b32_e32 v10, 16, v176
	v_and_b32_e32 v9, 0xffff0000, v174
	v_mul_f32_e32 v4, 0xbfb8aa3b, v10
	v_exp_f32_e32 v4, v4
	v_add_f32_e32 v1, v13, v171
	v_and_b32_e32 v11, 0xffff0000, v176
	v_mul_f32_e32 v0, 0xbfb8aa3b, v0
	v_add_f32_e32 v4, 1.0, v4
	v_mul_f32_e32 v1, 0xbfb8aa3b, v1
	v_rcp_f32_e32 v12, v4
	v_mul_f32_e32 v4, 0xbfb8aa3b, v11
	v_add_f32_e32 v2, v14, v172
	v_add_f32_e32 v3, v15, v173
	v_exp_f32_e32 v0, v0
	v_exp_f32_e32 v1, v1
	v_exp_f32_e32 v4, v4
	v_mul_f32_e32 v2, 0xbfb8aa3b, v2
	v_mul_f32_e32 v3, 0xbfb8aa3b, v3
	v_exp_f32_e32 v2, v2
	v_exp_f32_e32 v3, v3
	v_add_f32_e32 v0, 1.0, v0
	v_add_f32_e32 v1, 1.0, v1
	v_add_f32_e32 v4, 1.0, v4
	v_rcp_f32_e32 v0, v0
	v_rcp_f32_e32 v1, v1
	v_rcp_f32_e32 v13, v4
	v_add_f32_e32 v2, 1.0, v2
	v_add_f32_e32 v3, 1.0, v3
	v_rcp_f32_e32 v2, v2
	v_rcp_f32_e32 v3, v3
	v_pk_mul_f32 v[0:1], v[0:1], v[8:9]
	v_pk_mul_f32 v[8:9], v[12:13], v[10:11]
	v_lshlrev_b32_e32 v4, 16, v175
	v_lshlrev_b32_e32 v6, 16, v177
	v_and_b32_e32 v5, 0xffff0000, v175
	v_and_b32_e32 v7, 0xffff0000, v177
	v_pk_mul_f32 v[0:1], v[0:1], v[8:9]
	v_mul_f32_e32 v8, 0xbfb8aa3b, v6
	v_pk_mul_f32 v[2:3], v[2:3], v[4:5]
	v_mul_f32_e32 v4, 0xbfb8aa3b, v7
	v_exp_f32_e32 v8, v8
	v_exp_f32_e32 v4, v4
	v_cvt_pk_bf16_f32 v0, v0, v1
	v_add_f32_e32 v8, 1.0, v8
	v_add_f32_e32 v4, 1.0, v4
	v_rcp_f32_e32 v8, v8
	v_rcp_f32_e32 v9, v4
	s_nop 0
	v_pk_mul_f32 v[4:5], v[8:9], v[6:7]
	s_nop 0
	v_pk_mul_f32 v[2:3], v[2:3], v[4:5]
	s_nop 0
	v_cvt_pk_bf16_f32 v1, v2, v3
	global_store_dwordx2 v[16:17], v[0:1], off offset:112
	s_cbranch_scc0 .LBB0_1800
	s_branch .LBB0_1568

; __device__ __forceinline__ int otid() { return otid_full() & 255; }
; template <int D>
; __device__ __forceinline__ void gemm_acc(const bf* __restrict__ A, int lda, const bf* __restrict__ Bt, int ldb, int K,
;                                          f32x16 (&acc)[2][2], char* sm) {
;   const int tid = otid(), lane = tid & 63, w = tid >> 6, wr = w >> 1, wc = w & 1, r32 = lane & 31, h5 = lane >> 5;
;   const int lrow = tid >> 2, lch = tid & 3;
;   const bf* ga = A + (size_t)lrow * lda + lch * 8;
;   const bf* gb = Bt + (size_t)lrow * ldb + lch * 8;
;   const size_t a64 = (size_t)64 * lda, b64 = (size_t)64 * ldb;
;   const int nk = K >> 5;
;   char* sA = sm; char* sB = sm + 20480;
;   const int woff = lrow * 80 + lch * 16;
;   const int aoff = (wr * 64 + r32) * 80 + h5 * 16, boff = (wc * 64 + r32) * 80 + h5 * 16;
;   GStage S0, S1, S2, S3;
;   G_LOAD(S0, 0) G_LOAD(S1, 32)
;   if (D == 4) { G_LOAD(S2, 64) G_LOAD(S3, 96) }
;   G_WRITE(S0, 0)
;   if (D < nk) G_LOAD(S0, D * 32)
;   __syncthreads();
;   for (int kt0 = 0; kt0 < nk; kt0 += D) {
;     if (D == 4) {
;       G_ITER(kt0, 0, S1) G_ITER(kt0 + 1, 10240, S2) G_ITER(kt0 + 2, 0, S3) G_ITER(kt0 + 3, 10240, S0)
.LBB0_2064:
	v_mov_b32_e32 v0, v145
	v_mov_b32_e32 v20, v203
	v_mov_b32_e32 v17, v145
	v_bfe_u32 v22, v20, 2, 6
	v_lshlrev_b32_e32 v144, 10, v22
	v_lshlrev_b32_e32 v16, 4, v20
	v_lshl_add_u64 v[18:19], s[0:1], 0, v[144:145]
	v_and_b32_e32 v16, 48, v16
	v_lshl_add_u64 v[160:161], v[18:19], 0, v[16:17]
	v_and_b32_e32 v21, 31, v20
	v_bfe_u32 v18, v20, 1, 7
	v_add_co_u32_e32 v162, vcc, s34, v160
	v_and_or_b32 v19, v18, 64, v21
	v_and_b32_e32 v35, 16, v18
	v_and_b32_e32 v18, 0x5f, v20
	v_addc_co_u32_e32 v163, vcc, 0, v161, vcc
	v_or_b32_e32 v144, v144, v16
	v_mul_u32_u24_e32 v17, 0x50, v22
	v_mul_u32_u24_e32 v34, 0x50, v19
	v_mul_u32_u24_e32 v36, 0x50, v18
	global_load_dwordx4 v[18:21], v[160:161], off
	global_load_dwordx4 v[22:25], v[162:163], off
	global_load_dwordx4 v[26:29], v144, s[4:5]
	v_lshl_add_u64 v[30:31], s[4:5], 0, v[144:145]
	v_add_co_u32_e32 v164, vcc, s34, v30
	v_add3_u32 v167, v17, v16, s84
	s_nop 0
	v_addc_co_u32_e32 v165, vcc, 0, v31, vcc
	global_load_dwordx4 v[30:33], v[164:165], off
	global_load_dwordx4 v[112:115], v[160:161], off offset:64
	global_load_dwordx4 v[116:119], v[162:163], off offset:64
	global_load_dwordx4 v[120:123], v144, s[4:5] offset:64
	global_load_dwordx4 v[124:127], v[164:165], off offset:64
	global_load_dwordx4 v[96:99], v[160:161], off offset:128
	global_load_dwordx4 v[100:103], v[162:163], off offset:128
	global_load_dwordx4 v[104:107], v144, s[4:5] offset:128
	global_load_dwordx4 v[108:111], v[164:165], off offset:128
	global_load_dwordx4 v[80:83], v[160:161], off offset:192
	global_load_dwordx4 v[84:87], v[162:163], off offset:192
	global_load_dwordx4 v[88:91], v144, s[4:5] offset:192
	global_load_dwordx4 v[92:95], v[164:165], off offset:192
	v_add3_u32 v166, v34, v35, s84
	v_add3_u32 v168, v35, v36, s84
	v_mov_b32_e32 v1, v0
	v_mov_b32_e32 v2, v0
	v_mov_b32_e32 v3, v0
	v_mov_b32_e32 v4, v0
	v_mov_b32_e32 v5, v0
	v_mov_b32_e32 v6, v0
	v_mov_b32_e32 v7, v0
	v_mov_b32_e32 v8, v0
	v_mov_b32_e32 v9, v0
	v_mov_b32_e32 v10, v0
	v_mov_b32_e32 v11, v0
	v_mov_b32_e32 v12, v0
	v_mov_b32_e32 v13, v0
	v_mov_b32_e32 v14, v0
	v_mov_b32_e32 v15, v0
	s_waitcnt vmcnt(15)
	ds_write_b128 v167, v[18:21]
	s_waitcnt vmcnt(14)
	ds_write_b128 v167, v[22:25] offset:5120
	s_waitcnt vmcnt(13)
	ds_write_b128 v167, v[26:29] offset:20480
	s_waitcnt vmcnt(12)
	ds_write_b128 v167, v[30:33] offset:25600
	global_load_dwordx4 v[64:67], v[164:165], off offset:256
	global_load_dwordx4 v[68:71], v144, s[4:5] offset:256
	global_load_dwordx4 v[72:75], v[162:163], off offset:256
	global_load_dwordx4 v[76:79], v[160:161], off offset:256
	s_waitcnt lgkmcnt(0)
	s_barrier
	ds_read_b128 v[128:131], v166 offset:2560
	ds_read_b128 v[132:135], v168 offset:23040
	ds_read_b128 v[16:19], v166
	ds_read_b128 v[136:139], v166 offset:32
	ds_read_b128 v[140:143], v168 offset:20480
	ds_read_b128 v[170:173], v168 offset:20512
	s_waitcnt lgkmcnt(1)
	v_mfma_f32_32x32x16_bf16 v[48:63], v[140:143], v[16:19], v[0:15]
	v_mfma_f32_32x32x16_bf16 v[32:47], v[132:135], v[16:19], v[0:15]
	v_mfma_f32_32x32x16_bf16 v[16:31], v[140:143], v[128:131], v[0:15]
	v_mfma_f32_32x32x16_bf16 v[0:15], v[132:135], v[128:131], v[0:15]
	ds_read_b128 v[128:131], v166 offset:2592
	ds_read_b128 v[132:135], v168 offset:23072
	s_waitcnt vmcnt(15)
	ds_write_b128 v167, v[112:115] offset:10240
	s_waitcnt vmcnt(14)
	ds_write_b128 v167, v[116:119] offset:15360
	s_waitcnt vmcnt(13)
	ds_write_b128 v167, v[120:123] offset:30720
	s_waitcnt vmcnt(12)
	ds_write_b128 v167, v[124:127] offset:35840
	global_load_dwordx4 v[112:115], v[160:161], off offset:320
	global_load_dwordx4 v[116:119], v[162:163], off offset:320
	global_load_dwordx4 v[120:123], v144, s[4:5] offset:320
	global_load_dwordx4 v[124:127], v[164:165], off offset:320
	s_waitcnt lgkmcnt(0)
	s_barrier
	v_mfma_f32_32x32x16_bf16 v[32:47], v[132:135], v[136:139], v[32:47]
	v_mfma_f32_32x32x16_bf16 v[16:31], v[170:173], v[128:131], v[16:31]
	v_mfma_f32_32x32x16_bf16 v[0:15], v[132:135], v[128:131], v[0:15]
	v_mfma_f32_32x32x16_bf16 v[48:63], v[170:173], v[136:139], v[48:63]
	ds_read_b128 v[128:131], v166 offset:12800
	ds_read_b128 v[132:135], v168 offset:33280
	ds_read_b128 v[136:139], v166 offset:10240
	ds_read_b128 v[140:143], v166 offset:10272
	ds_read_b128 v[170:173], v168 offset:30720
	ds_read_b128 v[174:177], v168 offset:30752
	s_waitcnt lgkmcnt(3)
	v_mfma_f32_32x32x16_bf16 v[32:47], v[132:135], v[136:139], v[32:47]
	s_waitcnt lgkmcnt(1)
	v_mfma_f32_32x32x16_bf16 v[16:31], v[170:173], v[128:131], v[16:31]
	v_mfma_f32_32x32x16_bf16 v[0:15], v[132:135], v[128:131], v[0:15]
	ds_read_b128 v[128:131], v166 offset:12832
	ds_read_b128 v[132:135], v168 offset:33312
	s_waitcnt vmcnt(15)
	ds_write_b128 v167, v[96:99]
	s_waitcnt vmcnt(14)
	ds_write_b128 v167, v[100:103] offset:5120
	s_waitcnt vmcnt(13)
	ds_write_b128 v167, v[104:107] offset:20480
	s_waitcnt vmcnt(12)
	ds_write_b128 v167, v[108:111] offset:25600
	global_load_dwordx4 v[96:99], v[160:161], off offset:384
	global_load_dwordx4 v[100:103], v[162:163], off offset:384
	global_load_dwordx4 v[104:107], v144, s[4:5] offset:384
	global_load_dwordx4 v[108:111], v[164:165], off offset:384
	s_waitcnt lgkmcnt(0)
	s_barrier
	v_mfma_f32_32x32x16_bf16 v[48:63], v[170:173], v[136:139], v[48:63]
	v_mfma_f32_32x32x16_bf16 v[32:47], v[132:135], v[140:143], v[32:47]
	v_mfma_f32_32x32x16_bf16 v[16:31], v[174:177], v[128:131], v[16:31]
	v_mfma_f32_32x32x16_bf16 v[0:15], v[132:135], v[128:131], v[0:15]
	v_mfma_f32_32x32x16_bf16 v[48:63], v[174:177], v[140:143], v[48:63]
	ds_read_b128 v[128:131], v166 offset:2560
	ds_read_b128 v[132:135], v168 offset:23040
	ds_read_b128 v[136:139], v166
	ds_read_b128 v[140:143], v166 offset:32
	ds_read_b128 v[170:173], v168 offset:20480
	ds_read_b128 v[174:177], v168 offset:20512
	s_waitcnt lgkmcnt(3)
	v_mfma_f32_32x32x16_bf16 v[32:47], v[132:135], v[136:139], v[32:47]
	s_waitcnt lgkmcnt(1)
	v_mfma_f32_32x32x16_bf16 v[16:31], v[170:173], v[128:131], v[16:31]
	v_mfma_f32_32x32x16_bf16 v[0:15], v[132:135], v[128:131], v[0:15]
	ds_read_b128 v[128:131], v166 offset:2592
	ds_read_b128 v[132:135], v168 offset:23072
	s_waitcnt vmcnt(15)
	ds_write_b128 v167, v[80:83] offset:10240
	s_waitcnt vmcnt(14)
	ds_write_b128 v167, v[84:87] offset:15360
	s_waitcnt vmcnt(13)
	ds_write_b128 v167, v[88:91] offset:30720
	s_waitcnt vmcnt(12)
	ds_write_b128 v167, v[92:95] offset:35840
	global_load_dwordx4 v[80:83], v[160:161], off offset:448
	global_load_dwordx4 v[84:87], v[162:163], off offset:448
	global_load_dwordx4 v[88:91], v144, s[4:5] offset:448
	global_load_dwordx4 v[92:95], v[164:165], off offset:448
	s_waitcnt lgkmcnt(0)
	s_barrier
	v_mfma_f32_32x32x16_bf16 v[48:63], v[170:173], v[136:139], v[48:63]
	v_mfma_f32_32x32x16_bf16 v[48:63], v[174:177], v[140:143], v[48:63]
	v_mfma_f32_32x32x16_bf16 v[32:47], v[132:135], v[140:143], v[32:47]
	v_mfma_f32_32x32x16_bf16 v[16:31], v[174:177], v[128:131], v[16:31]
	v_mfma_f32_32x32x16_bf16 v[0:15], v[132:135], v[128:131], v[0:15]
	ds_read_b128 v[128:131], v166 offset:12800
	ds_read_b128 v[132:135], v168 offset:33280
	ds_read_b128 v[136:139], v166 offset:10240
	ds_read_b128 v[140:143], v166 offset:10272
	ds_read_b128 v[170:173], v168 offset:30720
	ds_read_b128 v[174:177], v168 offset:30752
	s_waitcnt lgkmcnt(1)
	v_mfma_f32_32x32x16_bf16 v[48:63], v[170:173], v[136:139], v[48:63]
	v_mfma_f32_32x32x16_bf16 v[32:47], v[132:135], v[136:139], v[32:47]
	v_mfma_f32_32x32x16_bf16 v[16:31], v[170:173], v[128:131], v[16:31]
	v_mfma_f32_32x32x16_bf16 v[0:15], v[132:135], v[128:131], v[0:15]
	ds_read_b128 v[128:131], v166 offset:12832
	ds_read_b128 v[132:135], v168 offset:33312
	s_waitcnt vmcnt(12)
	ds_write_b128 v167, v[76:79]
	ds_write_b128 v167, v[72:75] offset:5120
	ds_write_b128 v167, v[68:71] offset:20480
	ds_write_b128 v167, v[64:67] offset:25600
	global_load_dwordx4 v[64:67], v[160:161], off offset:512
	global_load_dwordx4 v[68:71], v[162:163], off offset:512
	global_load_dwordx4 v[72:75], v144, s[4:5] offset:512
	global_load_dwordx4 v[76:79], v[164:165], off offset:512
	s_waitcnt lgkmcnt(0)
	s_barrier
	v_mfma_f32_32x32x16_bf16 v[48:63], v[174:177], v[140:143], v[48:63]
	v_mfma_f32_32x32x16_bf16 v[32:47], v[132:135], v[140:143], v[32:47]
	v_mfma_f32_32x32x16_bf16 v[16:31], v[174:177], v[128:131], v[16:31]
	v_mfma_f32_32x32x16_bf16 v[0:15], v[132:135], v[128:131], v[0:15]
	ds_read_b128 v[128:131], v166 offset:2560
	ds_read_b128 v[132:135], v168 offset:23040
	ds_read_b128 v[136:139], v166
	ds_read_b128 v[140:143], v166 offset:32
	ds_read_b128 v[170:173], v168 offset:20480
	ds_read_b128 v[174:177], v168 offset:20512
	s_waitcnt lgkmcnt(1)
	v_mfma_f32_32x32x16_bf16 v[48:63], v[170:173], v[136:139], v[48:63]
	v_mfma_f32_32x32x16_bf16 v[32:47], v[132:135], v[136:139], v[32:47]
	v_mfma_f32_32x32x16_bf16 v[16:31], v[170:173], v[128:131], v[16:31]
	v_mfma_f32_32x32x16_bf16 v[0:15], v[132:135], v[128:131], v[0:15]
	ds_read_b128 v[128:131], v166 offset:2592
	ds_read_b128 v[132:135], v168 offset:23072
	s_waitcnt vmcnt(15)
	ds_write_b128 v167, v[112:115] offset:10240
	s_waitcnt vmcnt(14)
	ds_write_b128 v167, v[116:119] offset:15360
	s_waitcnt vmcnt(13)
	ds_write_b128 v167, v[120:123] offset:30720
	s_waitcnt vmcnt(12)
	ds_write_b128 v167, v[124:127] offset:35840
	global_load_dwordx4 v[112:115], v[160:161], off offset:576
	global_load_dwordx4 v[116:119], v[162:163], off offset:576
	global_load_dwordx4 v[120:123], v144, s[4:5] offset:576
	global_load_dwordx4 v[124:127], v[164:165], off offset:576
	s_waitcnt lgkmcnt(0)
	s_barrier
	v_mfma_f32_32x32x16_bf16 v[48:63], v[174:177], v[140:143], v[48:63]
	v_mfma_f32_32x32x16_bf16 v[32:47], v[132:135], v[140:143], v[32:47]
	v_mfma_f32_32x32x16_bf16 v[16:31], v[174:177], v[128:131], v[16:31]
	v_mfma_f32_32x32x16_bf16 v[0:15], v[132:135], v[128:131], v[0:15]
	ds_read_b128 v[128:131], v166 offset:12800
	ds_read_b128 v[132:135], v168 offset:33280
	ds_read_b128 v[136:139], v166 offset:10240
	ds_read_b128 v[140:143], v166 offset:10272
	ds_read_b128 v[170:173], v168 offset:30720
	ds_read_b128 v[174:177], v168 offset:30752
	s_waitcnt lgkmcnt(1)
	v_mfma_f32_32x32x16_bf16 v[48:63], v[170:173], v[136:139], v[48:63]
	v_mfma_f32_32x32x16_bf16 v[32:47], v[132:135], v[136:139], v[32:47]
	v_mfma_f32_32x32x16_bf16 v[16:31], v[170:173], v[128:131], v[16:31]
	v_mfma_f32_32x32x16_bf16 v[0:15], v[132:135], v[128:131], v[0:15]
	ds_read_b128 v[128:131], v166 offset:12832
	ds_read_b128 v[132:135], v168 offset:33312
	s_waitcnt vmcnt(15)
	ds_write_b128 v167, v[96:99]
	s_waitcnt vmcnt(14)
	ds_write_b128 v167, v[100:103] offset:5120
	s_waitcnt vmcnt(13)
	ds_write_b128 v167, v[104:107] offset:20480
	s_waitcnt vmcnt(12)
	ds_write_b128 v167, v[108:111] offset:25600
	s_waitcnt lgkmcnt(6)
	v_mfma_f32_32x32x16_bf16 v[48:63], v[174:177], v[140:143], v[48:63]
	s_waitcnt lgkmcnt(4)
	v_mfma_f32_32x32x16_bf16 v[32:47], v[132:135], v[140:143], v[32:47]
	v_mfma_f32_32x32x16_bf16 v[16:31], v[174:177], v[128:131], v[16:31]
	v_mfma_f32_32x32x16_bf16 v[0:15], v[132:135], v[128:131], v[0:15]
	global_load_dwordx4 v[128:131], v[160:161], off offset:640
	global_load_dwordx4 v[132:135], v[162:163], off offset:640
	global_load_dwordx4 v[136:139], v144, s[4:5] offset:640
	global_load_dwordx4 v[140:143], v[164:165], off offset:640
	s_waitcnt lgkmcnt(0)
	s_barrier
	ds_read_b128 v[96:99], v166 offset:2560
	ds_read_b128 v[100:103], v168 offset:23040
	ds_read_b128 v[104:107], v166
	ds_read_b128 v[108:111], v166 offset:32
	ds_read_b128 v[170:173], v168 offset:20480
	ds_read_b128 v[174:177], v168 offset:20512
	s_waitcnt lgkmcnt(3)
	v_mfma_f32_32x32x16_bf16 v[32:47], v[100:103], v[104:107], v[32:47]
	s_waitcnt lgkmcnt(1)
	v_mfma_f32_32x32x16_bf16 v[16:31], v[170:173], v[96:99], v[16:31]
	v_mfma_f32_32x32x16_bf16 v[0:15], v[100:103], v[96:99], v[0:15]
	ds_read_b128 v[96:99], v166 offset:2592
	ds_read_b128 v[100:103], v168 offset:23072
	s_waitcnt vmcnt(15)
	ds_write_b128 v167, v[80:83] offset:10240
	s_waitcnt vmcnt(14)
	ds_write_b128 v167, v[84:87] offset:15360
	s_waitcnt vmcnt(13)
	ds_write_b128 v167, v[88:91] offset:30720
	s_waitcnt vmcnt(12)
	ds_write_b128 v167, v[92:95] offset:35840
	global_load_dwordx4 v[80:83], v[160:161], off offset:704
	global_load_dwordx4 v[84:87], v[162:163], off offset:704
	global_load_dwordx4 v[88:91], v144, s[4:5] offset:704
	global_load_dwordx4 v[92:95], v[164:165], off offset:704
	s_waitcnt lgkmcnt(0)
	s_barrier
	v_mfma_f32_32x32x16_bf16 v[48:63], v[170:173], v[104:107], v[48:63]
	v_mfma_f32_32x32x16_bf16 v[48:63], v[174:177], v[108:111], v[48:63]
	v_mfma_f32_32x32x16_bf16 v[32:47], v[100:103], v[108:111], v[32:47]
	v_mfma_f32_32x32x16_bf16 v[16:31], v[174:177], v[96:99], v[16:31]
	v_mfma_f32_32x32x16_bf16 v[0:15], v[100:103], v[96:99], v[0:15]
	ds_read_b128 v[96:99], v166 offset:12800
	ds_read_b128 v[100:103], v168 offset:33280
	ds_read_b128 v[104:107], v166 offset:10240
	ds_read_b128 v[108:111], v166 offset:10272
	ds_read_b128 v[170:173], v168 offset:30720
	ds_read_b128 v[174:177], v168 offset:30752
	s_waitcnt lgkmcnt(1)
	v_mfma_f32_32x32x16_bf16 v[48:63], v[170:173], v[104:107], v[48:63]
	v_mfma_f32_32x32x16_bf16 v[32:47], v[100:103], v[104:107], v[32:47]
	v_mfma_f32_32x32x16_bf16 v[16:31], v[170:173], v[96:99], v[16:31]
	v_mfma_f32_32x32x16_bf16 v[0:15], v[100:103], v[96:99], v[0:15]
	ds_read_b128 v[96:99], v166 offset:12832
	ds_read_b128 v[100:103], v168 offset:33312
	s_waitcnt vmcnt(15)
	ds_write_b128 v167, v[64:67]
	s_waitcnt vmcnt(14)
	ds_write_b128 v167, v[68:71] offset:5120
	s_waitcnt vmcnt(13)
	ds_write_b128 v167, v[72:75] offset:20480
	s_waitcnt vmcnt(12)
	ds_write_b128 v167, v[76:79] offset:25600
	global_load_dwordx4 v[64:67], v[160:161], off offset:768
	global_load_dwordx4 v[68:71], v[162:163], off offset:768
	global_load_dwordx4 v[72:75], v144, s[4:5] offset:768
	global_load_dwordx4 v[76:79], v[164:165], off offset:768
	s_waitcnt lgkmcnt(0)
	s_barrier
	v_mfma_f32_32x32x16_bf16 v[48:63], v[174:177], v[108:111], v[48:63]
	v_mfma_f32_32x32x16_bf16 v[32:47], v[100:103], v[108:111], v[32:47]
	v_mfma_f32_32x32x16_bf16 v[16:31], v[174:177], v[96:99], v[16:31]
	v_mfma_f32_32x32x16_bf16 v[0:15], v[100:103], v[96:99], v[0:15]
	ds_read_b128 v[96:99], v166 offset:2560
	ds_read_b128 v[100:103], v168 offset:23040
	ds_read_b128 v[104:107], v166
	ds_read_b128 v[108:111], v166 offset:32
	ds_read_b128 v[170:173], v168 offset:20480
	ds_read_b128 v[174:177], v168 offset:20512
	s_waitcnt lgkmcnt(1)
	v_mfma_f32_32x32x16_bf16 v[48:63], v[170:173], v[104:107], v[48:63]
	v_mfma_f32_32x32x16_bf16 v[32:47], v[100:103], v[104:107], v[32:47]
	v_mfma_f32_32x32x16_bf16 v[16:31], v[170:173], v[96:99], v[16:31]
	v_mfma_f32_32x32x16_bf16 v[0:15], v[100:103], v[96:99], v[0:15]
	ds_read_b128 v[96:99], v166 offset:2592
	ds_read_b128 v[100:103], v168 offset:23072
	s_waitcnt vmcnt(15)
	ds_write_b128 v167, v[112:115] offset:10240
	s_waitcnt vmcnt(14)
	ds_write_b128 v167, v[116:119] offset:15360
	s_waitcnt vmcnt(13)
	ds_write_b128 v167, v[120:123] offset:30720
	s_waitcnt vmcnt(12)
	ds_write_b128 v167, v[124:127] offset:35840
	s_waitcnt lgkmcnt(6)
	v_mfma_f32_32x32x16_bf16 v[48:63], v[174:177], v[108:111], v[48:63]
	s_waitcnt lgkmcnt(4)
	v_mfma_f32_32x32x16_bf16 v[32:47], v[100:103], v[108:111], v[32:47]
	v_mfma_f32_32x32x16_bf16 v[16:31], v[174:177], v[96:99], v[16:31]
	v_mfma_f32_32x32x16_bf16 v[0:15], v[100:103], v[96:99], v[0:15]
	global_load_dwordx4 v[96:99], v[160:161], off offset:832
	global_load_dwordx4 v[100:103], v[162:163], off offset:832
	global_load_dwordx4 v[104:107], v144, s[4:5] offset:832
	global_load_dwordx4 v[108:111], v[164:165], off offset:832
	s_waitcnt lgkmcnt(0)
	s_barrier
	ds_read_b128 v[112:115], v166 offset:12800
	ds_read_b128 v[116:119], v168 offset:33280
	ds_read_b128 v[120:123], v166 offset:10240
	ds_read_b128 v[124:127], v166 offset:10272
	ds_read_b128 v[170:173], v168 offset:30720
	ds_read_b128 v[174:177], v168 offset:30752
	s_waitcnt lgkmcnt(1)
	v_mfma_f32_32x32x16_bf16 v[48:63], v[170:173], v[120:123], v[48:63]
	v_mfma_f32_32x32x16_bf16 v[32:47], v[116:119], v[120:123], v[32:47]
	v_mfma_f32_32x32x16_bf16 v[16:31], v[170:173], v[112:115], v[16:31]
	v_mfma_f32_32x32x16_bf16 v[0:15], v[116:119], v[112:115], v[0:15]
	ds_read_b128 v[112:115], v166 offset:12832
	ds_read_b128 v[116:119], v168 offset:33312
	s_waitcnt vmcnt(15)
	ds_write_b128 v167, v[128:131]
	s_waitcnt vmcnt(14)
	ds_write_b128 v167, v[132:135] offset:5120
	s_waitcnt vmcnt(13)
	ds_write_b128 v167, v[136:139] offset:20480
	s_waitcnt vmcnt(12)
	ds_write_b128 v167, v[140:143] offset:25600
	s_waitcnt lgkmcnt(6)
	v_mfma_f32_32x32x16_bf16 v[48:63], v[174:177], v[124:127], v[48:63]
	s_waitcnt lgkmcnt(4)
	v_mfma_f32_32x32x16_bf16 v[32:47], v[116:119], v[124:127], v[32:47]
	v_mfma_f32_32x32x16_bf16 v[16:31], v[174:177], v[112:115], v[16:31]
	v_mfma_f32_32x32x16_bf16 v[0:15], v[116:119], v[112:115], v[0:15]
	global_load_dwordx4 v[112:115], v[160:161], off offset:896
	global_load_dwordx4 v[116:119], v[162:163], off offset:896
	global_load_dwordx4 v[120:123], v144, s[4:5] offset:896
	global_load_dwordx4 v[124:127], v[164:165], off offset:896
	s_waitcnt lgkmcnt(0)
	s_barrier
	ds_read_b128 v[128:131], v166 offset:2560
	ds_read_b128 v[132:135], v168 offset:23040
	ds_read_b128 v[136:139], v166
	ds_read_b128 v[140:143], v166 offset:32
	ds_read_b128 v[170:173], v168 offset:20480
	ds_read_b128 v[174:177], v168 offset:20512
	s_waitcnt lgkmcnt(3)
	v_mfma_f32_32x32x16_bf16 v[32:47], v[132:135], v[136:139], v[32:47]
	s_waitcnt lgkmcnt(1)
	v_mfma_f32_32x32x16_bf16 v[16:31], v[170:173], v[128:131], v[16:31]
	v_mfma_f32_32x32x16_bf16 v[0:15], v[132:135], v[128:131], v[0:15]
	ds_read_b128 v[128:131], v166 offset:2592
	ds_read_b128 v[132:135], v168 offset:23072
	s_waitcnt vmcnt(15)
	ds_write_b128 v167, v[80:83] offset:10240
	s_waitcnt vmcnt(14)
	ds_write_b128 v167, v[84:87] offset:15360
	s_waitcnt vmcnt(13)
	ds_write_b128 v167, v[88:91] offset:30720
	s_waitcnt vmcnt(12)
	ds_write_b128 v167, v[92:95] offset:35840
	global_load_dwordx4 v[80:83], v[160:161], off offset:960
	global_load_dwordx4 v[84:87], v[162:163], off offset:960
	global_load_dwordx4 v[88:91], v144, s[4:5] offset:960
	global_load_dwordx4 v[92:95], v[164:165], off offset:960
	s_waitcnt lgkmcnt(0)
	s_barrier
	s_add_u32 s4, s4, 0x20000
	v_mfma_f32_32x32x16_bf16 v[48:63], v[170:173], v[136:139], v[48:63]
	s_addc_u32 s5, s5, 0
	v_mfma_f32_32x32x16_bf16 v[16:31], v[174:177], v[128:131], v[16:31]
	v_mfma_f32_32x32x16_bf16 v[0:15], v[132:135], v[128:131], v[0:15]
	v_mfma_f32_32x32x16_bf16 v[32:47], v[132:135], v[140:143], v[32:47]
	v_mfma_f32_32x32x16_bf16 v[48:63], v[174:177], v[140:143], v[48:63]
	ds_read_b128 v[128:131], v166 offset:12800
	ds_read_b128 v[132:135], v168 offset:33280
	ds_read_b128 v[136:139], v166 offset:10240
	ds_read_b128 v[140:143], v166 offset:10272
	ds_read_b128 v[160:163], v168 offset:30720
	ds_read_b128 v[170:173], v168 offset:30752
	s_waitcnt lgkmcnt(1)
	v_mfma_f32_32x32x16_bf16 v[16:31], v[160:163], v[128:131], v[16:31]
	v_mfma_f32_32x32x16_bf16 v[0:15], v[132:135], v[128:131], v[0:15]
	v_mfma_f32_32x32x16_bf16 v[32:47], v[132:135], v[136:139], v[32:47]
	ds_read_b128 v[128:131], v166 offset:12832
	ds_read_b128 v[132:135], v168 offset:33312
	s_waitcnt vmcnt(15)
	ds_write_b128 v167, v[64:67]
	s_waitcnt vmcnt(14)
	ds_write_b128 v167, v[68:71] offset:5120
	s_waitcnt vmcnt(13)
	ds_write_b128 v167, v[72:75] offset:20480
	s_waitcnt vmcnt(12)
	ds_write_b128 v167, v[76:79] offset:25600
	s_waitcnt lgkmcnt(0)
	s_barrier
	v_mfma_f32_32x32x16_bf16 v[48:63], v[160:163], v[136:139], v[48:63]
	v_mfma_f32_32x32x16_bf16 v[16:31], v[170:173], v[128:131], v[16:31]
	v_mfma_f32_32x32x16_bf16 v[0:15], v[132:135], v[128:131], v[0:15]
	v_mfma_f32_32x32x16_bf16 v[32:47], v[132:135], v[140:143], v[32:47]
	ds_read_b128 v[64:67], v166 offset:2560
	ds_read_b128 v[68:71], v168 offset:23040
	ds_read_b128 v[72:75], v166
	ds_read_b128 v[76:79], v166 offset:32
	ds_read_b128 v[128:131], v168 offset:20480
	ds_read_b128 v[132:135], v168 offset:20512
	v_mfma_f32_32x32x16_bf16 v[48:63], v[170:173], v[140:143], v[48:63]
	s_waitcnt lgkmcnt(1)
	v_mfma_f32_32x32x16_bf16 v[16:31], v[128:131], v[64:67], v[16:31]
	v_mfma_f32_32x32x16_bf16 v[0:15], v[68:71], v[64:67], v[0:15]
	v_mfma_f32_32x32x16_bf16 v[32:47], v[68:71], v[72:75], v[32:47]
	ds_read_b128 v[64:67], v166 offset:2592
	ds_read_b128 v[68:71], v168 offset:23072
	s_waitcnt vmcnt(11)
	ds_write_b128 v167, v[96:99] offset:10240
	s_waitcnt vmcnt(10)
	ds_write_b128 v167, v[100:103] offset:15360
	s_waitcnt vmcnt(9)
	ds_write_b128 v167, v[104:107] offset:30720
	s_waitcnt vmcnt(8)
	ds_write_b128 v167, v[108:111] offset:35840
	s_waitcnt lgkmcnt(0)
	s_barrier
	v_mfma_f32_32x32x16_bf16 v[48:63], v[128:131], v[72:75], v[48:63]
	v_mfma_f32_32x32x16_bf16 v[16:31], v[132:135], v[64:67], v[16:31]
	v_mfma_f32_32x32x16_bf16 v[0:15], v[68:71], v[64:67], v[0:15]
	v_mfma_f32_32x32x16_bf16 v[32:47], v[68:71], v[76:79], v[32:47]
	v_mfma_f32_32x32x16_bf16 v[48:63], v[132:135], v[76:79], v[48:63]
	ds_read_b128 v[64:67], v166 offset:12800
	ds_read_b128 v[68:71], v168 offset:33280
	ds_read_b128 v[72:75], v166 offset:10240
	ds_read_b128 v[76:79], v166 offset:10272
	ds_read_b128 v[96:99], v168 offset:30720
	ds_read_b128 v[100:103], v168 offset:30752
	s_waitcnt lgkmcnt(1)
	v_mfma_f32_32x32x16_bf16 v[16:31], v[96:99], v[64:67], v[16:31]
	v_mfma_f32_32x32x16_bf16 v[0:15], v[68:71], v[64:67], v[0:15]
	v_mfma_f32_32x32x16_bf16 v[32:47], v[68:71], v[72:75], v[32:47]
	ds_read_b128 v[64:67], v166 offset:12832
	ds_read_b128 v[68:71], v168 offset:33312
	s_waitcnt vmcnt(7)
	ds_write_b128 v167, v[112:115]
	s_waitcnt vmcnt(6)
	ds_write_b128 v167, v[116:119] offset:5120
	s_waitcnt vmcnt(5)
	ds_write_b128 v167, v[120:123] offset:20480
	s_waitcnt vmcnt(4)
	ds_write_b128 v167, v[124:127] offset:25600
	s_waitcnt lgkmcnt(0)
	s_barrier
	v_mfma_f32_32x32x16_bf16 v[48:63], v[96:99], v[72:75], v[48:63]
	v_mfma_f32_32x32x16_bf16 v[16:31], v[100:103], v[64:67], v[16:31]
	v_mfma_f32_32x32x16_bf16 v[0:15], v[68:71], v[64:67], v[0:15]
	v_mfma_f32_32x32x16_bf16 v[32:47], v[68:71], v[76:79], v[32:47]
	v_mfma_f32_32x32x16_bf16 v[48:63], v[100:103], v[76:79], v[48:63]
	ds_read_b128 v[64:67], v166 offset:2560
	ds_read_b128 v[68:71], v168 offset:23040
	ds_read_b128 v[72:75], v166
	ds_read_b128 v[76:79], v166 offset:32
	ds_read_b128 v[96:99], v168 offset:20480
	ds_read_b128 v[100:103], v168 offset:20512
	s_waitcnt lgkmcnt(1)
	v_mfma_f32_32x32x16_bf16 v[16:31], v[96:99], v[64:67], v[16:31]
	v_mfma_f32_32x32x16_bf16 v[0:15], v[68:71], v[64:67], v[0:15]
	v_mfma_f32_32x32x16_bf16 v[32:47], v[68:71], v[72:75], v[32:47]
	ds_read_b128 v[64:67], v166 offset:2592
	ds_read_b128 v[68:71], v168 offset:23072
	s_waitcnt vmcnt(3)
	ds_write_b128 v167, v[80:83] offset:10240
	s_waitcnt vmcnt(2)
	ds_write_b128 v167, v[84:87] offset:15360
	s_waitcnt vmcnt(1)
	ds_write_b128 v167, v[88:91] offset:30720
	s_waitcnt vmcnt(0)
	ds_write_b128 v167, v[92:95] offset:35840
	s_waitcnt lgkmcnt(0)
	s_barrier
; __device__ __forceinline__ float bflo(unsigned u) { return __uint_as_float(u << 16); }
; __device__ __forceinline__ float bfhi(unsigned u) { return __uint_as_float(u & 0xFFFF0000u); }
; __device__ __forceinline__ float sigmoidf_(float x) { return __builtin_amdgcn_rcpf(1.f + __expf(-x)); }
; __device__ __forceinline__ float siluf_(float x) { return x * __builtin_amdgcn_rcpf(1.f + __expf(-x)); }
; __device__ __forceinline__ void s5_pass2(const Params& p, int layer, int task, char* sm) {
;     ...
; #pragma unroll
;     for (int i = 0; i < 2; i++) {
;       const size_t tok = tok0 + wr * 64 + i * 32 + r32;
; #pragma unroll
;       for (int j = 0; j < 2; j++)
; #pragma unroll
;         for (int q = 0; q < 4; q++) {
;           const int n = tn * 128 + wc * 64 + j * 32 + q * 8 + h5 * 4;
;           float4 bg = *(const float4*)(p.b_glu + layer * 512 + n);
;           uint2 yy = *(const uint2*)(p.YG + tok * 512 + n);
;           uint2 zz = *(const uint2*)(p.P + tok * PW + C_S5Z + n);
;           float o0 = bflo(yy.x) * sigmoidf_(acc[i][j][4 * q] + bg.x) * siluf_(bflo(zz.x));
;           float o1 = bfhi(yy.x) * sigmoidf_(acc[i][j][4 * q + 1] + bg.y) * siluf_(bfhi(zz.x));
;           float o2 = bflo(yy.y) * sigmoidf_(acc[i][j][4 * q + 2] + bg.z) * siluf_(bflo(zz.y));
;           float o3 = bfhi(yy.y) * sigmoidf_(acc[i][j][4 * q + 3] + bg.w) * siluf_(bfhi(zz.y));
;           *(uint2*)(p.Y + tok * YW + Y_S5 + n) = make_uint2(pk2(o0, o1), pk2(o2, o3));
;         }
	v_mfma_f32_32x32x16_bf16 v[48:63], v[96:99], v[72:75], v[48:63]
	v_mfma_f32_32x32x16_bf16 v[16:31], v[100:103], v[64:67], v[16:31]
	v_mfma_f32_32x32x16_bf16 v[0:15], v[68:71], v[64:67], v[0:15]
	v_mfma_f32_32x32x16_bf16 v[32:47], v[68:71], v[76:79], v[32:47]
	v_mfma_f32_32x32x16_bf16 v[48:63], v[100:103], v[76:79], v[48:63]
	ds_read_b128 v[64:67], v166 offset:12800
	ds_read_b128 v[68:71], v168 offset:33280
	ds_read_b128 v[72:75], v166 offset:10240
	ds_read_b128 v[76:79], v166 offset:10272
	ds_read_b128 v[80:83], v168 offset:30720
	ds_read_b128 v[84:87], v168 offset:30752
	s_waitcnt lgkmcnt(1)
	v_mfma_f32_32x32x16_bf16 v[16:31], v[80:83], v[64:67], v[16:31]
	v_mfma_f32_32x32x16_bf16 v[0:15], v[68:71], v[64:67], v[0:15]
	v_mfma_f32_32x32x16_bf16 v[32:47], v[68:71], v[72:75], v[32:47]
	ds_read_b128 v[64:67], v166 offset:12832
	ds_read_b128 v[68:71], v168 offset:33312
	s_waitcnt lgkmcnt(0)
	s_barrier
	v_mfma_f32_32x32x16_bf16 v[16:31], v[84:87], v[64:67], v[16:31]
	v_mfma_f32_32x32x16_bf16 v[0:15], v[68:71], v[64:67], v[0:15]
	v_lshl_add_u64 v[66:67], v[152:153], 0, s[2:3]
	v_lshl_add_u64 v[64:65], v[156:157], 0, s[2:3]
	v_mfma_f32_32x32x16_bf16 v[48:63], v[80:83], v[72:75], v[48:63]
	v_lshl_add_u64 v[160:161], v[156:157], 0, s[2:3]
	v_lshl_add_u64 v[162:163], v[152:153], 0, s[2:3]
	v_lshl_add_u64 v[164:165], v[148:149], 0, s[2:3]
	v_lshl_add_u64 v[166:167], v[150:151], 0, s[2:3]
	global_load_dwordx4 v[88:91], v[158:159], off offset:-128
	global_load_dwordx2 v[92:93], v[160:161], off
	global_load_dwordx2 v[94:95], v[162:163], off offset:1024
	global_load_dwordx4 v[96:99], v[158:159], off offset:-96
	global_load_dwordx2 v[100:101], v[160:161], off offset:16
	global_load_dwordx2 v[102:103], v[162:163], off offset:1040
	global_load_dwordx4 v[104:107], v[158:159], off offset:-64
	global_load_dwordx2 v[108:109], v[160:161], off offset:32
	global_load_dwordx2 v[110:111], v[162:163], off offset:1056
	global_load_dwordx4 v[112:115], v[158:159], off offset:-32
	global_load_dwordx2 v[116:117], v[160:161], off offset:48
	global_load_dwordx2 v[118:119], v[162:163], off offset:1072
	global_load_dwordx4 v[120:123], v[158:159], off
	global_load_dwordx2 v[124:125], v[160:161], off offset:64
	global_load_dwordx2 v[126:127], v[162:163], off offset:1088
	global_load_dwordx4 v[128:131], v[158:159], off offset:32
	global_load_dwordx2 v[132:133], v[160:161], off offset:80
	global_load_dwordx2 v[134:135], v[162:163], off offset:1104
	global_load_dwordx4 v[136:139], v[158:159], off offset:64
	global_load_dwordx2 v[140:141], v[160:161], off offset:96
	global_load_dwordx2 v[142:143], v[162:163], off offset:1120
	global_load_dwordx4 v[170:173], v[158:159], off offset:96
	global_load_dwordx2 v[174:175], v[160:161], off offset:112
	global_load_dwordx2 v[176:177], v[162:163], off offset:1136
	v_mfma_f32_32x32x16_bf16 v[32:47], v[68:71], v[76:79], v[32:47]
	v_mfma_f32_32x32x16_bf16 v[48:63], v[84:87], v[76:79], v[48:63]
	s_waitcnt vmcnt(21)
	v_lshlrev_b32_e32 v76, 16, v92
	v_and_b32_e32 v77, 0xffff0000, v92
	s_nop 7
	v_add_f32_e32 v48, v48, v88
	v_lshlrev_b32_e32 v68, 16, v94
	v_mul_f32_e32 v72, 0xbfb8aa3b, v68
	v_exp_f32_e32 v72, v72
	v_add_f32_e32 v49, v49, v89
	v_and_b32_e32 v69, 0xffff0000, v94
	v_mul_f32_e32 v48, 0xbfb8aa3b, v48
	v_add_f32_e32 v72, 1.0, v72
	v_mul_f32_e32 v49, 0xbfb8aa3b, v49
	v_rcp_f32_e32 v78, v72
	v_mul_f32_e32 v72, 0xbfb8aa3b, v69
	v_exp_f32_e32 v48, v48
	v_exp_f32_e32 v49, v49
	v_exp_f32_e32 v72, v72
	v_add_f32_e32 v50, v50, v90
	v_add_f32_e32 v51, v51, v91
	v_mul_f32_e32 v50, 0xbfb8aa3b, v50
	v_mul_f32_e32 v51, 0xbfb8aa3b, v51
	v_exp_f32_e32 v50, v50
	v_exp_f32_e32 v51, v51
	v_add_f32_e32 v48, 1.0, v48
	v_add_f32_e32 v49, 1.0, v49
	v_add_f32_e32 v72, 1.0, v72
	v_rcp_f32_e32 v48, v48
	v_rcp_f32_e32 v49, v49
	v_rcp_f32_e32 v79, v72
	v_add_f32_e32 v50, 1.0, v50
	v_add_f32_e32 v51, 1.0, v51
	v_rcp_f32_e32 v50, v50
	v_rcp_f32_e32 v51, v51
	v_pk_mul_f32 v[48:49], v[48:49], v[76:77]
	v_pk_mul_f32 v[68:69], v[78:79], v[68:69]
	v_lshlrev_b32_e32 v70, 16, v95
	v_pk_mul_f32 v[48:49], v[48:49], v[68:69]
	v_lshlrev_b32_e32 v68, 16, v93
	v_and_b32_e32 v69, 0xffff0000, v93
	v_and_b32_e32 v71, 0xffff0000, v95
	v_mul_f32_e32 v72, 0xbfb8aa3b, v70
	v_pk_mul_f32 v[50:51], v[50:51], v[68:69]
	v_mul_f32_e32 v68, 0xbfb8aa3b, v71
	v_exp_f32_e32 v72, v72
	v_exp_f32_e32 v68, v68
	v_add_f32_e32 v72, 1.0, v72
	v_add_f32_e32 v68, 1.0, v68
	v_rcp_f32_e32 v72, v72
	v_rcp_f32_e32 v73, v68
	s_nop 0
	v_pk_mul_f32 v[68:69], v[72:73], v[70:71]
	s_nop 0
	v_pk_mul_f32 v[50:51], v[50:51], v[68:69]
	v_cvt_pk_bf16_f32 v68, v48, v49
	v_cvt_pk_bf16_f32 v69, v50, v51
	v_lshl_add_u64 v[48:49], v[154:155], 0, s[2:3]
	global_store_dwordx2 v[48:49], v[68:69], off
	global_load_dwordx4 v[88:91], v[158:159], off offset:-128
	global_load_dwordx2 v[92:93], v[164:165], off
	global_load_dwordx2 v[94:95], v[166:167], off offset:1024
	s_nop 0
	s_waitcnt vmcnt(22)
; __device__ __forceinline__ float bflo(unsigned u) { return __uint_as_float(u << 16); }
; __device__ __forceinline__ float bfhi(unsigned u) { return __uint_as_float(u & 0xFFFF0000u); }
; __device__ __forceinline__ float sigmoidf_(float x) { return __builtin_amdgcn_rcpf(1.f + __expf(-x)); }
; __device__ __forceinline__ float siluf_(float x) { return x * __builtin_amdgcn_rcpf(1.f + __expf(-x)); }
; __device__ __forceinline__ void s5_pass2(const Params& p, int layer, int task, char* sm) {
;     ...
; #pragma unroll
;     for (int i = 0; i < 2; i++) {
;       const size_t tok = tok0 + wr * 64 + i * 32 + r32;
; #pragma unroll
;       for (int j = 0; j < 2; j++)
; #pragma unroll
;         for (int q = 0; q < 4; q++) {
;           const int n = tn * 128 + wc * 64 + j * 32 + q * 8 + h5 * 4;
;           float4 bg = *(const float4*)(p.b_glu + layer * 512 + n);
;           uint2 yy = *(const uint2*)(p.YG + tok * 512 + n);
;           uint2 zz = *(const uint2*)(p.P + tok * PW + C_S5Z + n);
;           float o0 = bflo(yy.x) * sigmoidf_(acc[i][j][4 * q] + bg.x) * siluf_(bflo(zz.x));
;           float o1 = bfhi(yy.x) * sigmoidf_(acc[i][j][4 * q + 1] + bg.y) * siluf_(bfhi(zz.x));
;           float o2 = bflo(yy.y) * sigmoidf_(acc[i][j][4 * q + 2] + bg.z) * siluf_(bflo(zz.y));
;           float o3 = bfhi(yy.y) * sigmoidf_(acc[i][j][4 * q + 3] + bg.w) * siluf_(bfhi(zz.y));
;           *(uint2*)(p.Y + tok * YW + Y_S5 + n) = make_uint2(pk2(o0, o1), pk2(o2, o3));
;         }
	v_add_f32_e32 v52, v52, v96
	v_lshlrev_b32_e32 v74, 16, v100
	v_and_b32_e32 v75, 0xffff0000, v100
	v_add_f32_e32 v50, v53, v97
	v_mul_f32_e32 v50, 0xbfb8aa3b, v50
	v_exp_f32_e32 v50, v50
	v_lshlrev_b32_e32 v68, 16, v102
	v_and_b32_e32 v69, 0xffff0000, v102
	v_mul_f32_e32 v52, 0xbfb8aa3b, v52
	v_add_f32_e32 v50, 1.0, v50
	v_rcp_f32_e32 v53, v50
	v_mul_f32_e32 v50, 0xbfb8aa3b, v68
	v_exp_f32_e32 v50, v50
	v_exp_f32_e32 v52, v52
	v_add_f32_e32 v54, v54, v98
	v_add_f32_e32 v55, v55, v99
	v_add_f32_e32 v50, 1.0, v50
	v_rcp_f32_e32 v76, v50
	v_mul_f32_e32 v50, 0xbfb8aa3b, v69
	v_exp_f32_e32 v50, v50
	v_mul_f32_e32 v54, 0xbfb8aa3b, v54
	v_mul_f32_e32 v55, 0xbfb8aa3b, v55
	v_exp_f32_e32 v54, v54
	v_exp_f32_e32 v55, v55
	v_add_f32_e32 v52, 1.0, v52
	v_add_f32_e32 v50, 1.0, v50
	v_rcp_f32_e32 v52, v52
	v_rcp_f32_e32 v77, v50
	v_add_f32_e32 v54, 1.0, v54
	v_add_f32_e32 v55, 1.0, v55
	v_rcp_f32_e32 v54, v54
	v_rcp_f32_e32 v55, v55
	v_pk_mul_f32 v[52:53], v[52:53], v[74:75]
	v_pk_mul_f32 v[68:69], v[76:77], v[68:69]
	v_lshlrev_b32_e32 v50, 16, v101
	v_pk_mul_f32 v[52:53], v[52:53], v[68:69]
	v_lshlrev_b32_e32 v68, 16, v103
	v_and_b32_e32 v51, 0xffff0000, v101
	v_and_b32_e32 v69, 0xffff0000, v103
	v_mul_f32_e32 v70, 0xbfb8aa3b, v68
	v_pk_mul_f32 v[50:51], v[54:55], v[50:51]
	v_mul_f32_e32 v54, 0xbfb8aa3b, v69
	v_exp_f32_e32 v70, v70
	v_exp_f32_e32 v54, v54
	v_cvt_pk_bf16_f32 v52, v52, v53
	v_add_f32_e32 v70, 1.0, v70
	v_add_f32_e32 v54, 1.0, v54
	v_rcp_f32_e32 v70, v70
	v_rcp_f32_e32 v71, v54
	s_nop 0
	v_pk_mul_f32 v[54:55], v[70:71], v[68:69]
	s_nop 0
	v_pk_mul_f32 v[50:51], v[50:51], v[54:55]
	s_nop 0
	v_cvt_pk_bf16_f32 v53, v50, v51
	global_store_dwordx2 v[48:49], v[52:53], off offset:16
	global_load_dwordx4 v[96:99], v[158:159], off offset:-96
	global_load_dwordx2 v[100:101], v[164:165], off offset:16
	global_load_dwordx2 v[102:103], v[166:167], off offset:1040
	s_nop 0
	s_waitcnt vmcnt(23)
	v_add_f32_e32 v50, v56, v104
	v_lshlrev_b32_e32 v70, 16, v108
	v_lshlrev_b32_e32 v56, 16, v110
	v_and_b32_e32 v71, 0xffff0000, v108
	v_mul_f32_e32 v54, 0xbfb8aa3b, v56
	v_exp_f32_e32 v54, v54
	v_add_f32_e32 v51, v57, v105
	v_and_b32_e32 v57, 0xffff0000, v110
	v_mul_f32_e32 v50, 0xbfb8aa3b, v50
	v_add_f32_e32 v54, 1.0, v54
	v_mul_f32_e32 v51, 0xbfb8aa3b, v51
	v_rcp_f32_e32 v72, v54
	v_mul_f32_e32 v54, 0xbfb8aa3b, v57
	v_exp_f32_e32 v50, v50
	v_exp_f32_e32 v51, v51
	v_exp_f32_e32 v54, v54
	v_add_f32_e32 v52, v58, v106
	v_add_f32_e32 v53, v59, v107
	v_mul_f32_e32 v52, 0xbfb8aa3b, v52
	v_mul_f32_e32 v53, 0xbfb8aa3b, v53
	v_exp_f32_e32 v52, v52
	v_exp_f32_e32 v53, v53
	v_add_f32_e32 v50, 1.0, v50
	v_add_f32_e32 v51, 1.0, v51
	v_add_f32_e32 v54, 1.0, v54
	v_rcp_f32_e32 v50, v50
	v_rcp_f32_e32 v51, v51
	v_rcp_f32_e32 v73, v54
	v_add_f32_e32 v52, 1.0, v52
	v_add_f32_e32 v53, 1.0, v53
	v_rcp_f32_e32 v52, v52
	v_rcp_f32_e32 v53, v53
	v_pk_mul_f32 v[50:51], v[50:51], v[70:71]
	v_pk_mul_f32 v[56:57], v[72:73], v[56:57]
	v_lshlrev_b32_e32 v54, 16, v109
	v_pk_mul_f32 v[50:51], v[50:51], v[56:57]
	v_lshlrev_b32_e32 v56, 16, v111
	v_and_b32_e32 v55, 0xffff0000, v109
	v_and_b32_e32 v57, 0xffff0000, v111
	v_mul_f32_e32 v58, 0xbfb8aa3b, v56
	v_pk_mul_f32 v[52:53], v[52:53], v[54:55]
	v_mul_f32_e32 v54, 0xbfb8aa3b, v57
	v_exp_f32_e32 v58, v58
	v_exp_f32_e32 v54, v54
	v_cvt_pk_bf16_f32 v50, v50, v51
	v_add_f32_e32 v58, 1.0, v58
	v_add_f32_e32 v54, 1.0, v54
	v_rcp_f32_e32 v58, v58
	v_rcp_f32_e32 v59, v54
	s_nop 0
	v_pk_mul_f32 v[54:55], v[58:59], v[56:57]
	s_nop 0
	v_pk_mul_f32 v[52:53], v[52:53], v[54:55]
	s_nop 0
	v_cvt_pk_bf16_f32 v51, v52, v53
	global_store_dwordx2 v[48:49], v[50:51], off offset:32
	global_load_dwordx4 v[104:107], v[158:159], off offset:-64
	global_load_dwordx2 v[108:109], v[164:165], off offset:32
	global_load_dwordx2 v[110:111], v[166:167], off offset:1056
	s_nop 0
	s_waitcnt vmcnt(24)
	v_add_f32_e32 v50, v60, v112
	v_lshlrev_b32_e32 v58, 16, v116
	v_lshlrev_b32_e32 v60, 16, v118
	v_and_b32_e32 v59, 0xffff0000, v116
	v_mul_f32_e32 v54, 0xbfb8aa3b, v60
	v_exp_f32_e32 v54, v54
	v_add_f32_e32 v51, v61, v113
	v_and_b32_e32 v61, 0xffff0000, v118
	v_mul_f32_e32 v50, 0xbfb8aa3b, v50
	v_add_f32_e32 v54, 1.0, v54
	v_mul_f32_e32 v51, 0xbfb8aa3b, v51
	v_rcp_f32_e32 v68, v54
	v_mul_f32_e32 v54, 0xbfb8aa3b, v61
	v_add_f32_e32 v52, v62, v114
	v_add_f32_e32 v53, v63, v115
	v_exp_f32_e32 v50, v50
	v_exp_f32_e32 v51, v51
	v_exp_f32_e32 v54, v54
	v_mul_f32_e32 v52, 0xbfb8aa3b, v52
	v_mul_f32_e32 v53, 0xbfb8aa3b, v53
	v_exp_f32_e32 v52, v52
	v_exp_f32_e32 v53, v53
	v_add_f32_e32 v50, 1.0, v50
	v_add_f32_e32 v51, 1.0, v51
	v_add_f32_e32 v54, 1.0, v54
	v_rcp_f32_e32 v50, v50
	v_rcp_f32_e32 v51, v51
	v_rcp_f32_e32 v69, v54
	v_add_f32_e32 v52, 1.0, v52
	v_add_f32_e32 v53, 1.0, v53
	v_rcp_f32_e32 v52, v52
	v_rcp_f32_e32 v53, v53
	v_pk_mul_f32 v[50:51], v[50:51], v[58:59]
	v_pk_mul_f32 v[58:59], v[68:69], v[60:61]
	v_lshlrev_b32_e32 v54, 16, v117
	v_lshlrev_b32_e32 v56, 16, v119
	v_and_b32_e32 v55, 0xffff0000, v117
	v_and_b32_e32 v57, 0xffff0000, v119
	v_pk_mul_f32 v[50:51], v[50:51], v[58:59]
	v_mul_f32_e32 v58, 0xbfb8aa3b, v56
	v_pk_mul_f32 v[52:53], v[52:53], v[54:55]
	v_mul_f32_e32 v54, 0xbfb8aa3b, v57
	v_exp_f32_e32 v58, v58
	v_exp_f32_e32 v54, v54
	v_cvt_pk_bf16_f32 v50, v50, v51
	v_add_f32_e32 v58, 1.0, v58
	v_add_f32_e32 v54, 1.0, v54
	v_rcp_f32_e32 v58, v58
	v_rcp_f32_e32 v59, v54
	s_nop 0
	v_pk_mul_f32 v[54:55], v[58:59], v[56:57]
	s_nop 0
	v_pk_mul_f32 v[52:53], v[52:53], v[54:55]
	s_nop 0
	v_cvt_pk_bf16_f32 v51, v52, v53
	global_store_dwordx2 v[48:49], v[50:51], off offset:48
	global_load_dwordx4 v[112:115], v[158:159], off offset:-32
	global_load_dwordx2 v[116:117], v[164:165], off offset:48
	global_load_dwordx2 v[118:119], v[166:167], off offset:1072
	s_nop 0
	s_waitcnt vmcnt(25)
; __device__ __forceinline__ float bflo(unsigned u) { return __uint_as_float(u << 16); }
; __device__ __forceinline__ float bfhi(unsigned u) { return __uint_as_float(u & 0xFFFF0000u); }
; __device__ __forceinline__ float sigmoidf_(float x) { return __builtin_amdgcn_rcpf(1.f + __expf(-x)); }
; __device__ __forceinline__ float siluf_(float x) { return x * __builtin_amdgcn_rcpf(1.f + __expf(-x)); }
; __device__ __forceinline__ void s5_pass2(const Params& p, int layer, int task, char* sm) {
;     ...
;     for (int i = 0; i < 2; i++) {
;       const size_t tok = tok0 + wr * 64 + i * 32 + r32;
; #pragma unroll
;       for (int j = 0; j < 2; j++)
; #pragma unroll
;         for (int q = 0; q < 4; q++) {
;           const int n = tn * 128 + wc * 64 + j * 32 + q * 8 + h5 * 4;
;           float4 bg = *(const float4*)(p.b_glu + layer * 512 + n);
;           uint2 yy = *(const uint2*)(p.YG + tok * 512 + n);
;           uint2 zz = *(const uint2*)(p.P + tok * PW + C_S5Z + n);
;           float o0 = bflo(yy.x) * sigmoidf_(acc[i][j][4 * q] + bg.x) * siluf_(bflo(zz.x));
;           float o1 = bfhi(yy.x) * sigmoidf_(acc[i][j][4 * q + 1] + bg.y) * siluf_(bfhi(zz.x));
;           float o2 = bflo(yy.y) * sigmoidf_(acc[i][j][4 * q + 2] + bg.z) * siluf_(bflo(zz.y));
;           float o3 = bfhi(yy.y) * sigmoidf_(acc[i][j][4 * q + 3] + bg.w) * siluf_(bfhi(zz.y));
;           *(uint2*)(p.Y + tok * YW + Y_S5 + n) = make_uint2(pk2(o0, o1), pk2(o2, o3));
;         }
	v_add_f32_e32 v32, v32, v120
	v_lshlrev_b32_e32 v58, 16, v124
	v_lshlrev_b32_e32 v50, 16, v126
	v_and_b32_e32 v59, 0xffff0000, v124
	v_mul_f32_e32 v54, 0xbfb8aa3b, v50
	v_exp_f32_e32 v54, v54
	v_add_f32_e32 v33, v33, v121
	v_and_b32_e32 v51, 0xffff0000, v126
	v_mul_f32_e32 v32, 0xbfb8aa3b, v32
	v_add_f32_e32 v54, 1.0, v54
	v_mul_f32_e32 v33, 0xbfb8aa3b, v33
	v_rcp_f32_e32 v60, v54
	v_mul_f32_e32 v54, 0xbfb8aa3b, v51
	v_exp_f32_e32 v32, v32
	v_exp_f32_e32 v33, v33
	v_exp_f32_e32 v54, v54
	v_add_f32_e32 v34, v34, v122
	v_add_f32_e32 v35, v35, v123
	v_mul_f32_e32 v34, 0xbfb8aa3b, v34
	v_mul_f32_e32 v35, 0xbfb8aa3b, v35
	v_exp_f32_e32 v34, v34
	v_exp_f32_e32 v35, v35
	v_add_f32_e32 v32, 1.0, v32
	v_add_f32_e32 v33, 1.0, v33
	v_add_f32_e32 v54, 1.0, v54
	v_rcp_f32_e32 v32, v32
	v_rcp_f32_e32 v33, v33
	v_rcp_f32_e32 v61, v54
	v_add_f32_e32 v34, 1.0, v34
	v_add_f32_e32 v35, 1.0, v35
	v_rcp_f32_e32 v34, v34
	v_rcp_f32_e32 v35, v35
	v_pk_mul_f32 v[32:33], v[32:33], v[58:59]
	v_pk_mul_f32 v[50:51], v[60:61], v[50:51]
	v_lshlrev_b32_e32 v52, 16, v127
	v_pk_mul_f32 v[32:33], v[32:33], v[50:51]
	v_lshlrev_b32_e32 v50, 16, v125
	v_and_b32_e32 v51, 0xffff0000, v125
	v_and_b32_e32 v53, 0xffff0000, v127
	v_mul_f32_e32 v54, 0xbfb8aa3b, v52
	v_pk_mul_f32 v[34:35], v[34:35], v[50:51]
	v_mul_f32_e32 v50, 0xbfb8aa3b, v53
	v_exp_f32_e32 v54, v54
	v_exp_f32_e32 v50, v50
	v_cvt_pk_bf16_f32 v32, v32, v33
	v_add_f32_e32 v54, 1.0, v54
	v_add_f32_e32 v50, 1.0, v50
	v_rcp_f32_e32 v54, v54
	v_rcp_f32_e32 v55, v50
	s_nop 0
	v_pk_mul_f32 v[50:51], v[54:55], v[52:53]
	s_nop 0
	v_pk_mul_f32 v[34:35], v[34:35], v[50:51]
	s_nop 0
	v_cvt_pk_bf16_f32 v33, v34, v35
	global_store_dwordx2 v[48:49], v[32:33], off offset:64
	global_load_dwordx4 v[120:123], v[158:159], off
	global_load_dwordx2 v[124:125], v[164:165], off offset:64
	global_load_dwordx2 v[126:127], v[166:167], off offset:1088
	s_nop 0
	s_waitcnt vmcnt(26)
	v_add_f32_e32 v32, v36, v128
	v_lshlrev_b32_e32 v54, 16, v132
	v_lshlrev_b32_e32 v36, 16, v134
	v_and_b32_e32 v55, 0xffff0000, v132
	v_mul_f32_e32 v50, 0xbfb8aa3b, v36
	v_exp_f32_e32 v50, v50
	v_add_f32_e32 v33, v37, v129
	v_and_b32_e32 v37, 0xffff0000, v134
	v_mul_f32_e32 v32, 0xbfb8aa3b, v32
	v_add_f32_e32 v50, 1.0, v50
	v_mul_f32_e32 v33, 0xbfb8aa3b, v33
	v_rcp_f32_e32 v56, v50
	v_mul_f32_e32 v50, 0xbfb8aa3b, v37
	v_exp_f32_e32 v32, v32
	v_exp_f32_e32 v33, v33
	v_exp_f32_e32 v50, v50
	v_add_f32_e32 v34, v38, v130
	v_add_f32_e32 v35, v39, v131
	v_mul_f32_e32 v34, 0xbfb8aa3b, v34
	v_mul_f32_e32 v35, 0xbfb8aa3b, v35
	v_exp_f32_e32 v34, v34
	v_exp_f32_e32 v35, v35
	v_add_f32_e32 v32, 1.0, v32
	v_add_f32_e32 v33, 1.0, v33
	v_add_f32_e32 v50, 1.0, v50
	v_rcp_f32_e32 v32, v32
	v_rcp_f32_e32 v33, v33
	v_rcp_f32_e32 v57, v50
	v_add_f32_e32 v34, 1.0, v34
	v_add_f32_e32 v35, 1.0, v35
	v_rcp_f32_e32 v34, v34
	v_rcp_f32_e32 v35, v35
	v_pk_mul_f32 v[32:33], v[32:33], v[54:55]
	v_pk_mul_f32 v[36:37], v[56:57], v[36:37]
	v_lshlrev_b32_e32 v38, 16, v135
	v_pk_mul_f32 v[32:33], v[32:33], v[36:37]
	v_lshlrev_b32_e32 v36, 16, v133
	v_and_b32_e32 v37, 0xffff0000, v133
	v_and_b32_e32 v39, 0xffff0000, v135
	v_mul_f32_e32 v50, 0xbfb8aa3b, v38
	v_pk_mul_f32 v[34:35], v[34:35], v[36:37]
	v_mul_f32_e32 v36, 0xbfb8aa3b, v39
	v_exp_f32_e32 v50, v50
	v_exp_f32_e32 v36, v36
	v_cvt_pk_bf16_f32 v32, v32, v33
	v_add_f32_e32 v50, 1.0, v50
	v_add_f32_e32 v36, 1.0, v36
	v_rcp_f32_e32 v50, v50
	v_rcp_f32_e32 v51, v36
	s_nop 0
	v_pk_mul_f32 v[36:37], v[50:51], v[38:39]
	s_nop 0
	v_pk_mul_f32 v[34:35], v[34:35], v[36:37]
	s_nop 0
	v_cvt_pk_bf16_f32 v33, v34, v35
	global_store_dwordx2 v[48:49], v[32:33], off offset:80
	global_load_dwordx4 v[128:131], v[158:159], off offset:32
	global_load_dwordx2 v[132:133], v[164:165], off offset:80
	global_load_dwordx2 v[134:135], v[166:167], off offset:1104
	s_nop 0
	s_waitcnt vmcnt(27)
	v_add_f32_e32 v32, v40, v136
	v_lshlrev_b32_e32 v50, 16, v140
	v_lshlrev_b32_e32 v40, 16, v142
	v_and_b32_e32 v51, 0xffff0000, v140
	v_mul_f32_e32 v36, 0xbfb8aa3b, v40
	v_exp_f32_e32 v36, v36
	v_add_f32_e32 v33, v41, v137
	v_and_b32_e32 v41, 0xffff0000, v142
	v_mul_f32_e32 v32, 0xbfb8aa3b, v32
	v_add_f32_e32 v36, 1.0, v36
	v_mul_f32_e32 v33, 0xbfb8aa3b, v33
	v_rcp_f32_e32 v52, v36
	v_mul_f32_e32 v36, 0xbfb8aa3b, v41
	v_add_f32_e32 v34, v42, v138
	v_add_f32_e32 v35, v43, v139
	v_exp_f32_e32 v32, v32
	v_exp_f32_e32 v33, v33
	v_exp_f32_e32 v36, v36
	v_mul_f32_e32 v34, 0xbfb8aa3b, v34
	v_mul_f32_e32 v35, 0xbfb8aa3b, v35
	v_exp_f32_e32 v34, v34
	v_exp_f32_e32 v35, v35
	v_add_f32_e32 v32, 1.0, v32
	v_add_f32_e32 v33, 1.0, v33
	v_add_f32_e32 v36, 1.0, v36
	v_rcp_f32_e32 v32, v32
	v_rcp_f32_e32 v33, v33
	v_rcp_f32_e32 v53, v36
	v_add_f32_e32 v34, 1.0, v34
	v_add_f32_e32 v35, 1.0, v35
	v_rcp_f32_e32 v34, v34
	v_rcp_f32_e32 v35, v35
	v_pk_mul_f32 v[32:33], v[32:33], v[50:51]
	v_pk_mul_f32 v[40:41], v[52:53], v[40:41]
	v_lshlrev_b32_e32 v36, 16, v141
	v_lshlrev_b32_e32 v38, 16, v143
	v_and_b32_e32 v37, 0xffff0000, v141
	v_and_b32_e32 v39, 0xffff0000, v143
	v_pk_mul_f32 v[32:33], v[32:33], v[40:41]
	v_mul_f32_e32 v40, 0xbfb8aa3b, v38
	v_pk_mul_f32 v[34:35], v[34:35], v[36:37]
	v_mul_f32_e32 v36, 0xbfb8aa3b, v39
	v_exp_f32_e32 v40, v40
	v_exp_f32_e32 v36, v36
	v_cvt_pk_bf16_f32 v32, v32, v33
	v_add_f32_e32 v40, 1.0, v40
	v_add_f32_e32 v36, 1.0, v36
	v_rcp_f32_e32 v40, v40
	v_rcp_f32_e32 v41, v36
	s_nop 0
	v_pk_mul_f32 v[36:37], v[40:41], v[38:39]
	s_nop 0
	v_pk_mul_f32 v[34:35], v[34:35], v[36:37]
	s_nop 0
	v_cvt_pk_bf16_f32 v33, v34, v35
	global_store_dwordx2 v[48:49], v[32:33], off offset:96
	global_load_dwordx4 v[136:139], v[158:159], off offset:64
	global_load_dwordx2 v[140:141], v[164:165], off offset:96
	global_load_dwordx2 v[142:143], v[166:167], off offset:1120
	s_nop 0
	s_waitcnt vmcnt(28)
; __device__ __forceinline__ float bflo(unsigned u) { return __uint_as_float(u << 16); }
; __device__ __forceinline__ float bfhi(unsigned u) { return __uint_as_float(u & 0xFFFF0000u); }
; __device__ __forceinline__ float sigmoidf_(float x) { return __builtin_amdgcn_rcpf(1.f + __expf(-x)); }
; __device__ __forceinline__ float siluf_(float x) { return x * __builtin_amdgcn_rcpf(1.f + __expf(-x)); }
; __device__ __forceinline__ void s5_pass2(const Params& p, int layer, int task, char* sm) {
;     ...
;     for (int i = 0; i < 2; i++) {
;       const size_t tok = tok0 + wr * 64 + i * 32 + r32;
; #pragma unroll
;       for (int j = 0; j < 2; j++)
; #pragma unroll
;         for (int q = 0; q < 4; q++) {
;           const int n = tn * 128 + wc * 64 + j * 32 + q * 8 + h5 * 4;
;           float4 bg = *(const float4*)(p.b_glu + layer * 512 + n);
;           uint2 yy = *(const uint2*)(p.YG + tok * 512 + n);
;           uint2 zz = *(const uint2*)(p.P + tok * PW + C_S5Z + n);
;           float o0 = bflo(yy.x) * sigmoidf_(acc[i][j][4 * q] + bg.x) * siluf_(bflo(zz.x));
;           float o1 = bfhi(yy.x) * sigmoidf_(acc[i][j][4 * q + 1] + bg.y) * siluf_(bfhi(zz.x));
;           float o2 = bflo(yy.y) * sigmoidf_(acc[i][j][4 * q + 2] + bg.z) * siluf_(bflo(zz.y));
;           float o3 = bfhi(yy.y) * sigmoidf_(acc[i][j][4 * q + 3] + bg.w) * siluf_(bfhi(zz.y));
;           *(uint2*)(p.Y + tok * YW + Y_S5 + n) = make_uint2(pk2(o0, o1), pk2(o2, o3));
;         }
	v_add_f32_e32 v32, v44, v170
	v_lshlrev_b32_e32 v40, 16, v174
	v_lshlrev_b32_e32 v42, 16, v176
	v_and_b32_e32 v41, 0xffff0000, v174
	v_mul_f32_e32 v36, 0xbfb8aa3b, v42
	v_exp_f32_e32 v36, v36
	v_add_f32_e32 v33, v45, v171
	v_and_b32_e32 v43, 0xffff0000, v176
	v_mul_f32_e32 v32, 0xbfb8aa3b, v32
	v_add_f32_e32 v36, 1.0, v36
	v_mul_f32_e32 v33, 0xbfb8aa3b, v33
	v_rcp_f32_e32 v44, v36
	v_mul_f32_e32 v36, 0xbfb8aa3b, v43
	v_add_f32_e32 v34, v46, v172
	v_add_f32_e32 v35, v47, v173
	v_exp_f32_e32 v32, v32
	v_exp_f32_e32 v33, v33
	v_exp_f32_e32 v36, v36
	v_mul_f32_e32 v34, 0xbfb8aa3b, v34
	v_mul_f32_e32 v35, 0xbfb8aa3b, v35
	v_exp_f32_e32 v34, v34
	v_exp_f32_e32 v35, v35
	v_add_f32_e32 v32, 1.0, v32
	v_add_f32_e32 v33, 1.0, v33
	v_add_f32_e32 v36, 1.0, v36
	v_rcp_f32_e32 v32, v32
	v_rcp_f32_e32 v33, v33
	v_rcp_f32_e32 v45, v36
	v_add_f32_e32 v34, 1.0, v34
	v_add_f32_e32 v35, 1.0, v35
	v_rcp_f32_e32 v34, v34
	v_rcp_f32_e32 v35, v35
	v_pk_mul_f32 v[32:33], v[32:33], v[40:41]
	v_pk_mul_f32 v[40:41], v[44:45], v[42:43]
	v_lshlrev_b32_e32 v36, 16, v175
	v_lshlrev_b32_e32 v38, 16, v177
	v_and_b32_e32 v37, 0xffff0000, v175
	v_and_b32_e32 v39, 0xffff0000, v177
	v_pk_mul_f32 v[32:33], v[32:33], v[40:41]
	v_mul_f32_e32 v40, 0xbfb8aa3b, v38
	v_pk_mul_f32 v[34:35], v[34:35], v[36:37]
	v_mul_f32_e32 v36, 0xbfb8aa3b, v39
	v_exp_f32_e32 v40, v40
	v_exp_f32_e32 v36, v36
	v_cvt_pk_bf16_f32 v32, v32, v33
	v_add_f32_e32 v40, 1.0, v40
	v_add_f32_e32 v36, 1.0, v36
	v_rcp_f32_e32 v40, v40
	v_rcp_f32_e32 v41, v36
	s_nop 0
	v_pk_mul_f32 v[36:37], v[40:41], v[38:39]
	s_nop 0
	v_pk_mul_f32 v[34:35], v[34:35], v[36:37]
	v_lshl_add_u64 v[38:39], v[150:151], 0, s[2:3]
	v_cvt_pk_bf16_f32 v33, v34, v35
	global_store_dwordx2 v[48:49], v[32:33], off offset:112
	global_load_dwordx4 v[170:173], v[158:159], off offset:96
	global_load_dwordx2 v[174:175], v[164:165], off offset:112
	global_load_dwordx2 v[176:177], v[166:167], off offset:1136
	v_lshl_add_u64 v[36:37], v[148:149], 0, s[2:3]
	s_waitcnt vmcnt(28)
	v_add_f32_e32 v16, v16, v88
	v_add_f32_e32 v17, v17, v89
	v_lshlrev_b32_e32 v32, 16, v94
	v_lshlrev_b32_e32 v44, 16, v92
	v_and_b32_e32 v45, 0xffff0000, v92
	v_mul_f32_e32 v40, 0xbfb8aa3b, v32
	v_exp_f32_e32 v40, v40
	v_and_b32_e32 v33, 0xffff0000, v94
	v_mul_f32_e32 v16, 0xbfb8aa3b, v16
	v_mul_f32_e32 v17, 0xbfb8aa3b, v17
	v_add_f32_e32 v40, 1.0, v40
	v_rcp_f32_e32 v46, v40
	v_mul_f32_e32 v40, 0xbfb8aa3b, v33
	v_exp_f32_e32 v16, v16
	v_exp_f32_e32 v17, v17
	v_exp_f32_e32 v40, v40
	v_add_f32_e32 v18, v18, v90
	v_add_f32_e32 v19, v19, v91
	v_mul_f32_e32 v18, 0xbfb8aa3b, v18
	v_mul_f32_e32 v19, 0xbfb8aa3b, v19
	v_exp_f32_e32 v18, v18
	v_exp_f32_e32 v19, v19
	v_add_f32_e32 v16, 1.0, v16
	v_add_f32_e32 v17, 1.0, v17
	v_add_f32_e32 v40, 1.0, v40
	v_rcp_f32_e32 v16, v16
	v_rcp_f32_e32 v17, v17
	v_rcp_f32_e32 v47, v40
	v_add_f32_e32 v18, 1.0, v18
	v_add_f32_e32 v19, 1.0, v19
	v_rcp_f32_e32 v18, v18
	v_rcp_f32_e32 v19, v19
	v_pk_mul_f32 v[16:17], v[16:17], v[44:45]
	v_pk_mul_f32 v[32:33], v[46:47], v[32:33]
	v_lshlrev_b32_e32 v34, 16, v95
	v_pk_mul_f32 v[16:17], v[16:17], v[32:33]
	v_lshlrev_b32_e32 v32, 16, v93
	v_and_b32_e32 v33, 0xffff0000, v93
	v_and_b32_e32 v35, 0xffff0000, v95
	v_mul_f32_e32 v40, 0xbfb8aa3b, v34
	v_pk_mul_f32 v[18:19], v[18:19], v[32:33]
	v_mul_f32_e32 v32, 0xbfb8aa3b, v35
	v_exp_f32_e32 v40, v40
	v_exp_f32_e32 v32, v32
	v_add_f32_e32 v40, 1.0, v40
	v_add_f32_e32 v32, 1.0, v32
	v_rcp_f32_e32 v40, v40
	v_rcp_f32_e32 v41, v32
	s_nop 0
	v_pk_mul_f32 v[32:33], v[40:41], v[34:35]
	s_nop 0
	v_pk_mul_f32 v[32:33], v[18:19], v[32:33]
	v_cvt_pk_bf16_f32 v18, v16, v17
	v_cvt_pk_bf16_f32 v19, v32, v33
	v_lshl_add_u64 v[16:17], v[146:147], 0, s[2:3]
	global_store_dwordx2 v[16:17], v[18:19], off
	s_add_u32 s2, s2, 0x100
	s_addc_u32 s3, s3, 0
	s_cmpk_lg_i32 s2, 0x400
	s_waitcnt vmcnt(25)
	v_add_f32_e32 v19, v20, v96
	v_add_f32_e32 v21, v21, v97
	v_mul_f32_e32 v19, 0xbfb8aa3b, v19
	v_mul_f32_e32 v21, 0xbfb8aa3b, v21
	v_exp_f32_e32 v19, v19
	v_exp_f32_e32 v21, v21
	v_lshlrev_b32_e32 v18, 16, v100
	v_lshlrev_b32_e32 v32, 16, v102
	v_add_f32_e32 v19, 1.0, v19
	v_add_f32_e32 v21, 1.0, v21
	v_rcp_f32_e32 v20, v19
	v_rcp_f32_e32 v21, v21
	v_and_b32_e32 v19, 0xffff0000, v100
	v_and_b32_e32 v33, 0xffff0000, v102
	v_mul_f32_e32 v40, 0xbfb8aa3b, v32
	v_pk_mul_f32 v[18:19], v[20:21], v[18:19]
	v_mul_f32_e32 v20, 0xbfb8aa3b, v33
	v_exp_f32_e32 v40, v40
	v_exp_f32_e32 v20, v20
	v_add_f32_e32 v23, v23, v99
	v_mul_f32_e32 v23, 0xbfb8aa3b, v23
	v_add_f32_e32 v40, 1.0, v40
	v_add_f32_e32 v20, 1.0, v20
	v_rcp_f32_e32 v44, v40
	v_rcp_f32_e32 v45, v20
	v_exp_f32_e32 v23, v23
	v_pk_mul_f32 v[20:21], v[44:45], v[32:33]
	s_nop 0
	v_pk_mul_f32 v[18:19], v[18:19], v[20:21]
	v_add_f32_e32 v21, v22, v98
	v_mul_f32_e32 v21, 0xbfb8aa3b, v21
	v_exp_f32_e32 v21, v21
	v_add_f32_e32 v23, 1.0, v23
	v_rcp_f32_e32 v23, v23
	v_lshlrev_b32_e32 v20, 16, v101
	v_add_f32_e32 v21, 1.0, v21
	v_rcp_f32_e32 v22, v21
	v_lshlrev_b32_e32 v32, 16, v103
	v_and_b32_e32 v21, 0xffff0000, v101
	v_and_b32_e32 v33, 0xffff0000, v103
	v_mul_f32_e32 v34, 0xbfb8aa3b, v32
	v_pk_mul_f32 v[20:21], v[22:23], v[20:21]
	v_mul_f32_e32 v22, 0xbfb8aa3b, v33
	v_exp_f32_e32 v34, v34
	v_exp_f32_e32 v22, v22
	v_cvt_pk_bf16_f32 v18, v18, v19
	v_add_f32_e32 v34, 1.0, v34
	v_add_f32_e32 v22, 1.0, v22
	v_rcp_f32_e32 v34, v34
	v_rcp_f32_e32 v35, v22
	s_nop 0
	v_pk_mul_f32 v[22:23], v[34:35], v[32:33]
	s_nop 0
	v_pk_mul_f32 v[20:21], v[20:21], v[22:23]
	s_nop 0
	v_cvt_pk_bf16_f32 v19, v20, v21
	global_store_dwordx2 v[16:17], v[18:19], off offset:16
	s_nop 0
	s_waitcnt vmcnt(22)
; __device__ __forceinline__ float bflo(unsigned u) { return __uint_as_float(u << 16); }
; __device__ __forceinline__ float bfhi(unsigned u) { return __uint_as_float(u & 0xFFFF0000u); }
; __device__ __forceinline__ float sigmoidf_(float x) { return __builtin_amdgcn_rcpf(1.f + __expf(-x)); }
; __device__ __forceinline__ float siluf_(float x) { return x * __builtin_amdgcn_rcpf(1.f + __expf(-x)); }
; __device__ __forceinline__ void s5_pass2(const Params& p, int layer, int task, char* sm) {
;     ...
;     for (int i = 0; i < 2; i++) {
;       const size_t tok = tok0 + wr * 64 + i * 32 + r32;
; #pragma unroll
;       for (int j = 0; j < 2; j++)
; #pragma unroll
;         for (int q = 0; q < 4; q++) {
;           const int n = tn * 128 + wc * 64 + j * 32 + q * 8 + h5 * 4;
;           float4 bg = *(const float4*)(p.b_glu + layer * 512 + n);
;           uint2 yy = *(const uint2*)(p.YG + tok * 512 + n);
;           uint2 zz = *(const uint2*)(p.P + tok * PW + C_S5Z + n);
;           float o0 = bflo(yy.x) * sigmoidf_(acc[i][j][4 * q] + bg.x) * siluf_(bflo(zz.x));
;           float o1 = bfhi(yy.x) * sigmoidf_(acc[i][j][4 * q + 1] + bg.y) * siluf_(bfhi(zz.x));
;           float o2 = bflo(yy.y) * sigmoidf_(acc[i][j][4 * q + 2] + bg.z) * siluf_(bflo(zz.y));
;           float o3 = bfhi(yy.y) * sigmoidf_(acc[i][j][4 * q + 3] + bg.w) * siluf_(bfhi(zz.y));
;           *(uint2*)(p.Y + tok * YW + Y_S5 + n) = make_uint2(pk2(o0, o1), pk2(o2, o3));
;         }
	v_add_f32_e32 v18, v24, v104
	v_lshlrev_b32_e32 v34, 16, v108
	v_lshlrev_b32_e32 v24, 16, v110
	v_and_b32_e32 v35, 0xffff0000, v108
	v_mul_f32_e32 v22, 0xbfb8aa3b, v24
	v_exp_f32_e32 v22, v22
	v_add_f32_e32 v19, v25, v105
	v_and_b32_e32 v25, 0xffff0000, v110
	v_mul_f32_e32 v18, 0xbfb8aa3b, v18
	v_add_f32_e32 v22, 1.0, v22
	v_mul_f32_e32 v19, 0xbfb8aa3b, v19
	v_rcp_f32_e32 v40, v22
	v_mul_f32_e32 v22, 0xbfb8aa3b, v25
	v_exp_f32_e32 v18, v18
	v_exp_f32_e32 v19, v19
	v_exp_f32_e32 v22, v22
	v_add_f32_e32 v20, v26, v106
	v_add_f32_e32 v21, v27, v107
	v_mul_f32_e32 v20, 0xbfb8aa3b, v20
	v_mul_f32_e32 v21, 0xbfb8aa3b, v21
	v_exp_f32_e32 v20, v20
	v_exp_f32_e32 v21, v21
	v_add_f32_e32 v18, 1.0, v18
	v_add_f32_e32 v19, 1.0, v19
	v_add_f32_e32 v22, 1.0, v22
	v_rcp_f32_e32 v18, v18
	v_rcp_f32_e32 v19, v19
	v_rcp_f32_e32 v41, v22
	v_add_f32_e32 v20, 1.0, v20
	v_add_f32_e32 v21, 1.0, v21
	v_rcp_f32_e32 v20, v20
	v_rcp_f32_e32 v21, v21
	v_pk_mul_f32 v[18:19], v[18:19], v[34:35]
	v_pk_mul_f32 v[24:25], v[40:41], v[24:25]
	v_lshlrev_b32_e32 v22, 16, v109
	v_pk_mul_f32 v[18:19], v[18:19], v[24:25]
	v_lshlrev_b32_e32 v24, 16, v111
	v_and_b32_e32 v23, 0xffff0000, v109
	v_and_b32_e32 v25, 0xffff0000, v111
	v_mul_f32_e32 v26, 0xbfb8aa3b, v24
	v_pk_mul_f32 v[20:21], v[20:21], v[22:23]
	v_mul_f32_e32 v22, 0xbfb8aa3b, v25
	v_exp_f32_e32 v26, v26
	v_exp_f32_e32 v22, v22
	v_cvt_pk_bf16_f32 v18, v18, v19
	v_add_f32_e32 v26, 1.0, v26
	v_add_f32_e32 v22, 1.0, v22
	v_rcp_f32_e32 v26, v26
	v_rcp_f32_e32 v27, v22
	s_nop 0
	v_pk_mul_f32 v[22:23], v[26:27], v[24:25]
	s_nop 0
	v_pk_mul_f32 v[20:21], v[20:21], v[22:23]
	s_nop 0
	v_cvt_pk_bf16_f32 v19, v20, v21
	global_store_dwordx2 v[16:17], v[18:19], off offset:32
	s_nop 0
	s_waitcnt vmcnt(19)
	v_add_f32_e32 v18, v28, v112
	v_lshlrev_b32_e32 v26, 16, v116
	v_lshlrev_b32_e32 v28, 16, v118
	v_and_b32_e32 v27, 0xffff0000, v116
	v_mul_f32_e32 v22, 0xbfb8aa3b, v28
	v_exp_f32_e32 v22, v22
	v_add_f32_e32 v19, v29, v113
	v_and_b32_e32 v29, 0xffff0000, v118
	v_mul_f32_e32 v18, 0xbfb8aa3b, v18
	v_add_f32_e32 v22, 1.0, v22
	v_mul_f32_e32 v19, 0xbfb8aa3b, v19
	v_rcp_f32_e32 v32, v22
	v_mul_f32_e32 v22, 0xbfb8aa3b, v29
	v_add_f32_e32 v20, v30, v114
	v_add_f32_e32 v21, v31, v115
	v_exp_f32_e32 v18, v18
	v_exp_f32_e32 v19, v19
	v_exp_f32_e32 v22, v22
	v_mul_f32_e32 v20, 0xbfb8aa3b, v20
	v_mul_f32_e32 v21, 0xbfb8aa3b, v21
	v_exp_f32_e32 v20, v20
	v_exp_f32_e32 v21, v21
	v_add_f32_e32 v18, 1.0, v18
	v_add_f32_e32 v19, 1.0, v19
	v_add_f32_e32 v22, 1.0, v22
	v_rcp_f32_e32 v18, v18
	v_rcp_f32_e32 v19, v19
	v_rcp_f32_e32 v33, v22
	v_add_f32_e32 v20, 1.0, v20
	v_add_f32_e32 v21, 1.0, v21
	v_rcp_f32_e32 v20, v20
	v_rcp_f32_e32 v21, v21
	v_pk_mul_f32 v[18:19], v[18:19], v[26:27]
	v_pk_mul_f32 v[26:27], v[32:33], v[28:29]
	v_lshlrev_b32_e32 v22, 16, v117
	v_lshlrev_b32_e32 v24, 16, v119
	v_and_b32_e32 v23, 0xffff0000, v117
	v_and_b32_e32 v25, 0xffff0000, v119
	v_pk_mul_f32 v[18:19], v[18:19], v[26:27]
	v_mul_f32_e32 v26, 0xbfb8aa3b, v24
	v_pk_mul_f32 v[20:21], v[20:21], v[22:23]
	v_mul_f32_e32 v22, 0xbfb8aa3b, v25
	v_exp_f32_e32 v26, v26
	v_exp_f32_e32 v22, v22
	v_cvt_pk_bf16_f32 v18, v18, v19
	v_add_f32_e32 v26, 1.0, v26
	v_add_f32_e32 v22, 1.0, v22
	v_rcp_f32_e32 v26, v26
	v_rcp_f32_e32 v27, v22
	s_nop 0
	v_pk_mul_f32 v[22:23], v[26:27], v[24:25]
	s_nop 0
	v_pk_mul_f32 v[20:21], v[20:21], v[22:23]
	s_nop 0
	v_cvt_pk_bf16_f32 v19, v20, v21
	global_store_dwordx2 v[16:17], v[18:19], off offset:48
	s_nop 0
	s_waitcnt vmcnt(16)
	v_add_f32_e32 v0, v0, v120
	v_lshlrev_b32_e32 v26, 16, v124
	v_lshlrev_b32_e32 v18, 16, v126
	v_and_b32_e32 v27, 0xffff0000, v124
	v_mul_f32_e32 v22, 0xbfb8aa3b, v18
	v_exp_f32_e32 v22, v22
	v_add_f32_e32 v1, v1, v121
	v_and_b32_e32 v19, 0xffff0000, v126
	v_mul_f32_e32 v0, 0xbfb8aa3b, v0
	v_add_f32_e32 v22, 1.0, v22
	v_mul_f32_e32 v1, 0xbfb8aa3b, v1
	v_rcp_f32_e32 v28, v22
	v_mul_f32_e32 v22, 0xbfb8aa3b, v19
	v_exp_f32_e32 v0, v0
	v_exp_f32_e32 v1, v1
	v_exp_f32_e32 v22, v22
	v_add_f32_e32 v2, v2, v122
	v_add_f32_e32 v3, v3, v123
	v_mul_f32_e32 v2, 0xbfb8aa3b, v2
	v_mul_f32_e32 v3, 0xbfb8aa3b, v3
	v_exp_f32_e32 v2, v2
	v_exp_f32_e32 v3, v3
	v_add_f32_e32 v0, 1.0, v0
	v_add_f32_e32 v1, 1.0, v1
	v_add_f32_e32 v22, 1.0, v22
	v_rcp_f32_e32 v0, v0
	v_rcp_f32_e32 v1, v1
	v_rcp_f32_e32 v29, v22
	v_add_f32_e32 v2, 1.0, v2
	v_add_f32_e32 v3, 1.0, v3
	v_rcp_f32_e32 v2, v2
	v_rcp_f32_e32 v3, v3
	v_pk_mul_f32 v[0:1], v[0:1], v[26:27]
	v_pk_mul_f32 v[18:19], v[28:29], v[18:19]
	v_lshlrev_b32_e32 v20, 16, v127
	v_pk_mul_f32 v[0:1], v[0:1], v[18:19]
	v_lshlrev_b32_e32 v18, 16, v125
	v_and_b32_e32 v19, 0xffff0000, v125
	v_and_b32_e32 v21, 0xffff0000, v127
	v_mul_f32_e32 v22, 0xbfb8aa3b, v20
	v_pk_mul_f32 v[2:3], v[2:3], v[18:19]
	v_mul_f32_e32 v18, 0xbfb8aa3b, v21
	v_exp_f32_e32 v22, v22
	v_exp_f32_e32 v18, v18
	v_cvt_pk_bf16_f32 v0, v0, v1
	v_add_f32_e32 v22, 1.0, v22
	v_add_f32_e32 v18, 1.0, v18
	v_rcp_f32_e32 v22, v22
	v_rcp_f32_e32 v23, v18
	s_nop 0
	v_pk_mul_f32 v[18:19], v[22:23], v[20:21]
	s_nop 0
	v_pk_mul_f32 v[2:3], v[2:3], v[18:19]
	s_nop 0
	v_cvt_pk_bf16_f32 v1, v2, v3
	global_store_dwordx2 v[16:17], v[0:1], off offset:64
	s_nop 0
	s_waitcnt vmcnt(13)
; __device__ __forceinline__ float bflo(unsigned u) { return __uint_as_float(u << 16); }
; __device__ __forceinline__ float bfhi(unsigned u) { return __uint_as_float(u & 0xFFFF0000u); }
; __device__ __forceinline__ float sigmoidf_(float x) { return __builtin_amdgcn_rcpf(1.f + __expf(-x)); }
; __device__ __forceinline__ float siluf_(float x) { return x * __builtin_amdgcn_rcpf(1.f + __expf(-x)); }
; __device__ __forceinline__ void s5_pass2(const Params& p, int layer, int task, char* sm) {
;     ...
;     for (int i = 0; i < 2; i++) {
;       const size_t tok = tok0 + wr * 64 + i * 32 + r32;
; #pragma unroll
;       for (int j = 0; j < 2; j++)
; #pragma unroll
;         for (int q = 0; q < 4; q++) {
;           const int n = tn * 128 + wc * 64 + j * 32 + q * 8 + h5 * 4;
;           float4 bg = *(const float4*)(p.b_glu + layer * 512 + n);
;           uint2 yy = *(const uint2*)(p.YG + tok * 512 + n);
;           uint2 zz = *(const uint2*)(p.P + tok * PW + C_S5Z + n);
;           float o0 = bflo(yy.x) * sigmoidf_(acc[i][j][4 * q] + bg.x) * siluf_(bflo(zz.x));
;           float o1 = bfhi(yy.x) * sigmoidf_(acc[i][j][4 * q + 1] + bg.y) * siluf_(bfhi(zz.x));
;           float o2 = bflo(yy.y) * sigmoidf_(acc[i][j][4 * q + 2] + bg.z) * siluf_(bflo(zz.y));
;           float o3 = bfhi(yy.y) * sigmoidf_(acc[i][j][4 * q + 3] + bg.w) * siluf_(bfhi(zz.y));
;           *(uint2*)(p.Y + tok * YW + Y_S5 + n) = make_uint2(pk2(o0, o1), pk2(o2, o3));
;         }
	v_add_f32_e32 v0, v4, v128
	v_lshlrev_b32_e32 v22, 16, v132
	v_lshlrev_b32_e32 v4, 16, v134
	v_and_b32_e32 v23, 0xffff0000, v132
	v_mul_f32_e32 v18, 0xbfb8aa3b, v4
	v_exp_f32_e32 v18, v18
	v_add_f32_e32 v1, v5, v129
	v_and_b32_e32 v5, 0xffff0000, v134
	v_mul_f32_e32 v0, 0xbfb8aa3b, v0
	v_add_f32_e32 v18, 1.0, v18
	v_mul_f32_e32 v1, 0xbfb8aa3b, v1
	v_rcp_f32_e32 v24, v18
	v_mul_f32_e32 v18, 0xbfb8aa3b, v5
	v_exp_f32_e32 v0, v0
	v_exp_f32_e32 v1, v1
	v_exp_f32_e32 v18, v18
	v_add_f32_e32 v2, v6, v130
	v_add_f32_e32 v3, v7, v131
	v_mul_f32_e32 v2, 0xbfb8aa3b, v2
	v_mul_f32_e32 v3, 0xbfb8aa3b, v3
	v_exp_f32_e32 v2, v2
	v_exp_f32_e32 v3, v3
	v_add_f32_e32 v0, 1.0, v0
	v_add_f32_e32 v1, 1.0, v1
	v_add_f32_e32 v18, 1.0, v18
	v_rcp_f32_e32 v0, v0
	v_rcp_f32_e32 v1, v1
	v_rcp_f32_e32 v25, v18
	v_add_f32_e32 v2, 1.0, v2
	v_add_f32_e32 v3, 1.0, v3
	v_rcp_f32_e32 v2, v2
	v_rcp_f32_e32 v3, v3
	v_pk_mul_f32 v[0:1], v[0:1], v[22:23]
	v_pk_mul_f32 v[4:5], v[24:25], v[4:5]
	v_lshlrev_b32_e32 v6, 16, v135
	v_pk_mul_f32 v[0:1], v[0:1], v[4:5]
	v_lshlrev_b32_e32 v4, 16, v133
	v_and_b32_e32 v5, 0xffff0000, v133
	v_and_b32_e32 v7, 0xffff0000, v135
	v_mul_f32_e32 v18, 0xbfb8aa3b, v6
	v_pk_mul_f32 v[2:3], v[2:3], v[4:5]
	v_mul_f32_e32 v4, 0xbfb8aa3b, v7
	v_exp_f32_e32 v18, v18
	v_exp_f32_e32 v4, v4
	v_cvt_pk_bf16_f32 v0, v0, v1
	v_add_f32_e32 v18, 1.0, v18
	v_add_f32_e32 v4, 1.0, v4
	v_rcp_f32_e32 v18, v18
	v_rcp_f32_e32 v19, v4
	s_nop 0
	v_pk_mul_f32 v[4:5], v[18:19], v[6:7]
	s_nop 0
	v_pk_mul_f32 v[2:3], v[2:3], v[4:5]
	s_nop 0
	v_cvt_pk_bf16_f32 v1, v2, v3
	global_store_dwordx2 v[16:17], v[0:1], off offset:80
	s_nop 0
	s_waitcnt vmcnt(10)
	v_add_f32_e32 v0, v8, v136
	v_lshlrev_b32_e32 v18, 16, v140
	v_lshlrev_b32_e32 v8, 16, v142
	v_and_b32_e32 v19, 0xffff0000, v140
	v_mul_f32_e32 v4, 0xbfb8aa3b, v8
	v_exp_f32_e32 v4, v4
	v_add_f32_e32 v1, v9, v137
	v_and_b32_e32 v9, 0xffff0000, v142
	v_mul_f32_e32 v0, 0xbfb8aa3b, v0
	v_add_f32_e32 v4, 1.0, v4
	v_mul_f32_e32 v1, 0xbfb8aa3b, v1
	v_rcp_f32_e32 v20, v4
	v_mul_f32_e32 v4, 0xbfb8aa3b, v9
	v_add_f32_e32 v2, v10, v138
	v_add_f32_e32 v3, v11, v139
	v_exp_f32_e32 v0, v0
	v_exp_f32_e32 v1, v1
	v_exp_f32_e32 v4, v4
	v_mul_f32_e32 v2, 0xbfb8aa3b, v2
	v_mul_f32_e32 v3, 0xbfb8aa3b, v3
	v_exp_f32_e32 v2, v2
	v_exp_f32_e32 v3, v3
	v_add_f32_e32 v0, 1.0, v0
	v_add_f32_e32 v1, 1.0, v1
	v_add_f32_e32 v4, 1.0, v4
	v_rcp_f32_e32 v0, v0
	v_rcp_f32_e32 v1, v1
	v_rcp_f32_e32 v21, v4
	v_add_f32_e32 v2, 1.0, v2
	v_add_f32_e32 v3, 1.0, v3
	v_rcp_f32_e32 v2, v2
	v_rcp_f32_e32 v3, v3
	v_pk_mul_f32 v[0:1], v[0:1], v[18:19]
	v_pk_mul_f32 v[8:9], v[20:21], v[8:9]
	v_lshlrev_b32_e32 v4, 16, v141
	v_lshlrev_b32_e32 v6, 16, v143
	v_and_b32_e32 v5, 0xffff0000, v141
	v_and_b32_e32 v7, 0xffff0000, v143
	v_pk_mul_f32 v[0:1], v[0:1], v[8:9]
	v_mul_f32_e32 v8, 0xbfb8aa3b, v6
	v_pk_mul_f32 v[2:3], v[2:3], v[4:5]
	v_mul_f32_e32 v4, 0xbfb8aa3b, v7
	v_exp_f32_e32 v8, v8
	v_exp_f32_e32 v4, v4
	v_cvt_pk_bf16_f32 v0, v0, v1
	v_add_f32_e32 v8, 1.0, v8
	v_add_f32_e32 v4, 1.0, v4
	v_rcp_f32_e32 v8, v8
	v_rcp_f32_e32 v9, v4
	s_nop 0
	v_pk_mul_f32 v[4:5], v[8:9], v[6:7]
	s_nop 0
	v_pk_mul_f32 v[2:3], v[2:3], v[4:5]
	s_nop 0
	v_cvt_pk_bf16_f32 v1, v2, v3
	global_store_dwordx2 v[16:17], v[0:1], off offset:96
	s_nop 0
	v_lshl_add_u64 v[158:159], v[158:159], 0, s[6:7]
	s_waitcnt vmcnt(7)
	v_add_f32_e32 v0, v12, v170
	v_lshlrev_b32_e32 v8, 16, v174
	v_lshlrev_b32_e32 v10, 16, v176
	v_and_b32_e32 v9, 0xffff0000, v174
	v_mul_f32_e32 v4, 0xbfb8aa3b, v10
	v_exp_f32_e32 v4, v4
	v_add_f32_e32 v1, v13, v171
	v_and_b32_e32 v11, 0xffff0000, v176
	v_mul_f32_e32 v0, 0xbfb8aa3b, v0
	v_add_f32_e32 v4, 1.0, v4
	v_mul_f32_e32 v1, 0xbfb8aa3b, v1
	v_rcp_f32_e32 v12, v4
	v_mul_f32_e32 v4, 0xbfb8aa3b, v11
	v_add_f32_e32 v2, v14, v172
	v_add_f32_e32 v3, v15, v173
	v_exp_f32_e32 v0, v0
	v_exp_f32_e32 v1, v1
	v_exp_f32_e32 v4, v4
	v_mul_f32_e32 v2, 0xbfb8aa3b, v2
	v_mul_f32_e32 v3, 0xbfb8aa3b, v3
	v_exp_f32_e32 v2, v2
	v_exp_f32_e32 v3, v3
	v_add_f32_e32 v0, 1.0, v0
	v_add_f32_e32 v1, 1.0, v1
	v_add_f32_e32 v4, 1.0, v4
	v_rcp_f32_e32 v0, v0
	v_rcp_f32_e32 v1, v1
	v_rcp_f32_e32 v13, v4
	v_add_f32_e32 v2, 1.0, v2
	v_add_f32_e32 v3, 1.0, v3
	v_rcp_f32_e32 v2, v2
	v_rcp_f32_e32 v3, v3
	v_pk_mul_f32 v[0:1], v[0:1], v[8:9]
	v_pk_mul_f32 v[8:9], v[12:13], v[10:11]
	v_lshlrev_b32_e32 v4, 16, v175
	v_lshlrev_b32_e32 v6, 16, v177
	v_and_b32_e32 v5, 0xffff0000, v175
	v_and_b32_e32 v7, 0xffff0000, v177
	v_pk_mul_f32 v[0:1], v[0:1], v[8:9]
	v_mul_f32_e32 v8, 0xbfb8aa3b, v6
	v_pk_mul_f32 v[2:3], v[2:3], v[4:5]
	v_mul_f32_e32 v4, 0xbfb8aa3b, v7
	v_exp_f32_e32 v8, v8
	v_exp_f32_e32 v4, v4
	v_cvt_pk_bf16_f32 v0, v0, v1
	v_add_f32_e32 v8, 1.0, v8
	v_add_f32_e32 v4, 1.0, v4
	v_rcp_f32_e32 v8, v8
	v_rcp_f32_e32 v9, v4
	s_nop 0
	v_pk_mul_f32 v[4:5], v[8:9], v[6:7]
	s_nop 0
	v_pk_mul_f32 v[2:3], v[2:3], v[4:5]
	s_nop 0
	v_cvt_pk_bf16_f32 v1, v2, v3
	global_store_dwordx2 v[16:17], v[0:1], off offset:112
	s_cbranch_scc1 .LBB0_2064
; __device__ __forceinline__ int otid() { return otid_full() & 255; }
; __device__ __forceinline__ float bf2f(bf v) { return __uint_as_float(((unsigned)v) << 16); }
; __device__ __forceinline__ void ssd_dt_acs(const Params& p, int layer, size_t tok0, int gg, float* sAcs, float* sDt) {
;   const int tid = otid(), lane = tid & 63, w = tid >> 6;
; #pragma unroll
;   for (int k = 0; k < 2; k++) {
;     const int hh = 2 * w + k, hd = gg * 8 + hh;
;     const float bias = p.dt_bias[layer * 16 + hd], a = -__expf(p.a_log[layer * 16 + hd]);
;     const int l0 = 2 * lane;
;     float d0 = softplusf_(bf2f(p.P[(tok0 + l0) * PW + C_SDT + hd]) + bias);
;     float d1 = softplusf_(bf2f(p.P[(tok0 + l0 + 1) * PW + C_SDT + hd]) + bias);
; __device__ __forceinline__ void ssd_pass2(const Params& p, int layer, int task, char* sm) {
;   const int tid = otid(), lane = tid & 63, w = tid >> 6, r32 = lane & 31, h5 = lane >> 5;
;   const int lh = task & 1, gg = (task >> 1) & 1, c = (task >> 2) & 127, b = task >> 9;
;   const size_t tokb = (size_t)b * LSEQ; const int lc0 = c * 128; const size_t tok0 = tokb + lc0;
	v_readlane_b32 s0, v254, 39
	s_ashr_i32 s16, s0, 9
	v_mov_b32_e32 v198, v203
	s_bfe_u32 s21, s0, 0x70002
	s_ashr_i32 s17, s16, 31
	v_mov_b32_e32 v0, v203
	s_lshl_b64 s[14:15], s[16:17], 14
	s_lshl_b32 s17, s21, 7
	s_barrier
	v_readlane_b32 s52, v253, 3
	s_or_b32 s22, s14, s17
	v_and_b32_e32 v12, 63, v0
	v_lshrrev_b32_e32 v0, 5, v0
	v_readlane_b32 s62, v253, 13
	v_readlane_b32 s63, v253, 14
	v_readlane_b32 s1, v254, 40
	v_and_b32_e32 v4, 6, v0
	v_lshl_or_b32 v2, v12, 1, s22
	v_mov_b64_e32 v[0:1], s[62:63]
	s_bfe_u32 s20, s0, 0x10001
	v_readlane_b32 s53, v253, 4
	v_readlane_b32 s54, v253, 5
	v_readlane_b32 s55, v253, 6
	v_readlane_b32 s56, v253, 7
	v_readlane_b32 s57, v253, 8
	v_readlane_b32 s58, v253, 9
	v_readlane_b32 s59, v253, 10
	v_readlane_b32 s60, v253, 11
	v_readlane_b32 s61, v253, 12
	v_readlane_b32 s64, v253, 15
	v_readlane_b32 s65, v253, 16
	v_readlane_b32 s66, v253, 17
	v_readlane_b32 s67, v253, 18
	v_mad_u64_u32 v[0:1], s[0:1], v2, s96, v[0:1]
	v_mov_b32_e32 v2, 0x2d00
	s_lshl_b32 s2, s20, 3
	v_mad_i32_i24 v1, s15, v2, v1
	s_mov_b64 s[0:1], 0x28a0
	v_readlane_b32 s52, v252, 32
	v_lshl_add_u64 v[2:3], v[0:1], 0, s[0:1]
	v_or_b32_e32 v5, s2, v4
	v_readlane_b32 s0, v254, 26
	v_readlane_b32 s53, v252, 33
	s_mov_b32 s87, s2
	v_or_b32_e32 v144, s0, v5
	v_readlane_b32 s54, v252, 34
	v_readlane_b32 s55, v252, 35
	v_readlane_b32 s56, v252, 36
	v_readlane_b32 s57, v252, 37
	v_readlane_b32 s58, v252, 38
	v_readlane_b32 s59, v252, 39
	s_mov_b64 s[0:1], s[52:53]
	v_lshlrev_b64 v[8:9], 2, v[144:145]
	s_mov_b64 s[2:3], s[54:55]
	s_mov_b64 s[4:5], s[56:57]
	v_lshl_add_u64 v[6:7], s[2:3], 0, v[8:9]
	v_lshl_add_u64 v[8:9], s[4:5], 0, v[8:9]
	v_lshlrev_b32_e32 v144, 1, v5
	global_load_dword v7, v[6:7], off
	s_mov_b32 s0, 0x3c23d70a
	global_load_dword v6, v[8:9], off
	v_lshl_add_u64 v[8:9], v[2:3], 0, v[144:145]
	global_load_ushort v5, v[8:9], off
	v_readlane_b32 s60, v252, 40
	v_readlane_b32 s61, v252, 41
	v_readlane_b32 s62, v252, 42
	v_readlane_b32 s63, v252, 43
	v_readlane_b32 s64, v252, 44
	v_readlane_b32 s65, v252, 45
	v_readlane_b32 s66, v252, 46
	v_readlane_b32 s67, v252, 47
	s_mov_b64 s[6:7], s[58:59]
	s_waitcnt vmcnt(0)
	v_lshlrev_b32_e32 v5, 16, v5
	v_add_f32_e32 v5, v7, v5
	v_mul_f32_e32 v8, 0x3fb8aa3b, v5
	v_exp_f32_e32 v9, v8
	s_nop 0
	v_cmp_ngt_f32_e32 vcc, s0, v9
	s_and_saveexec_b64 s[0:1], vcc
	s_xor_b64 s[2:3], exec, s[0:1]
	s_cbranch_execz .LBB0_2067
	v_add_f32_e32 v8, 1.0, v9
	s_mov_b32 s0, 0x800000
	v_cmp_gt_f32_e32 vcc, s0, v8
	s_mov_b32 s0, 0x3f317217
	s_nop 0
	v_cndmask_b32_e64 v9, 0, 32, vcc
	v_ldexp_f32 v8, v8, v9
	v_log_f32_e32 v8, v8
	s_nop 0
	v_mul_f32_e32 v9, 0x3f317217, v8
	v_fma_f32 v9, v8, s0, -v9
	v_fmac_f32_e32 v9, 0x3377d1cf, v8
	s_mov_b32 s0, 0x7f800000
	v_fmac_f32_e32 v9, 0x3f317217, v8
	v_cmp_lt_f32_e64 s[0:1], |v8|, s0
	s_nop 1
	v_cndmask_b32_e64 v8, v8, v9, s[0:1]
	v_mov_b32_e32 v9, 0x41b17218
	v_cndmask_b32_e32 v9, 0, v9, vcc
	v_sub_f32_e32 v8, v8, v9
